# speedup vs baseline: 1.0218x; 1.0163x over previous
; __device__ __forceinline__ float bf2f(u16 h) { return __uint_as_float(((unsigned)h) << 16); }
; __device__ __forceinline__ float h2f(u16 u) { return (float)__builtin_bit_cast(_Float16, u); }
; #define BFLO(u) __uint_as_float((u) << 16)
; #define BFHI(u) __uint_as_float((u) & 0xffff0000u)
; __device__ __forceinline__ void scan_block(const int WV, const Params& P, int layer, int bh, int hv) {
;     ...
;   auto issue = [&](int chunk) {
;     size_t t = tbase + (size_t)chunk * SCH + htok;
;     const u16* zr = z + t * DIN + hch;
;     size_t ri = t * 1024 + hch;
;     Lr = *(const unsigned*)zr; Lk = *(const unsigned*)(zr + 1024); Lv = z[t * DIN + 2048 + hrow];
;     Lw = *(const unsigned*)(rwW + ri); Lkk = *(const unsigned*)(rwKK + ri); Lb = *(const unsigned*)(rwB + ri);
;     Lgn = rwG[t * 1024 + hrow];
;   };
;     ...
;   auto commit = [&](int buf) {
;     float* dst = ring + (size_t)(buf * SCH + htok) * 384;
;     *(f32x2*)(dst + c2 * 2) = (f32x2){-BFLO(Lkk), -BFHI(Lkk)};
;     *(f32x2*)(dst + 64 + c2 * 2) = (f32x2){h2f((u16)(Lw & 0xffff)), h2f((u16)(Lw >> 16))};
;     *(f32x2*)(dst + 128 + c2 * 2) = (f32x2){BFLO(Lb), BFHI(Lb)};
;     *(f32x2*)(dst + 192 + c2 * 2) = (f32x2){BFLO(Lk), BFHI(Lk)};
;     *(f32x2*)(dst + 256 + c2 * 2) = (f32x2){BFLO(Lr), BFHI(Lr)};
;     dst[320 + c2] = bf2f(Lv);
;   };
;     ...
;   wait_flags16(tflag, 16, lane);
;   u16 Lg0 = 0, Lg1 = 0;
;   issue(0); commit(0); Lg0 = Lgn;
;   issue(1);
;   __syncthreads();
;   float S[4] = {0.f, 0.f, 0.f, 0.f};
;   const int vi = lane >> 4, ki = lane & 15;
;   const int opoff = 4 * ki, voff = 320 + wid * 4 + vi;
;   const int yoff = (wid * 4 + vi) * 16 + ki;
;     ...
;   for (int chunk = 0; chunk < NCH; ++chunk) {
;     const int buf = chunk & 1;
;     if (chunk + 1 < NCH) { commit(buf ^ 1); Lg1 = Lgn; }
.LBB0_291:
	v_ashrrev_i32_e32 v18, 6, v5
	v_lshrrev_b32_e32 v0, 5, v6
	v_lshl_or_b32 v24, v18, 1, v0
	v_lshlrev_b32_e32 v8, 1, v24
	v_ashrrev_i32_e32 v9, 31, v8
	v_readlane_b32 s4, v251, 12
	v_lshlrev_b64 v[8:9], 3, v[8:9]
	v_readlane_b32 s5, v251, 13
	v_ashrrev_i32_e32 v25, 31, v24
	v_lshlrev_b32_e32 v0, 1, v2
	v_lshl_add_u64 v[32:33], s[4:5], 0, v[8:9]
	v_readlane_b32 s4, v251, 14
	v_readlane_b32 s5, v251, 15
	s_waitcnt vmcnt(0)
	buffer_inv sc1
	v_lshlrev_b32_e32 v47, 2, v7
	v_lshl_add_u64 v[26:27], s[4:5], 0, v[8:9]
	v_readlane_b32 s4, v251, 22
	v_readlane_b32 s5, v251, 23
	v_mov_b64_e32 v[8:9], s[46:47]
	v_and_b32_e32 v5, 15, v5
	v_lshl_add_u64 v[34:35], v[24:25], 0, s[4:5]
	v_mad_u64_u32 v[10:11], s[4:5], v34, s90, v[8:9]
	v_lshlrev_b64 v[12:13], 11, v[34:35]
	v_mad_i32_i24 v11, v35, s90, v11
	v_or_b32_e32 v14, v12, v0
	v_mov_b32_e32 v15, v13
	v_lshl_add_u64 v[2:3], v[10:11], 0, v[0:1]
	v_lshl_add_u64 v[16:17], s[62:63], 0, v[14:15]
	global_load_dword v19, v[2:3], off
	global_load_dword v20, v[2:3], off offset:2048
	global_load_dword v21, v[16:17], off
	v_lshl_add_u64 v[16:17], s[64:65], 0, v[14:15]
	v_lshlrev_b32_e32 v2, 1, v22
	v_mov_b32_e32 v3, v1
	global_load_dword v16, v[16:17], off
	v_lshl_add_u64 v[10:11], v[10:11], 0, v[2:3]
	v_lshl_add_u64 v[14:15], s[66:67], 0, v[14:15]
	global_load_dword v17, v[14:15], off
	v_lshl_add_u64 v[12:13], s[68:69], 0, v[12:13]
	v_add_co_u32_e32 v10, vcc, s36, v10
	v_lshl_add_u64 v[12:13], v[12:13], 0, v[2:3]
	s_nop 0
	v_addc_co_u32_e32 v11, vcc, 0, v11, vcc
	global_load_ushort v48, v[12:13], off
	v_mul_lo_u32 v14, v24, s56
	global_load_ushort v10, v[10:11], off
	v_or_b32_e32 v7, v47, v14
	v_lshlrev_b32_e32 v11, 2, v4
	v_readlane_b32 s4, v251, 20
	v_readlane_b32 s5, v251, 21
	v_sub_u32_e32 v51, 0, v11
	v_lshl_add_u64 v[38:39], s[68:69], 0, v[2:3]
	v_lshl_add_u64 v[40:41], s[46:47], 0, v[2:3]
	v_lshlrev_b32_e32 v53, 2, v5
	v_mov_b32_e32 v60, 0
	v_readlane_b32 s58, v251, 34
	s_mov_b32 s12, 16
	s_mov_b32 s22, 0
	v_sub_u32_e32 v54, 0x200, v6
	v_lshl_or_b32 v59, v5, 4, v170
	v_mov_b64_e32 v[42:43], 0
	s_mov_b64 s[8:9], 0
	s_mov_b64 s[10:11], 0
	v_mov_b32_e32 v61, 0
	v_mov_b32_e32 v62, 0
	v_mov_b32_e32 v63, 0
	v_mov_b64_e32 v[44:45], 0
	v_mov_b32_e32 v50, 0
	v_mov_b32_e32 v52, 0
	v_mov_b32_e32 v71, 0
	v_mov_b32_e32 v36, 0
	v_mov_b32_e32 v37, v60
	v_readlane_b32 s59, v251, 35
	s_waitcnt vmcnt(4)
	v_cvt_f32_f16_e32 v14, v21
	v_cvt_f32_f16_sdwa v15, v21 dst_sel:DWORD dst_unused:UNUSED_PAD src0_sel:WORD_1
	s_waitcnt vmcnt(3)
	v_lshlrev_b32_e32 v12, 16, v16
	v_and_b32_e32 v13, 0xffff0000, v16
	v_pk_add_f32 v[12:13], v[12:13], 0 neg_lo:[1,1] neg_hi:[1,1]
	ds_write2_b64 v7, v[12:13], v[14:15] offset1:32
	s_waitcnt vmcnt(2)
	v_lshlrev_b32_e32 v12, 16, v17
	v_and_b32_e32 v13, 0xffff0000, v17
	v_lshlrev_b32_e32 v14, 16, v20
	v_and_b32_e32 v15, 0xffff0000, v20
	ds_write2_b64 v7, v[12:13], v[14:15] offset0:64 offset1:96
	v_lshlrev_b32_e32 v12, 16, v19
	v_and_b32_e32 v13, 0xffff0000, v19
	ds_write_b64 v7, v[12:13] offset:1024
	s_waitcnt vmcnt(0)
	v_lshlrev_b32_e32 v10, 16, v10
	v_sub_u32_e32 v7, v7, v11
	ds_write_b32 v7, v10 offset:1280
	v_lshl_add_u64 v[10:11], s[4:5], 0, v[24:25]
	v_mad_u64_u32 v[8:9], s[4:5], v10, s90, v[8:9]
	v_mad_i32_i24 v9, v11, s90, v9
	v_lshl_add_u64 v[12:13], v[8:9], 0, v[0:1]
	v_lshl_add_u64 v[8:9], v[8:9], 0, v[2:3]
	v_add_co_u32_e32 v8, vcc, s36, v8
	global_load_dword v64, v[12:13], off
	global_load_dword v65, v[12:13], off offset:2048
	v_addc_co_u32_e32 v9, vcc, 0, v9, vcc
	global_load_ushort v66, v[8:9], off
	v_lshlrev_b64 v[8:9], 11, v[10:11]
	v_or_b32_e32 v10, v8, v0
	v_mov_b32_e32 v11, v9
	v_lshl_add_u64 v[12:13], s[62:63], 0, v[10:11]
	v_lshl_add_u64 v[8:9], s[68:69], 0, v[8:9]
	global_load_dword v67, v[12:13], off
	v_lshl_add_u64 v[12:13], s[64:65], 0, v[10:11]
	v_lshl_add_u64 v[10:11], s[66:67], 0, v[10:11]
	v_lshl_add_u64 v[8:9], v[8:9], 0, v[2:3]
	global_load_dword v68, v[12:13], off
	global_load_dword v69, v[10:11], off
	global_load_ushort v70, v[8:9], off
	v_lshrrev_b32_e32 v7, 4, v6
	v_lshlrev_b32_e32 v2, 6, v4
	v_lshl_or_b32 v55, v24, 11, v2
	v_lshlrev_b32_e32 v2, 8, v18
	v_lshlrev_b32_e32 v3, 6, v7
	v_or3_b32 v2, v2, v3, v53
	v_add_u32_e32 v57, 0xc000, v2
	v_lshlrev_b32_e32 v2, 2, v7
	v_lshl_or_b32 v2, v18, 4, v2
	v_cmp_eq_u32_e64 s[4:5], 0, v4
	v_lshl_or_b32 v56, v18, 2, v7
	v_add_u32_e32 v58, 0xb00, v2
	v_mov_b32_e32 v2, 0
	s_waitcnt vmcnt(0) lgkmcnt(0)
	s_barrier
.LBB0_292:
	s_and_b32 s23, s22, 1
	v_mov_b32_e32 v49, v48
	s_cmpk_eq_i32 s22, 0x3ff
	v_mov_b32_e32 v48, v2
	s_cbranch_scc1 .LBB0_310
	s_lshl_b32 s6, s23, 4
	v_xad_u32 v2, s6, 16, v24
	v_mul_lo_u32 v4, v2, s56
	v_or_b32_e32 v6, v47, v4
	s_waitcnt vmcnt(3)
	v_cvt_f32_f16_sdwa v5, v67 dst_sel:DWORD dst_unused:UNUSED_PAD src0_sel:WORD_1
	v_cvt_f32_f16_e32 v4, v67
	s_waitcnt vmcnt(3)
	v_lshlrev_b32_e32 v2, 16, v68
	v_and_b32_e32 v3, 0xffff0000, v68
	v_xor_b32_e32 v2, 0x80000000, v2
	v_xor_b32_e32 v3, 0x80000000, v3
	ds_write2_b64 v6, v[2:3], v[4:5] offset1:32
	s_waitcnt vmcnt(3)
	v_lshlrev_b32_e32 v2, 16, v69
	v_and_b32_e32 v3, 0xffff0000, v69
	v_lshlrev_b32_e32 v4, 16, v65
	v_and_b32_e32 v5, 0xffff0000, v65
	ds_write2_b64 v6, v[2:3], v[4:5] offset0:64 offset1:96
	v_lshlrev_b32_e32 v2, 16, v64
	v_and_b32_e32 v3, 0xffff0000, v64
	ds_write_b64 v6, v[2:3] offset:1024
	v_lshlrev_b32_e32 v2, 16, v66
	v_add_u32_e32 v3, v6, v51
	s_waitcnt vmcnt(3)
	v_mov_b32_e32 v48, v70
	ds_write_b32 v3, v2 offset:1280
	s_cmpk_gt_u32 s22, 0x3fd
	s_cbranch_scc0 .LBB0_311

; __device__ __forceinline__ float bf2f(u16 h) { return __uint_as_float(((unsigned)h) << 16); }
; #define SCAN_LOAD(R, TOKP) do { const float* _p = (TOKP); \
;     R##nk = *(const f32x4*)(_p + opoff); R##w = *(const f32x4*)(_p + 64 + opoff); R##b = *(const f32x4*)(_p + 128 + opoff); \
;     R##k = *(const f32x4*)(_p + 192 + opoff); R##r = *(const f32x4*)(_p + 256 + opoff); R##v = _p[voff]; } while (0)
; __device__ __forceinline__ void scan_block(const int WV, const Params& P, int layer, int bh, int hv) {
;     ...
;   auto post_b = [&](int chunk, unsigned epoch) {
;     size_t t = tbase + (size_t)chunk * SCH + htok;
;     const int slot = (chunk & 1) * (SCH * 2);
;     for (unsigned spins = 0; spins < (1u << 22); ++spins) {
;       bool ok = ((unsigned)(pg1 >> 32) == epoch) && ((unsigned)(pg2 >> 32) == epoch);
;       if (__all(ok)) break;
;       __builtin_amdgcn_s_sleep(1);
;       pg1 = __hip_atomic_load(xpart + slot, __ATOMIC_RELAXED, __HIP_MEMORY_SCOPE_AGENT);
;       pg2 = __hip_atomic_load(xpart + slot + 1, __ATOMIC_RELAXED, __HIP_MEMORY_SCOPE_AGENT);
;     }
;     float p1 = __uint_as_float((unsigned)pg1), p2 = __uint_as_float((unsigned)pg2);
;     float mean = (Ps1 + p1) * (1.f / 64.f);
;     float var = (Ps2 + p2) * (1.f / 64.f) - mean * mean;
;     float rstd = rsqrtf(fmaxf(var, 0.f) + GN_EPS);
;     float o = ((Py - mean) * rstd * gw1 + gb1 + Pbon) * bf2f(Pg);
;     z[t * DIN + hrow] = f2bf(o);
;   };
;     ...
; #pragma unroll 2
;       for (int tok = 0; tok < SCH; tok += 2) {
;         SCAN_LOAD(B, base + (tok + 1) * 384);
;         SCAN_STEP(A, yb + tok * 512);
;         SCAN_LOAD(A, base + ((tok + 2) & (SCH - 1)) * 384);
;         SCAN_STEP(B, yb + (tok + 1) * 512);
;       }
.Lpp_skip:
	s_cmp_lg_u32 s20, 10
	s_cbranch_scc1 .Lpb_skip
	s_cmp_eq_u32 s22, 0
	s_cbranch_scc1 .Lpb_skip
	s_add_i32 s80, s22, s31
	v_mov_b32_e32 v204, s80
.Lpb_spin:
	s_waitcnt vmcnt(1)
	v_cmp_eq_u32_e32 vcc, v204, v43
	s_waitcnt vmcnt(0)
	v_cmp_eq_u32_e64 s[6:7], v204, v45
	s_and_b64 s[6:7], vcc, s[6:7]
	s_cmp_eq_u64 s[6:7], exec
	s_cbranch_scc1 .Lpb_ok
	s_sleep 1
	global_load_dwordx2 v[42:43], v[254:255], off sc1
	global_load_dwordx2 v[44:45], v[254:255], off offset:8 sc1
	s_branch .Lpb_spin
.Lpb_ok:
	v_add_f32_e32 v205, v36, v42
	v_mul_f32_e32 v206, 0x3c800000, v205
	v_add_f32_e32 v207, v37, v44
	v_mul_f32_e32 v206, v206, v206
	v_fma_f32 v206, v207, s50, -v206
	v_max_f32_e32 v206, 0, v206
	v_add_f32_e32 v206, 0x3a27c5ac, v206
	v_cmp_gt_f32_e32 vcc, s94, v206
	v_mul_f32_e32 v207, 0x4b800000, v206
	v_fmac_f32_e32 v50, 0xbc800000, v205
	v_cndmask_b32_e32 v206, v206, v207, vcc
	v_rsq_f32_e32 v206, v206
	s_add_i32 s80, s22, -1
	s_lshl_b32 s80, s80, 4
	v_lshl_add_u64 v[200:201], v[34:35], 0, s[80:81]
	v_mul_f32_e32 v207, 0x45800000, v206
	v_cndmask_b32_e32 v206, v206, v207, vcc
	v_mul_f32_e32 v205, v50, v206
	v_fma_f32 v205, v23, v205, v46
	v_add_f32_e32 v205, v52, v205
	v_lshlrev_b32_e32 v206, 16, v71
	v_mul_f32_e32 v205, v205, v206
	v_cvt_pk_bf16_f32 v207, v205, s0
	v_mad_u64_u32 v[202:203], s[6:7], v200, s90, v[40:41]
	v_mad_i32_i24 v203, v201, s90, v203
	global_store_short v[202:203], v207, off
.Lpb_skip:
	ds_read_b128 v[76:79], v74
	ds_read_b128 v[80:83], v74 offset:256
	ds_read_b128 v[84:87], v74 offset:512
	ds_read_b128 v[88:91], v74 offset:768
	ds_read_b128 v[92:95], v74 offset:1024
	ds_read_b32 v96, v73
	s_waitcnt lgkmcnt(6)
	v_mul_f32 v97, v60, v2
	v_fmac_f32 v97, v61, v3
	v_fmac_f32 v97, v62, v4
	v_fmac_f32 v97, v63, v5
	v_mul_f32 v99, v60, v6
	v_mul_f32 v100, v61, v7
	v_add_f32_dpp v97, v97, v97 row_ror:8 row_mask:0xf bank_mask:0xf
	v_mul_f32 v101, v62, v8
	v_mul_f32 v102, v63, v9
	v_add_f32_dpp v97, v97, v97 row_ror:4 row_mask:0xf bank_mask:0xf
	v_fmac_f32 v99, v75, v14
	v_fmac_f32 v100, v75, v15
	v_add_f32_dpp v97, v97, v97 row_ror:2 row_mask:0xf bank_mask:0xf
	v_fmac_f32 v101, v75, v16
	v_fmac_f32 v102, v75, v17
	v_add_f32_dpp v97, v97, v97 row_ror:1 row_mask:0xf bank_mask:0xf
	v_fma_f32 v60, v97, v10, v99
	v_fma_f32 v61, v97, v11, v100
	v_fma_f32 v62, v97, v12, v101
	v_fma_f32 v63, v97, v13, v102
	v_mul_f32 v98, v60, v18
	v_fmac_f32 v98, v61, v19
	v_fmac_f32 v98, v62, v20
	v_fmac_f32 v98, v63, v21
	ds_write_b32 v72, v98
	ds_read_b128 v[2:5], v74 offset:1536
	ds_read_b128 v[6:9], v74 offset:1792
	ds_read_b128 v[10:13], v74 offset:2048
	ds_read_b128 v[14:17], v74 offset:2304
	ds_read_b128 v[18:21], v74 offset:2560
	ds_read_b32 v75, v73 offset:1536
	s_add_i32 s21, s20, 6
	s_and_b32 s21, s21, 12
	s_mulk_i32 s21, 0x600
	s_waitcnt lgkmcnt(7)
	v_mul_f32 v97, v60, v76
	v_fmac_f32 v97, v61, v77
	v_fmac_f32 v97, v62, v78
	v_fmac_f32 v97, v63, v79
	v_mul_f32 v99, v60, v80
	v_mul_f32 v100, v61, v81
	v_add_f32_dpp v97, v97, v97 row_ror:8 row_mask:0xf bank_mask:0xf
	v_mul_f32 v101, v62, v82
	v_mul_f32 v102, v63, v83
	v_add_f32_dpp v97, v97, v97 row_ror:4 row_mask:0xf bank_mask:0xf
	v_fmac_f32 v99, v96, v88
	v_fmac_f32 v100, v96, v89
	v_add_f32_dpp v97, v97, v97 row_ror:2 row_mask:0xf bank_mask:0xf
	v_fmac_f32 v101, v96, v90
	v_fmac_f32 v102, v96, v91
	v_add_f32_dpp v97, v97, v97 row_ror:1 row_mask:0xf bank_mask:0xf
	v_fma_f32 v60, v97, v84, v99
	v_fma_f32 v61, v97, v85, v100
	v_fma_f32 v62, v97, v86, v101
	v_fma_f32 v63, v97, v87, v102
	v_mul_f32 v98, v60, v92
	v_fmac_f32 v98, v61, v93
	v_fmac_f32 v98, v62, v94
	v_fmac_f32 v98, v63, v95
	ds_write_b32 v72, v98 offset:2048
	s_add_i32 s21, s13, s21
	ds_read_b128 v[76:79], v74 offset:3072
	ds_read_b128 v[80:83], v74 offset:3328
	ds_read_b128 v[84:87], v74 offset:3584
	ds_read_b128 v[88:91], v74 offset:3840
	ds_read_b128 v[92:95], v74 offset:4096
	ds_read_b32 v96, v73 offset:3072
	s_waitcnt lgkmcnt(7)
	v_mul_f32 v97, v60, v2
	v_fmac_f32 v97, v61, v3
	v_fmac_f32 v97, v62, v4
	v_fmac_f32 v97, v63, v5
	v_mul_f32 v99, v60, v6
	v_mul_f32 v100, v61, v7
	v_add_f32_dpp v97, v97, v97 row_ror:8 row_mask:0xf bank_mask:0xf
	v_mul_f32 v101, v62, v8
	v_mul_f32 v102, v63, v9
	v_add_f32_dpp v97, v97, v97 row_ror:4 row_mask:0xf bank_mask:0xf
	v_fmac_f32 v99, v75, v14
	v_fmac_f32 v100, v75, v15
	v_add_f32_dpp v97, v97, v97 row_ror:2 row_mask:0xf bank_mask:0xf
	v_fmac_f32 v101, v75, v16
	v_fmac_f32 v102, v75, v17
	v_add_f32_dpp v97, v97, v97 row_ror:1 row_mask:0xf bank_mask:0xf
	v_fma_f32 v60, v97, v10, v99
	v_fma_f32 v61, v97, v11, v100
	v_fma_f32 v62, v97, v12, v101
	v_fma_f32 v63, v97, v13, v102
	v_mul_f32 v98, v60, v18
	v_fmac_f32 v98, v61, v19
	v_fmac_f32 v98, v62, v20
	v_fmac_f32 v98, v63, v21
	ds_write_b32 v72, v98 offset:4096
	v_lshl_add_u32 v18, v53, 2, s21
	ds_read_b128 v[2:5], v18
	ds_read_b128 v[6:9], v18 offset:256
	ds_read_b128 v[10:13], v18 offset:512
	ds_read_b128 v[14:17], v18 offset:768
	v_lshl_add_u32 v75, v56, 2, s21
	ds_read_b128 v[18:21], v18 offset:1024
	ds_read_b32 v75, v75 offset:1280
	s_add_i32 s20, s20, 4
	s_waitcnt lgkmcnt(7)
	v_mul_f32 v97, v60, v76
	v_fmac_f32 v97, v61, v77
	v_fmac_f32 v97, v62, v78
	v_fmac_f32 v97, v63, v79
	v_mul_f32 v99, v60, v80
	v_mul_f32 v100, v61, v81
	v_add_f32_dpp v97, v97, v97 row_ror:8 row_mask:0xf bank_mask:0xf
	v_mul_f32 v101, v62, v82
	v_mul_f32 v102, v63, v83
	v_add_f32_dpp v97, v97, v97 row_ror:4 row_mask:0xf bank_mask:0xf
	v_fmac_f32 v99, v96, v88
	v_fmac_f32 v100, v96, v89
	v_add_f32_dpp v97, v97, v97 row_ror:2 row_mask:0xf bank_mask:0xf
	v_fmac_f32 v101, v96, v90
	v_fmac_f32 v102, v96, v91
	v_add_f32_dpp v97, v97, v97 row_ror:1 row_mask:0xf bank_mask:0xf
	v_fma_f32 v60, v97, v84, v99
	v_fma_f32 v61, v97, v85, v100
	v_fma_f32 v62, v97, v86, v101
	v_fma_f32 v63, v97, v87, v102
	v_mul_f32 v98, v60, v92
	v_fmac_f32 v98, v61, v93
	v_fmac_f32 v98, v62, v94
	v_fmac_f32 v98, v63, v95
	ds_write_b32 v72, v98 offset:6144
	v_add_u32_e32 v72, 0x2000, v72
	v_add_u32_e32 v73, 0x1800, v73
	s_cmp_gt_u32 s20, 13
	v_add_u32_e32 v74, 0x1800, v74
	s_cbranch_scc0 .LBB0_297
	s_waitcnt lgkmcnt(0)
	s_barrier
	s_branch .LBB0_332

; __device__ __forceinline__ void scan_block(const int WV, const Params& P, int layer, int bh, int hv) {
;     ...
;   auto post_a = [&](int chunk, int buf, unsigned epoch) {
;     const float* src = ring + (size_t)(buf * SCH + htok) * 384;
;     const float* yp = ypart + (size_t)buf * (SCH * 512) + (size_t)htok * 512 + c2 * 16;
;     f32x4 ya = *(const f32x4*)yp + *(const f32x4*)(yp + 4), yb2 = *(const f32x4*)(yp + 8) + *(const f32x4*)(yp + 12);
;     ya = ya + yb2;
;     float y = (ya[0] + ya[1]) + (ya[2] + ya[3]);
;     f32x2 k = *(const f32x2*)(src + 192 + c2 * 2), r = *(const f32x2*)(src + 256 + c2 * 2);
;     float v = src[320 + c2];
;     float s1 = row32_allsum(y), s2 = row32_allsum(y * y);
;     float dot = row32_allsum(r[0] * k[0] * rk2[0] + r[1] * k[1] * rk2[1]);
;     const int slot = (chunk & 1) * (SCH * 2);
;     if (c2 == 0) {
;       __hip_atomic_store(xmine + slot, ((unsigned long long)epoch << 32) | __float_as_uint(s1), __ATOMIC_RELAXED, __HIP_MEMORY_SCOPE_AGENT);
;       __hip_atomic_store(xmine + slot + 1, ((unsigned long long)epoch << 32) | __float_as_uint(s2), __ATOMIC_RELAXED, __HIP_MEMORY_SCOPE_AGENT);
;     }
;     Py = y; Pbon = v * dot; Ps1 = s1; Ps2 = s2; Pg = Lgc;
;   };
.LBB0_329:
	s_or_b64 exec, exec, s[12:13]
	v_cndmask_b32_e64 v4, 0, 1, s[20:21]
	v_cmp_ne_u32_e32 vcc, 0, v4
	s_cmp_eq_u64 vcc, exec
	s_cbranch_scc1 .LBB0_317
	s_add_i32 s25, s25, -4
	s_cmp_eq_u32 s25, 0
	s_cselect_b64 s[10:11], -1, 0
	s_sleep 2
	s_branch .LBB0_317
.LBB0_332:
	s_waitcnt lgkmcnt(3)
	v_lshl_add_u32 v14, s23, 15, v55
	ds_read_b128 v[2:5], v14 offset:49152
	ds_read_b128 v[6:9], v14 offset:49168
	ds_read_b128 v[10:13], v14 offset:49184
	ds_read_b128 v[14:17], v14 offset:49200
	s_waitcnt lgkmcnt(6)
	v_lshl_add_u32 v18, s23, 4, v24
	v_mul_lo_u32 v18, v18, s56
	s_waitcnt lgkmcnt(2)
	v_pk_add_f32 v[4:5], v[4:5], v[8:9]
	v_pk_add_f32 v[2:3], v[2:3], v[6:7]
	s_waitcnt lgkmcnt(0)
	v_pk_add_f32 v[6:7], v[12:13], v[16:17]
	v_pk_add_f32 v[8:9], v[10:11], v[14:15]
	v_pk_add_f32 v[4:5], v[4:5], v[6:7]
	v_pk_add_f32 v[2:3], v[2:3], v[8:9]
	s_nop 0
	v_add_f32_e32 v2, v2, v3
	v_add_f32_e32 v3, v4, v5
	v_add_f32_e32 v50, v2, v3
	v_or_b32_e32 v2, v47, v18
	ds_read2_b64 v[4:7], v2 offset0:96 offset1:128
	v_add_f32_dpp v3, v50, v50 row_ror:8 row_mask:0xf bank_mask:0xf bound_ctrl:1
	v_add_u32_e32 v2, v2, v51
	ds_read_b32 v2, v2 offset:1280
	v_add_f32_dpp v3, v3, v3 row_ror:4 row_mask:0xf bank_mask:0xf bound_ctrl:1
	s_waitcnt lgkmcnt(1)
	v_pk_mul_f32 v[4:5], v[4:5], v[6:7]
	v_add_f32_dpp v3, v3, v3 row_ror:2 row_mask:0xf bank_mask:0xf bound_ctrl:1
	v_pk_mul_f32 v[4:5], v[28:29], v[4:5]
	s_nop 0
	v_add_f32_dpp v8, v3, v3 row_ror:1 row_mask:0xf bank_mask:0xf bound_ctrl:1
	v_mul_f32_e32 v3, v50, v50
	v_mov_b32_e32 v10, v8
	s_nop 1
	v_permlane16_swap_b32_e32 v8, v10
	v_mov_b32_dpp v3, v3 row_ror:8 row_mask:0xf bank_mask:0xf bound_ctrl:1
	v_fmac_f32_e32 v3, v50, v50
	s_nop 1
	v_add_f32_dpp v3, v3, v3 row_ror:4 row_mask:0xf bank_mask:0xf bound_ctrl:1
	s_nop 1
	v_add_f32_dpp v3, v3, v3 row_ror:2 row_mask:0xf bank_mask:0xf bound_ctrl:1
	s_nop 1
	v_add_f32_dpp v9, v3, v3 row_ror:1 row_mask:0xf bank_mask:0xf bound_ctrl:1
	v_add_f32_e32 v3, v4, v5
	v_mov_b32_e32 v11, v9
	s_nop 1
	v_permlane16_swap_b32_e32 v9, v11
	v_add_f32_dpp v3, v3, v3 row_ror:8 row_mask:0xf bank_mask:0xf bound_ctrl:1
	v_pk_add_f32 v[36:37], v[8:9], v[10:11]
	s_nop 0
	v_add_f32_dpp v3, v3, v3 row_ror:4 row_mask:0xf bank_mask:0xf bound_ctrl:1
	s_nop 1
	v_add_f32_dpp v3, v3, v3 row_ror:2 row_mask:0xf bank_mask:0xf bound_ctrl:1
	s_nop 1
	v_add_f32_dpp v3, v3, v3 row_ror:1 row_mask:0xf bank_mask:0xf bound_ctrl:1
	v_mov_b32_e32 v4, v3
	s_nop 1
	v_permlane16_swap_b32_e32 v3, v4
	s_and_saveexec_b64 s[6:7], s[4:5]
	s_cbranch_execz .LBB0_334
	s_lshl_b32 s20, s22, 8
	s_add_i32 s13, s51, s22
	s_and_b32 s80, s20, 0x100
	v_lshl_add_u64 v[6:7], v[32:33], 0, s[80:81]
	v_mov_b32_e32 v9, s13
	v_mov_b32_e32 v8, v36
	global_store_dwordx2 v[6:7], v[8:9], off sc1
	v_mov_b32_e32 v8, v37
	global_store_dwordx2 v[6:7], v[8:9], off offset:8 sc1

; __device__ __forceinline__ void attn_item(const int WV, const Params& P, int bh, int qb) {
;     ...
;     if (kt * 64 <= q0 + 31) {
;       const float* cks = (const float*)(cur + 128 * KP);
;       f32x16 st[2];
; #pragma unroll
;       for (int kb = 0; kb < 2; ++kb) {
; #pragma unroll
;         for (int gq = 0; gq < 4; ++gq) {
;           f32x4 ck4 = *(const f32x4*)(cks + kb * 32 + gq * 8 + hf * 4);
;           st[kb][gq * 4 + 0] = ck4[0]; st[kb][gq * 4 + 1] = ck4[1]; st[kb][gq * 4 + 2] = ck4[2]; st[kb][gq * 4 + 3] = ck4[3];
;         }
; #pragma unroll
;         for (int s = 0; s < 4; ++s) {
;           bf16x8 a = *(const bf16x8*)(cur + (kb * 32 + n) * KP + s * 32 + hf * 16);
;           st[kb] = __builtin_amdgcn_mfma_f32_32x32x16_bf16(a, qf[s], st[kb], 0, 0, 0);
;         }
;       }
;       if (kt * 64 + 63 > q0) {
; #pragma unroll
;         for (int kb = 0; kb < 2; ++kb)
; #pragma unroll
;           for (int i = 0; i < 16; ++i) {
;             int key = kt * 64 + kb * 32 + (i >> 2) * 8 + hf * 4 + (i & 3);
;             if (key > q0 + n) st[kb][i] = -INFINITY;
;           }
;       }
.LBB0_386:
	s_add_i32 s33, s29, -3
	v_cmp_le_i32_e32 vcc, s28, v129
	s_and_saveexec_b64 s[12:13], vcc
	s_cbranch_execz .LBB0_390
	s_and_b32 s34, s33, 2
	s_mulk_i32 s34, 0x4900
	v_lshl_or_b32 v0, v113, 2, s34
	v_or_b32_e32 v2, s34, v118
	ds_read_b128 v[64:67], v0 offset:18432
	ds_read_b128 v[68:71], v0 offset:18464
	ds_read_b128 v[72:75], v0 offset:18496
	ds_read_b128 v[76:79], v0 offset:18528
	v_add_u32_e32 v10, v2, v134
	ds_read_b128 v[200:203], v10
	ds_read_b128 v[204:207], v10 offset:32
	ds_read_b128 v[208:211], v10 offset:64
	ds_read_b128 v[212:215], v10 offset:96
	ds_read_b128 v[48:51], v0 offset:18560
	ds_read_b128 v[52:55], v0 offset:18592
	ds_read_b128 v[56:59], v0 offset:18624
	ds_read_b128 v[60:63], v0 offset:18656
	ds_read_b128 v[216:219], v10 offset:4608
	ds_read_b128 v[220:223], v10 offset:4640
	ds_read_b128 v[224:227], v10 offset:4672
	s_add_i32 s20, s28, 63
	v_cmp_gt_i32_e32 vcc, s20, v116
	s_waitcnt lgkmcnt(10)
	v_mfma_f32_32x32x16_bf16 v[64:79], v[200:203], v[80:83], v[64:79]
	ds_read_b128 v[228:231], v10 offset:4704
	s_waitcnt lgkmcnt(10)
	v_mfma_f32_32x32x16_bf16 v[64:79], v[204:207], v[84:87], v[64:79]
	s_waitcnt lgkmcnt(9)
	v_mfma_f32_32x32x16_bf16 v[64:79], v[208:211], v[88:91], v[64:79]
	s_waitcnt lgkmcnt(8)
	v_mfma_f32_32x32x16_bf16 v[64:79], v[212:215], v[92:95], v[64:79]
	s_waitcnt lgkmcnt(3)
	v_mfma_f32_32x32x16_bf16 v[48:63], v[216:219], v[80:83], v[48:63]
	s_waitcnt lgkmcnt(2)
	v_mfma_f32_32x32x16_bf16 v[48:63], v[220:223], v[84:87], v[48:63]
	s_waitcnt lgkmcnt(1)
	v_mfma_f32_32x32x16_bf16 v[48:63], v[224:227], v[88:91], v[48:63]
	s_waitcnt lgkmcnt(0)
	v_mfma_f32_32x32x16_bf16 v[48:63], v[228:231], v[92:95], v[48:63]
	s_nop 1
	s_and_saveexec_b64 s[20:21], vcc
	s_cbranch_execz .LBB0_389
	v_add_u32_e32 v0, s28, v113
	v_cmp_lt_i32_e32 vcc, v0, v135
	v_add_u32_e32 v2, 2, v0
	s_nop 0
	v_cndmask_b32_e32 v65, v171, v65, vcc
	v_cmp_le_i32_e32 vcc, v0, v135
	s_nop 1
	v_cndmask_b32_e32 v64, v171, v64, vcc
	v_cmp_le_i32_e32 vcc, v2, v135
	v_add_u32_e32 v2, 3, v0
	s_nop 0
	v_cndmask_b32_e32 v66, v171, v66, vcc
	v_cmp_le_i32_e32 vcc, v2, v135
	v_add_u32_e32 v2, 8, v0
	s_nop 0
	v_cndmask_b32_e32 v67, v171, v67, vcc
	v_cmp_le_i32_e32 vcc, v2, v135
	v_add_u32_e32 v2, 9, v0
	s_nop 0
	v_cndmask_b32_e32 v68, v171, v68, vcc
	v_cmp_le_i32_e32 vcc, v2, v135
	v_add_u32_e32 v2, 10, v0
	s_nop 0
	v_cndmask_b32_e32 v69, v171, v69, vcc
	v_cmp_le_i32_e32 vcc, v2, v135
	v_add_u32_e32 v2, 11, v0
	s_nop 0
	v_cndmask_b32_e32 v70, v171, v70, vcc
	v_cmp_le_i32_e32 vcc, v2, v135
	v_add_u32_e32 v2, 16, v0
	s_nop 0
	v_cndmask_b32_e32 v71, v171, v71, vcc
	v_cmp_le_i32_e32 vcc, v2, v135
	v_add_u32_e32 v2, 17, v0
	s_nop 0
	v_cndmask_b32_e32 v72, v171, v72, vcc
	v_cmp_le_i32_e32 vcc, v2, v135
	v_add_u32_e32 v2, 18, v0
	s_nop 0
	v_cndmask_b32_e32 v73, v171, v73, vcc
	v_cmp_le_i32_e32 vcc, v2, v135
	v_add_u32_e32 v2, 19, v0
	s_nop 0
	v_cndmask_b32_e32 v74, v171, v74, vcc
	v_cmp_le_i32_e32 vcc, v2, v135
	v_add_u32_e32 v2, 24, v0
	s_nop 0
	v_cndmask_b32_e32 v75, v171, v75, vcc
	v_cmp_le_i32_e32 vcc, v2, v135
	v_add_u32_e32 v2, 25, v0
	s_nop 0
	v_cndmask_b32_e32 v76, v171, v76, vcc
	v_cmp_le_i32_e32 vcc, v2, v135
	v_add_u32_e32 v2, 26, v0
	s_nop 0
	v_cndmask_b32_e32 v77, v171, v77, vcc
	v_cmp_le_i32_e32 vcc, v2, v135
	v_add_u32_e32 v2, 27, v0
	s_nop 0
	v_cndmask_b32_e32 v78, v171, v78, vcc
	v_cmp_le_i32_e32 vcc, v2, v135
	v_add_u32_e32 v2, 32, v0
	s_nop 0
	v_cndmask_b32_e32 v79, v171, v79, vcc
	v_cmp_le_i32_e32 vcc, v2, v135
	v_add_u32_e32 v2, 33, v0
	s_nop 0
	v_cndmask_b32_e32 v48, v171, v48, vcc
	v_cmp_le_i32_e32 vcc, v2, v135
	v_add_u32_e32 v2, 34, v0
	s_nop 0
	v_cndmask_b32_e32 v49, v171, v49, vcc
	v_cmp_le_i32_e32 vcc, v2, v135
	v_add_u32_e32 v2, 35, v0
	s_nop 0
	v_cndmask_b32_e32 v50, v171, v50, vcc
	v_cmp_le_i32_e32 vcc, v2, v135
	v_add_u32_e32 v2, 40, v0
	s_nop 0
	v_cndmask_b32_e32 v51, v171, v51, vcc
	v_cmp_le_i32_e32 vcc, v2, v135
	v_add_u32_e32 v2, 41, v0
	s_nop 0
	v_cndmask_b32_e32 v52, v171, v52, vcc
	v_cmp_le_i32_e32 vcc, v2, v135
	v_add_u32_e32 v2, 42, v0
	s_nop 0
	v_cndmask_b32_e32 v53, v171, v53, vcc
	v_cmp_le_i32_e32 vcc, v2, v135
	v_add_u32_e32 v2, 43, v0
	s_nop 0
	v_cndmask_b32_e32 v54, v171, v54, vcc
	v_cmp_le_i32_e32 vcc, v2, v135
	v_add_u32_e32 v2, 48, v0
	s_nop 0
	v_cndmask_b32_e32 v55, v171, v55, vcc
	v_cmp_le_i32_e32 vcc, v2, v135
	v_add_u32_e32 v2, 49, v0
	s_nop 0
	v_cndmask_b32_e32 v56, v171, v56, vcc
	v_cmp_le_i32_e32 vcc, v2, v135
	v_add_u32_e32 v2, 50, v0
	s_nop 0
	v_cndmask_b32_e32 v57, v171, v57, vcc
	v_cmp_le_i32_e32 vcc, v2, v135
	v_add_u32_e32 v2, 51, v0
	s_nop 0
	v_cndmask_b32_e32 v58, v171, v58, vcc
	v_cmp_le_i32_e32 vcc, v2, v135
	v_add_u32_e32 v2, 56, v0
	s_nop 0
	v_cndmask_b32_e32 v59, v171, v59, vcc
	v_cmp_le_i32_e32 vcc, v2, v135
	v_add_u32_e32 v2, 57, v0
	s_nop 0
	v_cndmask_b32_e32 v60, v171, v60, vcc
	v_cmp_le_i32_e32 vcc, v2, v135
	v_add_u32_e32 v2, 58, v0
	v_add_u32_e32 v0, 59, v0
	v_cndmask_b32_e32 v61, v171, v61, vcc
	v_cmp_le_i32_e32 vcc, v2, v135
	s_nop 1
	v_cndmask_b32_e32 v62, v171, v62, vcc
	v_cmp_le_i32_e32 vcc, v0, v135
	s_nop 1
	v_cndmask_b32_e32 v63, v171, v63, vcc
; __device__ __forceinline__ void attn_item(const int WV, const Params& P, int bh, int qb) {
;     ...
;       float mx = -INFINITY;
; #pragma unroll
;       for (int kb = 0; kb < 2; ++kb)
; #pragma unroll
;         for (int i = 0; i < 16; ++i) mx = fmaxf(mx, st[kb][i]);
;       {
;         auto rr = __builtin_amdgcn_permlane32_swap(__float_as_uint(mx), __float_as_uint(mx), false, false);
;         mx = fmaxf(__uint_as_float(rr[0]), __uint_as_float(rr[1]));
;       }
;       const float mn = fmaxf(m, mx);
;       const float alpha = __builtin_amdgcn_exp2f(m - mn);
;       m = mn;
;       float ps = 0.f;
;       bf16x8 pb[4];
; #pragma unroll
;       for (int kb = 0; kb < 2; ++kb)
; #pragma unroll
;         for (int i = 0; i < 16; i += 2) {
;           float p0 = __builtin_amdgcn_exp2f(st[kb][i] - mn), p1 = __builtin_amdgcn_exp2f(st[kb][i + 1] - mn);
;           ps += p0 + p1;
;           unsigned pk = pack2bf(p0, p1);
;           pb[kb * 2 + (i >> 3)][i & 7] = (short)(pk & 0xffff);
;           pb[kb * 2 + (i >> 3)][(i & 7) + 1] = (short)(pk >> 16);
;         }
;       l = l * alpha + ps;
; #pragma unroll
;       for (int i = 0; i < 16; ++i) { ot[0][i] *= alpha; ot[1][i] *= alpha; }
;       const char* vb = cur + 64 * KP;
; #pragma unroll
;       for (int db = 0; db < 2; ++db)
; #pragma unroll
;         for (int s = 0; s < 4; ++s) {
;           const char* rp = vb + (db * 32 + n) * KP + (16 * s + 4 * hf) * 2;
;           typedef __attribute__((ext_vector_type(4))) short s16x4;
;           s16x4 lo = *(const s16x4*)rp, hi = *(const s16x4*)(rp + 16);
;           bf16x8 a;
;           a[0] = lo[0]; a[1] = lo[1]; a[2] = lo[2]; a[3] = lo[3]; a[4] = hi[0]; a[5] = hi[1]; a[6] = hi[2]; a[7] = hi[3];
;           ot[db] = __builtin_amdgcn_mfma_f32_32x32x16_bf16(a, pb[s], ot[db], 0, 0, 0);
;         }
.LBB0_389:
	s_or_b64 exec, exec, s[20:21]
	v_max3_f32 v0, v64, s76, v65
	v_max3_f32 v0, v0, v66, v67
	v_max3_f32 v0, v0, v68, v69
	v_max3_f32 v0, v0, v70, v71
	v_max3_f32 v0, v0, v72, v73
	v_max3_f32 v0, v0, v74, v75
	v_max3_f32 v0, v0, v76, v77
	v_max3_f32 v0, v0, v78, v79
	s_nop 0
	v_max3_f32 v0, v0, v48, v49
	v_max3_f32 v0, v0, v50, v51
	v_max3_f32 v0, v0, v52, v53
	v_max3_f32 v0, v0, v54, v55
	v_max3_f32 v0, v0, v56, v57
	v_max3_f32 v0, v0, v58, v59
	v_max3_f32 v0, v0, v60, v61
	v_max3_f32 v0, v0, v62, v63
	v_mov_b32_e32 v2, v0
	s_nop 1
	v_permlane32_swap_b32_e32 v0, v2
	v_max3_f32 v138, v137, v0, v2
	v_sub_f32_e32 v0, v64, v138
	v_exp_f32_e32 v2, v0
	v_sub_f32_e32 v0, v65, v138
	v_exp_f32_e32 v3, v0
	v_sub_f32_e32 v0, v66, v138
	v_exp_f32_e32 v4, v0
	v_sub_f32_e32 v0, v67, v138
	v_exp_f32_e32 v0, v0
	v_add_f32_e32 v5, v2, v3
	v_cvt_pk_bf16_f32 v2, v2, v3
	v_sub_f32_e32 v3, v68, v138
	v_pk_add_f32 v[6:7], v[4:5], v[0:1]
	v_exp_f32_e32 v5, v3
	v_sub_f32_e32 v3, v69, v138
	v_exp_f32_e32 v10, v3
	v_sub_f32_e32 v3, v70, v138
	v_pk_add_f32 v[6:7], v[6:7], v[6:7] op_sel_hi:[0,1]
	v_exp_f32_e32 v8, v3
	v_sub_f32_e32 v3, v71, v138
	v_exp_f32_e32 v6, v3
	v_cvt_pk_bf16_f32 v3, v4, v0
	v_add_f32_e32 v9, v5, v10
	v_cvt_pk_bf16_f32 v4, v5, v10
	v_sub_f32_e32 v5, v73, v138
	v_pk_add_f32 v[10:11], v[8:9], v[6:7]
	v_sub_f32_e32 v0, v72, v138
	v_exp_f32_e32 v7, v5
	v_sub_f32_e32 v5, v74, v138
	v_pk_add_f32 v[10:11], v[10:11], v[10:11] op_sel_hi:[0,1]
	v_exp_f32_e32 v0, v0
	v_exp_f32_e32 v12, v5
	v_sub_f32_e32 v5, v75, v138
	v_exp_f32_e32 v10, v5
	v_add_f32_e32 v13, v0, v7
	v_cvt_pk_bf16_f32 v5, v8, v6
	v_cvt_pk_bf16_f32 v6, v0, v7
	v_pk_add_f32 v[8:9], v[12:13], v[10:11]
	v_sub_f32_e32 v7, v77, v138
	v_pk_add_f32 v[14:15], v[8:9], v[8:9] op_sel_hi:[0,1]
	v_sub_f32_e32 v0, v76, v138
	v_exp_f32_e32 v8, v7
	v_sub_f32_e32 v7, v78, v138
	v_exp_f32_e32 v0, v0
	v_exp_f32_e32 v64, v7
	v_sub_f32_e32 v7, v79, v138
	v_exp_f32_e32 v14, v7
	v_add_f32_e32 v65, v0, v8
	v_cvt_pk_bf16_f32 v7, v12, v10
	v_sub_f32_e32 v9, v49, v138
	v_pk_add_f32 v[10:11], v[64:65], v[14:15]
	v_cvt_pk_bf16_f32 v8, v0, v8
	v_pk_add_f32 v[12:13], v[10:11], v[10:11] op_sel_hi:[0,1]
	v_sub_f32_e32 v0, v48, v138
	v_exp_f32_e32 v10, v9
	v_sub_f32_e32 v9, v50, v138
	v_exp_f32_e32 v0, v0
	v_exp_f32_e32 v48, v9
	v_sub_f32_e32 v9, v51, v138
	v_exp_f32_e32 v12, v9
	v_add_f32_e32 v49, v0, v10
	v_sub_f32_e32 v11, v53, v138
	v_cvt_pk_bf16_f32 v9, v64, v14
	v_cvt_pk_bf16_f32 v10, v0, v10
	v_pk_add_f32 v[14:15], v[48:49], v[12:13]
	v_sub_f32_e32 v0, v52, v138
	v_exp_f32_e32 v13, v11
	v_sub_f32_e32 v11, v54, v138
	v_pk_add_f32 v[14:15], v[14:15], v[14:15] op_sel_hi:[0,1]
	v_exp_f32_e32 v0, v0
	v_exp_f32_e32 v64, v11
	v_sub_f32_e32 v11, v55, v138
	v_exp_f32_e32 v14, v11
	v_cvt_pk_bf16_f32 v11, v48, v12
	v_add_f32_e32 v65, v0, v13
	v_cvt_pk_bf16_f32 v12, v0, v13
	v_sub_f32_e32 v13, v58, v138
	v_add3_u32 v58, s34, v134, v128
	v_pk_add_f32 v[48:49], v[64:65], v[14:15]
	v_sub_f32_e32 v0, v56, v138
	v_exp_f32_e32 v56, v13
	v_sub_f32_e32 v13, v59, v138
	v_add_u32_e32 v59, 0x2000, v58
	v_pk_add_f32 v[66:67], v[48:49], v[48:49] op_sel_hi:[0,1]
	ds_read2_b64 v[48:51], v59 offset0:128 offset1:130
	v_sub_f32_e32 v137, v137, v138
	v_exp_f32_e32 v65, v0
	v_sub_f32_e32 v0, v57, v138
	v_exp_f32_e32 v68, v0
	v_exp_f32_e32 v0, v137
	ds_read2_b64 v[52:55], v59 offset0:132 offset1:134
	v_exp_f32_e32 v66, v13
	v_add_f32_e32 v57, v65, v68
	v_mul_f32_e32 v46, v46, v0
	v_mul_f32_e32 v47, v47, v0
	v_mul_f32_e32 v44, v44, v0
	v_mul_f32_e32 v45, v45, v0
	v_mul_f32_e32 v42, v42, v0
	v_mul_f32_e32 v43, v43, v0
	v_mul_f32_e32 v40, v40, v0
	v_mul_f32_e32 v41, v41, v0
	v_mul_f32_e32 v38, v38, v0
	v_mul_f32_e32 v39, v39, v0
	v_mul_f32_e32 v36, v36, v0
	v_mul_f32_e32 v37, v37, v0
	v_mul_f32_e32 v34, v34, v0
	v_mul_f32_e32 v35, v35, v0
	v_mul_f32_e32 v32, v32, v0
	v_mul_f32_e32 v33, v33, v0
	v_cvt_pk_bf16_f32 v13, v64, v14
	v_pk_add_f32 v[14:15], v[56:57], v[66:67]
	s_waitcnt lgkmcnt(1)
	v_mfma_f32_32x32x16_bf16 v[32:47], v[48:51], v[2:5], v[32:47]
	ds_read2_b64 v[48:51], v59 offset0:136 offset1:138
	v_pk_add_f32 v[14:15], v[14:15], v[14:15] op_sel_hi:[0,1]
	v_sub_f32_e32 v14, v60, v138
	v_exp_f32_e32 v64, v14
	v_sub_f32_e32 v14, v61, v138
	v_exp_f32_e32 v61, v14
	v_sub_f32_e32 v14, v62, v138
	s_waitcnt lgkmcnt(1)
	v_mfma_f32_32x32x16_bf16 v[32:47], v[52:55], v[6:9], v[32:47]
	v_add_u32_e32 v62, 0x3000, v58
	ds_read2_b64 v[52:55], v59 offset0:140 offset1:142
	v_mul_f32_e64 v30, v30, v0
	v_mul_f32_e64 v31, v31, v0
	v_mul_f32_e64 v28, v28, v0
	v_mul_f32_e64 v29, v29, v0
	v_mul_f32_e32 v26, v26, v0
	v_mul_f32_e32 v27, v27, v0
	v_mul_f32_e32 v24, v24, v0
	v_mul_f32_e32 v25, v25, v0
	v_mul_f32_e32 v22, v22, v0
	v_mul_f32_e32 v23, v23, v0
	s_waitcnt lgkmcnt(1)
	v_mfma_f32_32x32x16_bf16 v[32:47], v[48:51], v[10:13], v[32:47]
	v_cvt_pk_bf16_f32 v49, v56, v66
	ds_read2_b64 v[56:59], v62 offset0:192 offset1:194
	v_mul_f32_e64 v20, v20, v0
	v_mul_f32_e64 v21, v21, v0
	v_mul_f32_e64 v18, v18, v0
	v_mul_f32_e64 v19, v19, v0
	v_mul_f32_e32 v16, v16, v0
	v_mul_f32_e32 v17, v17, v0
	v_exp_f32_e32 v60, v14
	v_sub_f32_e32 v14, v63, v138
	s_waitcnt lgkmcnt(0)
	v_mfma_f32_32x32x16_bf16 v[16:31], v[56:59], v[2:5], v[16:31]
	ds_read2_b64 v[2:5], v62 offset0:196 offset1:198
	v_exp_f32_e32 v14, v14
	v_cvt_pk_bf16_f32 v48, v65, v68
	v_cvt_pk_bf16_f32 v50, v64, v61
	v_add_f32_e32 v61, v64, v61
	v_cvt_pk_bf16_f32 v51, v60, v14
	v_mov_b32_e32 v137, v138
	s_waitcnt lgkmcnt(0)
	v_mfma_f32_32x32x16_bf16 v[16:31], v[2:5], v[6:9], v[16:31]
	ds_read2_b64 v[2:5], v62 offset0:200 offset1:202
	v_add_f32_e64 v6, v60, v14
	v_add_f32_e64 v7, v61, v15
	v_add_f32_e32 v6, v6, v7
	v_fmac_f32_e32 v6, v136, v0
	v_mov_b32_e32 v136, v6
	s_waitcnt lgkmcnt(0)
	v_mfma_f32_32x32x16_bf16 v[16:31], v[2:5], v[10:13], v[16:31]
	ds_read2_b64 v[2:5], v62 offset0:204 offset1:206
	v_mfma_f32_32x32x16_bf16 v[32:47], v[52:55], v[48:51], v[32:47]
	s_waitcnt lgkmcnt(0)
	v_mfma_f32_32x32x16_bf16 v[16:31], v[2:5], v[48:51], v[16:31]
; __device__ __forceinline__ void attn_item(const int WV, const Params& P, int bh, int qb) {
;     ...
;     if (kt * 64 <= q0 + 31) {
;       const float* cks = (const float*)(cur + 128 * KP);
;       f32x16 st[2];
; #pragma unroll
;       for (int kb = 0; kb < 2; ++kb) {
; #pragma unroll
;         for (int gq = 0; gq < 4; ++gq) {
;           f32x4 ck4 = *(const f32x4*)(cks + kb * 32 + gq * 8 + hf * 4);
;           st[kb][gq * 4 + 0] = ck4[0]; st[kb][gq * 4 + 1] = ck4[1]; st[kb][gq * 4 + 2] = ck4[2]; st[kb][gq * 4 + 3] = ck4[3];
;         }
; #pragma unroll
;         for (int s = 0; s < 4; ++s) {
;           bf16x8 a = *(const bf16x8*)(cur + (kb * 32 + n) * KP + s * 32 + hf * 16);
;           st[kb] = __builtin_amdgcn_mfma_f32_32x32x16_bf16(a, qf[s], st[kb], 0, 0, 0);
;         }
;       }
;       if (kt * 64 + 63 > q0) {
; #pragma unroll
;         for (int kb = 0; kb < 2; ++kb)
; #pragma unroll
;           for (int i = 0; i < 16; ++i) {
;             int key = kt * 64 + kb * 32 + (i >> 2) * 8 + hf * 4 + (i & 3);
;             if (key > q0 + n) st[kb][i] = -INFINITY;
;           }
;       }
.LBB0_390:
	s_or_b64 exec, exec, s[12:13]
	s_add_i32 s12, s28, 64
	v_cmp_le_i32_e32 vcc, s12, v129
	s_and_saveexec_b64 s[12:13], vcc
	s_cbranch_execz .LBB0_394
	s_add_i32 s20, s29, -2
	s_and_b32 s34, s20, 3
	s_mulk_i32 s34, 0x4900
	v_lshl_or_b32 v0, v113, 2, s34
	v_or_b32_e32 v2, s34, v118
	ds_read_b128 v[64:67], v0 offset:18432
	ds_read_b128 v[68:71], v0 offset:18464
	ds_read_b128 v[72:75], v0 offset:18496
	ds_read_b128 v[76:79], v0 offset:18528
	v_add_u32_e32 v10, v2, v134
	ds_read_b128 v[200:203], v10
	ds_read_b128 v[204:207], v10 offset:32
	ds_read_b128 v[208:211], v10 offset:64
	ds_read_b128 v[212:215], v10 offset:96
	ds_read_b128 v[48:51], v0 offset:18560
	ds_read_b128 v[52:55], v0 offset:18592
	ds_read_b128 v[56:59], v0 offset:18624
	ds_read_b128 v[60:63], v0 offset:18656
	ds_read_b128 v[216:219], v10 offset:4608
	ds_read_b128 v[220:223], v10 offset:4640
	ds_read_b128 v[224:227], v10 offset:4672
	s_add_i32 s20, s28, 0x7f
	v_cmp_gt_i32_e32 vcc, s20, v116
	s_waitcnt lgkmcnt(10)
	v_mfma_f32_32x32x16_bf16 v[64:79], v[200:203], v[80:83], v[64:79]
	ds_read_b128 v[228:231], v10 offset:4704
	s_waitcnt lgkmcnt(10)
	v_mfma_f32_32x32x16_bf16 v[64:79], v[204:207], v[84:87], v[64:79]
	s_waitcnt lgkmcnt(9)
	v_mfma_f32_32x32x16_bf16 v[64:79], v[208:211], v[88:91], v[64:79]
	s_waitcnt lgkmcnt(8)
	v_mfma_f32_32x32x16_bf16 v[64:79], v[212:215], v[92:95], v[64:79]
	s_waitcnt lgkmcnt(3)
	v_mfma_f32_32x32x16_bf16 v[48:63], v[216:219], v[80:83], v[48:63]
	s_waitcnt lgkmcnt(2)
	v_mfma_f32_32x32x16_bf16 v[48:63], v[220:223], v[84:87], v[48:63]
	s_waitcnt lgkmcnt(1)
	v_mfma_f32_32x32x16_bf16 v[48:63], v[224:227], v[88:91], v[48:63]
	s_waitcnt lgkmcnt(0)
	v_mfma_f32_32x32x16_bf16 v[48:63], v[228:231], v[92:95], v[48:63]
	s_nop 1
	s_and_saveexec_b64 s[20:21], vcc
	s_cbranch_execz .LBB0_393
	v_add_u32_e32 v0, s28, v113
	v_add_u32_e32 v2, 64, v0
	v_cmp_lt_i32_e32 vcc, v2, v135
	s_nop 1
	v_cndmask_b32_e32 v65, v171, v65, vcc
	v_cmp_le_i32_e32 vcc, v2, v135
	v_add_u32_e32 v2, 0x42, v0
	s_nop 0
	v_cndmask_b32_e32 v64, v171, v64, vcc
	v_cmp_le_i32_e32 vcc, v2, v135
	v_add_u32_e32 v2, 0x43, v0
	s_nop 0
	v_cndmask_b32_e32 v66, v171, v66, vcc
	v_cmp_le_i32_e32 vcc, v2, v135
	v_add_u32_e32 v2, 0x48, v0
	s_nop 0
	v_cndmask_b32_e32 v67, v171, v67, vcc
	v_cmp_le_i32_e32 vcc, v2, v135
	v_add_u32_e32 v2, 0x49, v0
	s_nop 0
	v_cndmask_b32_e32 v68, v171, v68, vcc
	v_cmp_le_i32_e32 vcc, v2, v135
	v_add_u32_e32 v2, 0x4a, v0
	s_nop 0
	v_cndmask_b32_e32 v69, v171, v69, vcc
	v_cmp_le_i32_e32 vcc, v2, v135
	v_add_u32_e32 v2, 0x4b, v0
	s_nop 0
	v_cndmask_b32_e32 v70, v171, v70, vcc
	v_cmp_le_i32_e32 vcc, v2, v135
	v_add_u32_e32 v2, 0x50, v0
	s_nop 0
	v_cndmask_b32_e32 v71, v171, v71, vcc
	v_cmp_le_i32_e32 vcc, v2, v135
	v_add_u32_e32 v2, 0x51, v0
	s_nop 0
	v_cndmask_b32_e32 v72, v171, v72, vcc
	v_cmp_le_i32_e32 vcc, v2, v135
	v_add_u32_e32 v2, 0x52, v0
	s_nop 0
	v_cndmask_b32_e32 v73, v171, v73, vcc
	v_cmp_le_i32_e32 vcc, v2, v135
	v_add_u32_e32 v2, 0x53, v0
	s_nop 0
	v_cndmask_b32_e32 v74, v171, v74, vcc
	v_cmp_le_i32_e32 vcc, v2, v135
	v_add_u32_e32 v2, 0x58, v0
	s_nop 0
	v_cndmask_b32_e32 v75, v171, v75, vcc
	v_cmp_le_i32_e32 vcc, v2, v135
	v_add_u32_e32 v2, 0x59, v0
	s_nop 0
	v_cndmask_b32_e32 v76, v171, v76, vcc
	v_cmp_le_i32_e32 vcc, v2, v135
	v_add_u32_e32 v2, 0x5a, v0
	s_nop 0
	v_cndmask_b32_e32 v77, v171, v77, vcc
	v_cmp_le_i32_e32 vcc, v2, v135
	v_add_u32_e32 v2, 0x5b, v0
	s_nop 0
	v_cndmask_b32_e32 v78, v171, v78, vcc
	v_cmp_le_i32_e32 vcc, v2, v135
	v_add_u32_e32 v2, 0x60, v0
	s_nop 0
	v_cndmask_b32_e32 v79, v171, v79, vcc
	v_cmp_le_i32_e32 vcc, v2, v135
	v_add_u32_e32 v2, 0x61, v0
	s_nop 0
	v_cndmask_b32_e32 v48, v171, v48, vcc
	v_cmp_le_i32_e32 vcc, v2, v135
	v_add_u32_e32 v2, 0x62, v0
	s_nop 0
	v_cndmask_b32_e32 v49, v171, v49, vcc
	v_cmp_le_i32_e32 vcc, v2, v135
	v_add_u32_e32 v2, 0x63, v0
	s_nop 0
	v_cndmask_b32_e32 v50, v171, v50, vcc
	v_cmp_le_i32_e32 vcc, v2, v135
	v_add_u32_e32 v2, 0x68, v0
	s_nop 0
	v_cndmask_b32_e32 v51, v171, v51, vcc
	v_cmp_le_i32_e32 vcc, v2, v135
	v_add_u32_e32 v2, 0x69, v0
	s_nop 0
	v_cndmask_b32_e32 v52, v171, v52, vcc
	v_cmp_le_i32_e32 vcc, v2, v135
	v_add_u32_e32 v2, 0x6a, v0
	s_nop 0
	v_cndmask_b32_e32 v53, v171, v53, vcc
	v_cmp_le_i32_e32 vcc, v2, v135
	v_add_u32_e32 v2, 0x6b, v0
	s_nop 0
	v_cndmask_b32_e32 v54, v171, v54, vcc
	v_cmp_le_i32_e32 vcc, v2, v135
	v_add_u32_e32 v2, 0x70, v0
	s_nop 0
	v_cndmask_b32_e32 v55, v171, v55, vcc
	v_cmp_le_i32_e32 vcc, v2, v135
	v_add_u32_e32 v2, 0x71, v0
	s_nop 0
	v_cndmask_b32_e32 v56, v171, v56, vcc
	v_cmp_le_i32_e32 vcc, v2, v135
	v_add_u32_e32 v2, 0x72, v0
	s_nop 0
	v_cndmask_b32_e32 v57, v171, v57, vcc
	v_cmp_le_i32_e32 vcc, v2, v135
	v_add_u32_e32 v2, 0x73, v0
	s_nop 0
	v_cndmask_b32_e32 v58, v171, v58, vcc
	v_cmp_le_i32_e32 vcc, v2, v135
	v_add_u32_e32 v2, 0x78, v0
	s_nop 0
	v_cndmask_b32_e32 v59, v171, v59, vcc
	v_cmp_le_i32_e32 vcc, v2, v135
	v_add_u32_e32 v2, 0x79, v0
	s_nop 0
	v_cndmask_b32_e32 v60, v171, v60, vcc
	v_cmp_le_i32_e32 vcc, v2, v135
	v_add_u32_e32 v2, 0x7a, v0
	v_add_u32_e32 v0, 0x7b, v0
	v_cndmask_b32_e32 v61, v171, v61, vcc
	v_cmp_le_i32_e32 vcc, v2, v135
	s_nop 1
	v_cndmask_b32_e32 v62, v171, v62, vcc
	v_cmp_le_i32_e32 vcc, v0, v135
	s_nop 1
	v_cndmask_b32_e32 v63, v171, v63, vcc

; #define BFLO_(u) __uint_as_float((u) << 16)
; #define BFHI_(u) __uint_as_float((u) & 0xffff0000u)
; #define EPI_CALL(ai, m) epi_block(EPI, g, acc[ai][0][m][0], acc[ai][0][m][1], acc[ai][1][m][0], acc[ai][1][m][1], \
;       brow + ai * HALF + e_wr * 64 + m * 16 + e_fq * 4, tok0, rs, sq);
; __device__ __forceinline__ void epi_block(const int EPI, const GemmArgs& g, f32x4 a00, f32x4 a01, f32x4 a10, f32x4 a11,
;                                           const int fbase, const int tok0, const float (&rs)[4], float (&sq)[4]) {
;     ...
;     } else if (EPI == EPI_PLE) {
;       const size_t idx = (size_t)token * D_ + fbase;
;       const float r = rs[q];
;       float4 hv = *(const float4*)(g.h + idx);
;       uint2 pp = *(const uint2*)(g.pp + idx);
;       const float rl = -r * 1.4426950408889634f;
;       hv.x += BFLO_(pp.x) * __builtin_amdgcn_rcpf(1.f + __builtin_amdgcn_exp2f(v0 * rl));
;       hv.y += BFHI_(pp.x) * __builtin_amdgcn_rcpf(1.f + __builtin_amdgcn_exp2f(v1 * rl));
;       hv.z += BFLO_(pp.y) * __builtin_amdgcn_rcpf(1.f + __builtin_amdgcn_exp2f(v2 * rl));
;       hv.w += BFHI_(pp.y) * __builtin_amdgcn_rcpf(1.f + __builtin_amdgcn_exp2f(v3 * rl));
;       *(float4*)(g.h + idx) = hv;
;       uint2 o; o.x = pack2bf(hv.x, hv.y); o.y = pack2bf(hv.z, hv.w);
;       *(uint2*)(g.outb + idx) = o;
;       sq[q] += (hv.x * hv.x + hv.y * hv.y) + (hv.z * hv.z + hv.w * hv.w);
; __device__ __forceinline__ void gemm_phase(const int WV, const GemmArgs& g, int tile0) {
;     ...
;     EPI_CALL(0, 0) EPI_CALL(0, 1) EPI_CALL(0, 2) EPI_CALL(0, 3)
;     EPI_CALL(1, 0) EPI_CALL(1, 1) EPI_CALL(1, 2) EPI_CALL(1, 3)
.Lple_epi:
	v_lshl_add_u32 v142, v140, 11, v148
	v_lshlrev_b32_e32 v148, 2, v142
	v_lshlrev_b32_e32 v152, 1, v142
	v_add_u32_e32 v149, 0x20000, v148
	v_add_u32_e32 v150, 0x100000, v148
	v_add_u32_e32 v151, 0x120000, v148
	v_add_u32_e32 v153, 0x10000, v152
	v_add_u32_e32 v154, 0x80000, v152
	v_add_u32_e32 v155, 0x90000, v152
	v_mul_f32_e32 v156, 0xbfb8aa3b, v146
	v_mul_f32_e32 v157, 0xbfb8aa3b, v147
	v_mul_f32_e32 v158, 0xbfb8aa3b, v144
	v_mul_f32_e32 v159, 0xbfb8aa3b, v145
	global_load_dwordx4 v[184:187], v148, s[72:73]
	global_load_dwordx2 v[188:189], v152, s[40:41]
	global_load_dwordx4 v[190:193], v149, s[72:73]
	global_load_dwordx2 v[194:195], v153, s[40:41]
	global_load_dwordx4 v[196:199], v150, s[72:73]
	global_load_dwordx2 v[200:201], v154, s[40:41]
	global_load_dwordx4 v[202:205], v151, s[72:73]
	global_load_dwordx2 v[206:207], v155, s[40:41]
	global_load_dwordx4 v[208:211], v148, s[72:73] offset:64
	global_load_dwordx2 v[212:213], v152, s[40:41] offset:32
	global_load_dwordx4 v[214:217], v149, s[72:73] offset:64
	global_load_dwordx2 v[218:219], v153, s[40:41] offset:32
	global_load_dwordx4 v[220:223], v150, s[72:73] offset:64
	global_load_dwordx2 v[224:225], v154, s[40:41] offset:32
	global_load_dwordx4 v[226:229], v151, s[72:73] offset:64
	global_load_dwordx2 v[230:231], v155, s[40:41] offset:32
	global_load_dwordx4 v[232:235], v148, s[72:73] offset:128
	global_load_dwordx2 v[236:237], v152, s[40:41] offset:64
	global_load_dwordx4 v[238:241], v149, s[72:73] offset:128
	global_load_dwordx2 v[242:243], v153, s[40:41] offset:64
	v_mov_b32_e32 v160, 0
	v_mov_b32_e32 v161, 0
	v_mov_b32_e32 v142, 0
	v_mov_b32_e32 v143, 0
	v_mul_f32_e32 v244, v126, v156
	v_mul_f32_e32 v245, v127, v156
	v_mul_f32_e32 v246, v128, v156
	v_mul_f32_e32 v247, v129, v156
	v_exp_f32_e32 v244, v244
	v_exp_f32_e32 v245, v245
	v_exp_f32_e32 v246, v246
	v_exp_f32_e32 v247, v247
	v_add_f32_e32 v244, 1.0, v244
	v_add_f32_e32 v245, 1.0, v245
	v_add_f32_e32 v246, 1.0, v246
	v_add_f32_e32 v247, 1.0, v247
	v_rcp_f32_e32 v244, v244
	v_rcp_f32_e32 v245, v245
	v_rcp_f32_e32 v246, v246
	v_rcp_f32_e32 v247, v247
	s_waitcnt vmcnt(18)
	v_lshlrev_b32_e32 v248, 16, v188
	v_lshlrev_b32_e32 v249, 16, v189
	v_and_b32_e32 v188, 0xffff0000, v188
	v_and_b32_e32 v189, 0xffff0000, v189
	v_fma_f32 v126, v244, v248, v184
	v_fma_f32 v127, v245, v188, v185
	v_fma_f32 v128, v246, v249, v186
	v_fma_f32 v129, v247, v189, v187
	v_cvt_pk_bf16_f32 v244, v126, v127
	v_cvt_pk_bf16_f32 v245, v128, v129
	global_store_dwordx4 v148, v[126:129], s[72:73]
	global_store_dwordx2 v152, v[244:245], s[58:59]
	global_load_dwordx4 v[184:187], v150, s[72:73] offset:128
	global_load_dwordx2 v[188:189], v154, s[40:41] offset:64
	v_pk_mul_f32 v[126:127], v[126:127], v[126:127]
	v_pk_mul_f32 v[128:129], v[128:129], v[128:129]
	v_add_f32_e32 v126, v126, v127
	v_add_f32_e32 v128, v128, v129
	v_add_f32_e32 v126, v126, v128
	v_add_f32_e32 v160, v160, v126
	v_mul_f32_e32 v244, v122, v157
	v_mul_f32_e32 v245, v123, v157
	v_mul_f32_e32 v246, v124, v157
	v_mul_f32_e32 v247, v125, v157
	v_exp_f32_e32 v244, v244
	v_exp_f32_e32 v245, v245
	v_exp_f32_e32 v246, v246
	v_exp_f32_e32 v247, v247
	v_add_f32_e32 v244, 1.0, v244
	v_add_f32_e32 v245, 1.0, v245
	v_add_f32_e32 v246, 1.0, v246
	v_add_f32_e32 v247, 1.0, v247
	v_rcp_f32_e32 v244, v244
	v_rcp_f32_e32 v245, v245
	v_rcp_f32_e32 v246, v246
	v_rcp_f32_e32 v247, v247
	s_waitcnt vmcnt(20)
	v_lshlrev_b32_e32 v248, 16, v194
	v_lshlrev_b32_e32 v249, 16, v195
	v_and_b32_e32 v194, 0xffff0000, v194
	v_and_b32_e32 v195, 0xffff0000, v195
	v_fma_f32 v122, v244, v248, v190
	v_fma_f32 v123, v245, v194, v191
	v_fma_f32 v124, v246, v249, v192
	v_fma_f32 v125, v247, v195, v193
	v_cvt_pk_bf16_f32 v244, v122, v123
	v_cvt_pk_bf16_f32 v245, v124, v125
	global_store_dwordx4 v149, v[122:125], s[72:73]
	global_store_dwordx2 v153, v[244:245], s[58:59]
	global_load_dwordx4 v[190:193], v151, s[72:73] offset:128
	global_load_dwordx2 v[194:195], v155, s[40:41] offset:64
	v_pk_mul_f32 v[122:123], v[122:123], v[122:123]
	v_pk_mul_f32 v[124:125], v[124:125], v[124:125]
	v_add_f32_e32 v122, v122, v123
	v_add_f32_e32 v124, v124, v125
	v_add_f32_e32 v122, v122, v124
	v_add_f32_e32 v161, v161, v122
	v_mul_f32_e32 v244, v118, v158
	v_mul_f32_e32 v245, v119, v158
	v_mul_f32_e32 v246, v120, v158
	v_mul_f32_e32 v247, v121, v158
	v_exp_f32_e32 v244, v244
	v_exp_f32_e32 v245, v245
	v_exp_f32_e32 v246, v246
	v_exp_f32_e32 v247, v247
	v_add_f32_e32 v244, 1.0, v244
	v_add_f32_e32 v245, 1.0, v245
	v_add_f32_e32 v246, 1.0, v246
	v_add_f32_e32 v247, 1.0, v247
	v_rcp_f32_e32 v244, v244
	v_rcp_f32_e32 v245, v245
	v_rcp_f32_e32 v246, v246
	v_rcp_f32_e32 v247, v247
	s_waitcnt vmcnt(22)
	v_lshlrev_b32_e32 v248, 16, v200
	v_lshlrev_b32_e32 v249, 16, v201
	v_and_b32_e32 v200, 0xffff0000, v200
	v_and_b32_e32 v201, 0xffff0000, v201
	v_fma_f32 v118, v244, v248, v196
	v_fma_f32 v119, v245, v200, v197
	v_fma_f32 v120, v246, v249, v198
	v_fma_f32 v121, v247, v201, v199
	v_cvt_pk_bf16_f32 v244, v118, v119
	v_cvt_pk_bf16_f32 v245, v120, v121
	global_store_dwordx4 v150, v[118:121], s[72:73]
	global_store_dwordx2 v154, v[244:245], s[58:59]
	global_load_dwordx4 v[196:199], v148, s[72:73] offset:192
	global_load_dwordx2 v[200:201], v152, s[40:41] offset:96
	v_pk_mul_f32 v[118:119], v[118:119], v[118:119]
	v_pk_mul_f32 v[120:121], v[120:121], v[120:121]
	v_add_f32_e32 v118, v118, v119
	v_add_f32_e32 v120, v120, v121
	v_add_f32_e32 v118, v118, v120
	v_add_f32_e32 v142, v142, v118
	v_mul_f32_e32 v244, v114, v159
	v_mul_f32_e32 v245, v115, v159
	v_mul_f32_e32 v246, v116, v159
	v_mul_f32_e32 v247, v117, v159
	v_exp_f32_e32 v244, v244
	v_exp_f32_e32 v245, v245
	v_exp_f32_e32 v246, v246
	v_exp_f32_e32 v247, v247
	v_add_f32_e32 v244, 1.0, v244
	v_add_f32_e32 v245, 1.0, v245
	v_add_f32_e32 v246, 1.0, v246
	v_add_f32_e32 v247, 1.0, v247
	v_rcp_f32_e32 v244, v244
	v_rcp_f32_e32 v245, v245
	v_rcp_f32_e32 v246, v246
	v_rcp_f32_e32 v247, v247
	s_waitcnt vmcnt(24)
; #define BFLO_(u) __uint_as_float((u) << 16)
; #define BFHI_(u) __uint_as_float((u) & 0xffff0000u)
; #define EPI_CALL(ai, m) epi_block(EPI, g, acc[ai][0][m][0], acc[ai][0][m][1], acc[ai][1][m][0], acc[ai][1][m][1], \
;       brow + ai * HALF + e_wr * 64 + m * 16 + e_fq * 4, tok0, rs, sq);
; __device__ __forceinline__ void epi_block(const int EPI, const GemmArgs& g, f32x4 a00, f32x4 a01, f32x4 a10, f32x4 a11,
;                                           const int fbase, const int tok0, const float (&rs)[4], float (&sq)[4]) {
;     ...
;     } else if (EPI == EPI_PLE) {
;       const size_t idx = (size_t)token * D_ + fbase;
;       const float r = rs[q];
;       float4 hv = *(const float4*)(g.h + idx);
;       uint2 pp = *(const uint2*)(g.pp + idx);
;       const float rl = -r * 1.4426950408889634f;
;       hv.x += BFLO_(pp.x) * __builtin_amdgcn_rcpf(1.f + __builtin_amdgcn_exp2f(v0 * rl));
;       hv.y += BFHI_(pp.x) * __builtin_amdgcn_rcpf(1.f + __builtin_amdgcn_exp2f(v1 * rl));
;       hv.z += BFLO_(pp.y) * __builtin_amdgcn_rcpf(1.f + __builtin_amdgcn_exp2f(v2 * rl));
;       hv.w += BFHI_(pp.y) * __builtin_amdgcn_rcpf(1.f + __builtin_amdgcn_exp2f(v3 * rl));
;       *(float4*)(g.h + idx) = hv;
;       uint2 o; o.x = pack2bf(hv.x, hv.y); o.y = pack2bf(hv.z, hv.w);
;       *(uint2*)(g.outb + idx) = o;
;       sq[q] += (hv.x * hv.x + hv.y * hv.y) + (hv.z * hv.z + hv.w * hv.w);
; __device__ __forceinline__ void gemm_phase(const int WV, const GemmArgs& g, int tile0) {
;     ...
;     EPI_CALL(0, 0) EPI_CALL(0, 1) EPI_CALL(0, 2) EPI_CALL(0, 3)
;     EPI_CALL(1, 0) EPI_CALL(1, 1) EPI_CALL(1, 2) EPI_CALL(1, 3)
	v_lshlrev_b32_e32 v248, 16, v206
	v_lshlrev_b32_e32 v249, 16, v207
	v_and_b32_e32 v206, 0xffff0000, v206
	v_and_b32_e32 v207, 0xffff0000, v207
	v_fma_f32 v114, v244, v248, v202
	v_fma_f32 v115, v245, v206, v203
	v_fma_f32 v116, v246, v249, v204
	v_fma_f32 v117, v247, v207, v205
	v_cvt_pk_bf16_f32 v244, v114, v115
	v_cvt_pk_bf16_f32 v245, v116, v117
	global_store_dwordx4 v151, v[114:117], s[72:73]
	global_store_dwordx2 v155, v[244:245], s[58:59]
	global_load_dwordx4 v[202:205], v149, s[72:73] offset:192
	global_load_dwordx2 v[206:207], v153, s[40:41] offset:96
	v_pk_mul_f32 v[114:115], v[114:115], v[114:115]
	v_pk_mul_f32 v[116:117], v[116:117], v[116:117]
	v_add_f32_e32 v114, v114, v115
	v_add_f32_e32 v116, v116, v117
	v_add_f32_e32 v114, v114, v116
	v_add_f32_e32 v143, v143, v114
	v_mul_f32_e32 v244, v110, v156
	v_mul_f32_e32 v245, v111, v156
	v_mul_f32_e32 v246, v112, v156
	v_mul_f32_e32 v247, v113, v156
	v_exp_f32_e32 v244, v244
	v_exp_f32_e32 v245, v245
	v_exp_f32_e32 v246, v246
	v_exp_f32_e32 v247, v247
	v_add_f32_e32 v244, 1.0, v244
	v_add_f32_e32 v245, 1.0, v245
	v_add_f32_e32 v246, 1.0, v246
	v_add_f32_e32 v247, 1.0, v247
	v_rcp_f32_e32 v244, v244
	v_rcp_f32_e32 v245, v245
	v_rcp_f32_e32 v246, v246
	v_rcp_f32_e32 v247, v247
	s_waitcnt vmcnt(26)
	v_lshlrev_b32_e32 v248, 16, v212
	v_lshlrev_b32_e32 v249, 16, v213
	v_and_b32_e32 v212, 0xffff0000, v212
	v_and_b32_e32 v213, 0xffff0000, v213
	v_fma_f32 v110, v244, v248, v208
	v_fma_f32 v111, v245, v212, v209
	v_fma_f32 v112, v246, v249, v210
	v_fma_f32 v113, v247, v213, v211
	v_cvt_pk_bf16_f32 v244, v110, v111
	v_cvt_pk_bf16_f32 v245, v112, v113
	global_store_dwordx4 v148, v[110:113], s[72:73] offset:64
	global_store_dwordx2 v152, v[244:245], s[58:59] offset:32
	global_load_dwordx4 v[208:211], v150, s[72:73] offset:192
	global_load_dwordx2 v[212:213], v154, s[40:41] offset:96
	v_pk_mul_f32 v[110:111], v[110:111], v[110:111]
	v_pk_mul_f32 v[112:113], v[112:113], v[112:113]
	v_add_f32_e32 v110, v110, v111
	v_add_f32_e32 v112, v112, v113
	v_add_f32_e32 v110, v110, v112
	v_add_f32_e32 v160, v160, v110
	v_mul_f32_e32 v244, v106, v157
	v_mul_f32_e32 v245, v107, v157
	v_mul_f32_e32 v246, v108, v157
	v_mul_f32_e32 v247, v109, v157
	v_exp_f32_e32 v244, v244
	v_exp_f32_e32 v245, v245
	v_exp_f32_e32 v246, v246
	v_exp_f32_e32 v247, v247
	v_add_f32_e32 v244, 1.0, v244
	v_add_f32_e32 v245, 1.0, v245
	v_add_f32_e32 v246, 1.0, v246
	v_add_f32_e32 v247, 1.0, v247
	v_rcp_f32_e32 v244, v244
	v_rcp_f32_e32 v245, v245
	v_rcp_f32_e32 v246, v246
	v_rcp_f32_e32 v247, v247
	s_waitcnt vmcnt(28)
	v_lshlrev_b32_e32 v248, 16, v218
	v_lshlrev_b32_e32 v249, 16, v219
	v_and_b32_e32 v218, 0xffff0000, v218
	v_and_b32_e32 v219, 0xffff0000, v219
	v_fma_f32 v106, v244, v248, v214
	v_fma_f32 v107, v245, v218, v215
	v_fma_f32 v108, v246, v249, v216
	v_fma_f32 v109, v247, v219, v217
	v_cvt_pk_bf16_f32 v244, v106, v107
	v_cvt_pk_bf16_f32 v245, v108, v109
	global_store_dwordx4 v149, v[106:109], s[72:73] offset:64
	global_store_dwordx2 v153, v[244:245], s[58:59] offset:32
	global_load_dwordx4 v[214:217], v151, s[72:73] offset:192
	global_load_dwordx2 v[218:219], v155, s[40:41] offset:96
	v_pk_mul_f32 v[106:107], v[106:107], v[106:107]
	v_pk_mul_f32 v[108:109], v[108:109], v[108:109]
	v_add_f32_e32 v106, v106, v107
	v_add_f32_e32 v108, v108, v109
	v_add_f32_e32 v106, v106, v108
	v_add_f32_e32 v161, v161, v106
	v_mul_f32_e32 v244, v102, v158
	v_mul_f32_e32 v245, v103, v158
	v_mul_f32_e32 v246, v104, v158
	v_mul_f32_e32 v247, v105, v158
	v_exp_f32_e32 v244, v244
	v_exp_f32_e32 v245, v245
	v_exp_f32_e32 v246, v246
	v_exp_f32_e32 v247, v247
	v_add_f32_e32 v244, 1.0, v244
	v_add_f32_e32 v245, 1.0, v245
	v_add_f32_e32 v246, 1.0, v246
	v_add_f32_e32 v247, 1.0, v247
	v_rcp_f32_e32 v244, v244
	v_rcp_f32_e32 v245, v245
	v_rcp_f32_e32 v246, v246
	v_rcp_f32_e32 v247, v247
	s_waitcnt vmcnt(30)
	v_lshlrev_b32_e32 v248, 16, v224
	v_lshlrev_b32_e32 v249, 16, v225
	v_and_b32_e32 v224, 0xffff0000, v224
	v_and_b32_e32 v225, 0xffff0000, v225
	v_fma_f32 v102, v244, v248, v220
	v_fma_f32 v103, v245, v224, v221
	v_fma_f32 v104, v246, v249, v222
	v_fma_f32 v105, v247, v225, v223
	v_cvt_pk_bf16_f32 v244, v102, v103
	v_cvt_pk_bf16_f32 v245, v104, v105
	global_store_dwordx4 v150, v[102:105], s[72:73] offset:64
	global_store_dwordx2 v154, v[244:245], s[58:59] offset:32
	global_load_dwordx4 v[220:223], v148, s[72:73] offset:512
	global_load_dwordx2 v[224:225], v152, s[40:41] offset:256
	v_pk_mul_f32 v[102:103], v[102:103], v[102:103]
	v_pk_mul_f32 v[104:105], v[104:105], v[104:105]
	v_add_f32_e32 v102, v102, v103
	v_add_f32_e32 v104, v104, v105
	v_add_f32_e32 v102, v102, v104
	v_add_f32_e32 v142, v142, v102
	v_mul_f32_e32 v244, v98, v159
	v_mul_f32_e32 v245, v99, v159
	v_mul_f32_e32 v246, v100, v159
	v_mul_f32_e32 v247, v101, v159
	v_exp_f32_e32 v244, v244
	v_exp_f32_e32 v245, v245
	v_exp_f32_e32 v246, v246
	v_exp_f32_e32 v247, v247
	v_add_f32_e32 v244, 1.0, v244
	v_add_f32_e32 v245, 1.0, v245
	v_add_f32_e32 v246, 1.0, v246
	v_add_f32_e32 v247, 1.0, v247
	v_rcp_f32_e32 v244, v244
	v_rcp_f32_e32 v245, v245
	v_rcp_f32_e32 v246, v246
	v_rcp_f32_e32 v247, v247
	s_waitcnt vmcnt(32)
; #define BFLO_(u) __uint_as_float((u) << 16)
; #define BFHI_(u) __uint_as_float((u) & 0xffff0000u)
; #define EPI_CALL(ai, m) epi_block(EPI, g, acc[ai][0][m][0], acc[ai][0][m][1], acc[ai][1][m][0], acc[ai][1][m][1], \
;       brow + ai * HALF + e_wr * 64 + m * 16 + e_fq * 4, tok0, rs, sq);
; __device__ __forceinline__ void epi_block(const int EPI, const GemmArgs& g, f32x4 a00, f32x4 a01, f32x4 a10, f32x4 a11,
;                                           const int fbase, const int tok0, const float (&rs)[4], float (&sq)[4]) {
;     ...
;     } else if (EPI == EPI_PLE) {
;       const size_t idx = (size_t)token * D_ + fbase;
;       const float r = rs[q];
;       float4 hv = *(const float4*)(g.h + idx);
;       uint2 pp = *(const uint2*)(g.pp + idx);
;       const float rl = -r * 1.4426950408889634f;
;       hv.x += BFLO_(pp.x) * __builtin_amdgcn_rcpf(1.f + __builtin_amdgcn_exp2f(v0 * rl));
;       hv.y += BFHI_(pp.x) * __builtin_amdgcn_rcpf(1.f + __builtin_amdgcn_exp2f(v1 * rl));
;       hv.z += BFLO_(pp.y) * __builtin_amdgcn_rcpf(1.f + __builtin_amdgcn_exp2f(v2 * rl));
;       hv.w += BFHI_(pp.y) * __builtin_amdgcn_rcpf(1.f + __builtin_amdgcn_exp2f(v3 * rl));
;       *(float4*)(g.h + idx) = hv;
;       uint2 o; o.x = pack2bf(hv.x, hv.y); o.y = pack2bf(hv.z, hv.w);
;       *(uint2*)(g.outb + idx) = o;
;       sq[q] += (hv.x * hv.x + hv.y * hv.y) + (hv.z * hv.z + hv.w * hv.w);
; __device__ __forceinline__ void gemm_phase(const int WV, const GemmArgs& g, int tile0) {
;     ...
;     EPI_CALL(0, 0) EPI_CALL(0, 1) EPI_CALL(0, 2) EPI_CALL(0, 3)
;     EPI_CALL(1, 0) EPI_CALL(1, 1) EPI_CALL(1, 2) EPI_CALL(1, 3)
	v_lshlrev_b32_e32 v248, 16, v230
	v_lshlrev_b32_e32 v249, 16, v231
	v_and_b32_e32 v230, 0xffff0000, v230
	v_and_b32_e32 v231, 0xffff0000, v231
	v_fma_f32 v98, v244, v248, v226
	v_fma_f32 v99, v245, v230, v227
	v_fma_f32 v100, v246, v249, v228
	v_fma_f32 v101, v247, v231, v229
	v_cvt_pk_bf16_f32 v244, v98, v99
	v_cvt_pk_bf16_f32 v245, v100, v101
	global_store_dwordx4 v151, v[98:101], s[72:73] offset:64
	global_store_dwordx2 v155, v[244:245], s[58:59] offset:32
	global_load_dwordx4 v[226:229], v149, s[72:73] offset:512
	global_load_dwordx2 v[230:231], v153, s[40:41] offset:256
	v_pk_mul_f32 v[98:99], v[98:99], v[98:99]
	v_pk_mul_f32 v[100:101], v[100:101], v[100:101]
	v_add_f32_e32 v98, v98, v99
	v_add_f32_e32 v100, v100, v101
	v_add_f32_e32 v98, v98, v100
	v_add_f32_e32 v143, v143, v98
	v_mul_f32_e32 v244, v94, v156
	v_mul_f32_e32 v245, v95, v156
	v_mul_f32_e32 v246, v96, v156
	v_mul_f32_e32 v247, v97, v156
	v_exp_f32_e32 v244, v244
	v_exp_f32_e32 v245, v245
	v_exp_f32_e32 v246, v246
	v_exp_f32_e32 v247, v247
	v_add_f32_e32 v244, 1.0, v244
	v_add_f32_e32 v245, 1.0, v245
	v_add_f32_e32 v246, 1.0, v246
	v_add_f32_e32 v247, 1.0, v247
	v_rcp_f32_e32 v244, v244
	v_rcp_f32_e32 v245, v245
	v_rcp_f32_e32 v246, v246
	v_rcp_f32_e32 v247, v247
	s_waitcnt vmcnt(34)
	v_lshlrev_b32_e32 v248, 16, v236
	v_lshlrev_b32_e32 v249, 16, v237
	v_and_b32_e32 v236, 0xffff0000, v236
	v_and_b32_e32 v237, 0xffff0000, v237
	v_fma_f32 v94, v244, v248, v232
	v_fma_f32 v95, v245, v236, v233
	v_fma_f32 v96, v246, v249, v234
	v_fma_f32 v97, v247, v237, v235
	v_cvt_pk_bf16_f32 v244, v94, v95
	v_cvt_pk_bf16_f32 v245, v96, v97
	global_store_dwordx4 v148, v[94:97], s[72:73] offset:128
	global_store_dwordx2 v152, v[244:245], s[58:59] offset:64
	global_load_dwordx4 v[232:235], v150, s[72:73] offset:512
	global_load_dwordx2 v[236:237], v154, s[40:41] offset:256
	v_pk_mul_f32 v[94:95], v[94:95], v[94:95]
	v_pk_mul_f32 v[96:97], v[96:97], v[96:97]
	v_add_f32_e32 v94, v94, v95
	v_add_f32_e32 v96, v96, v97
	v_add_f32_e32 v94, v94, v96
	v_add_f32_e32 v160, v160, v94
	v_mul_f32_e32 v244, v90, v157
	v_mul_f32_e32 v245, v91, v157
	v_mul_f32_e32 v246, v92, v157
	v_mul_f32_e32 v247, v93, v157
	v_exp_f32_e32 v244, v244
	v_exp_f32_e32 v245, v245
	v_exp_f32_e32 v246, v246
	v_exp_f32_e32 v247, v247
	v_add_f32_e32 v244, 1.0, v244
	v_add_f32_e32 v245, 1.0, v245
	v_add_f32_e32 v246, 1.0, v246
	v_add_f32_e32 v247, 1.0, v247
	v_rcp_f32_e32 v244, v244
	v_rcp_f32_e32 v245, v245
	v_rcp_f32_e32 v246, v246
	v_rcp_f32_e32 v247, v247
	s_waitcnt vmcnt(36)
	v_lshlrev_b32_e32 v248, 16, v242
	v_lshlrev_b32_e32 v249, 16, v243
	v_and_b32_e32 v242, 0xffff0000, v242
	v_and_b32_e32 v243, 0xffff0000, v243
	v_fma_f32 v90, v244, v248, v238
	v_fma_f32 v91, v245, v242, v239
	v_fma_f32 v92, v246, v249, v240
	v_fma_f32 v93, v247, v243, v241
	v_cvt_pk_bf16_f32 v244, v90, v91
	v_cvt_pk_bf16_f32 v245, v92, v93
	global_store_dwordx4 v149, v[90:93], s[72:73] offset:128
	global_store_dwordx2 v153, v[244:245], s[58:59] offset:64
	global_load_dwordx4 v[238:241], v151, s[72:73] offset:512
	global_load_dwordx2 v[242:243], v155, s[40:41] offset:256
	v_pk_mul_f32 v[90:91], v[90:91], v[90:91]
	v_pk_mul_f32 v[92:93], v[92:93], v[92:93]
	v_add_f32_e32 v90, v90, v91
	v_add_f32_e32 v92, v92, v93
	v_add_f32_e32 v90, v90, v92
	v_add_f32_e32 v161, v161, v90
	v_mul_f32_e32 v244, v86, v158
	v_mul_f32_e32 v245, v87, v158
	v_mul_f32_e32 v246, v88, v158
	v_mul_f32_e32 v247, v89, v158
	v_exp_f32_e32 v244, v244
	v_exp_f32_e32 v245, v245
	v_exp_f32_e32 v246, v246
	v_exp_f32_e32 v247, v247
	v_add_f32_e32 v244, 1.0, v244
	v_add_f32_e32 v245, 1.0, v245
	v_add_f32_e32 v246, 1.0, v246
	v_add_f32_e32 v247, 1.0, v247
	v_rcp_f32_e32 v244, v244
	v_rcp_f32_e32 v245, v245
	v_rcp_f32_e32 v246, v246
	v_rcp_f32_e32 v247, v247
	s_waitcnt vmcnt(36)
	v_lshlrev_b32_e32 v248, 16, v188
	v_lshlrev_b32_e32 v249, 16, v189
	v_and_b32_e32 v188, 0xffff0000, v188
	v_and_b32_e32 v189, 0xffff0000, v189
	v_fma_f32 v86, v244, v248, v184
	v_fma_f32 v87, v245, v188, v185
	v_fma_f32 v88, v246, v249, v186
	v_fma_f32 v89, v247, v189, v187
	v_cvt_pk_bf16_f32 v244, v86, v87
	v_cvt_pk_bf16_f32 v245, v88, v89
	global_store_dwordx4 v150, v[86:89], s[72:73] offset:128
	global_store_dwordx2 v154, v[244:245], s[58:59] offset:64
	global_load_dwordx4 v[184:187], v148, s[72:73] offset:576
	global_load_dwordx2 v[188:189], v152, s[40:41] offset:288
	v_pk_mul_f32 v[86:87], v[86:87], v[86:87]
	v_pk_mul_f32 v[88:89], v[88:89], v[88:89]
	v_add_f32_e32 v86, v86, v87
	v_add_f32_e32 v88, v88, v89
	v_add_f32_e32 v86, v86, v88
	v_add_f32_e32 v142, v142, v86
	v_mul_f32_e32 v244, v82, v159
	v_mul_f32_e32 v245, v83, v159
	v_mul_f32_e32 v246, v84, v159
	v_mul_f32_e32 v247, v85, v159
	v_exp_f32_e32 v244, v244
	v_exp_f32_e32 v245, v245
	v_exp_f32_e32 v246, v246
	v_exp_f32_e32 v247, v247
	v_add_f32_e32 v244, 1.0, v244
	v_add_f32_e32 v245, 1.0, v245
	v_add_f32_e32 v246, 1.0, v246
	v_add_f32_e32 v247, 1.0, v247
	v_rcp_f32_e32 v244, v244
	v_rcp_f32_e32 v245, v245
	v_rcp_f32_e32 v246, v246
	v_rcp_f32_e32 v247, v247
	s_waitcnt vmcnt(36)
; #define BFLO_(u) __uint_as_float((u) << 16)
; #define BFHI_(u) __uint_as_float((u) & 0xffff0000u)
; #define EPI_CALL(ai, m) epi_block(EPI, g, acc[ai][0][m][0], acc[ai][0][m][1], acc[ai][1][m][0], acc[ai][1][m][1], \
;       brow + ai * HALF + e_wr * 64 + m * 16 + e_fq * 4, tok0, rs, sq);
; __device__ __forceinline__ void epi_block(const int EPI, const GemmArgs& g, f32x4 a00, f32x4 a01, f32x4 a10, f32x4 a11,
;                                           const int fbase, const int tok0, const float (&rs)[4], float (&sq)[4]) {
;     ...
;     } else if (EPI == EPI_PLE) {
;       const size_t idx = (size_t)token * D_ + fbase;
;       const float r = rs[q];
;       float4 hv = *(const float4*)(g.h + idx);
;       uint2 pp = *(const uint2*)(g.pp + idx);
;       const float rl = -r * 1.4426950408889634f;
;       hv.x += BFLO_(pp.x) * __builtin_amdgcn_rcpf(1.f + __builtin_amdgcn_exp2f(v0 * rl));
;       hv.y += BFHI_(pp.x) * __builtin_amdgcn_rcpf(1.f + __builtin_amdgcn_exp2f(v1 * rl));
;       hv.z += BFLO_(pp.y) * __builtin_amdgcn_rcpf(1.f + __builtin_amdgcn_exp2f(v2 * rl));
;       hv.w += BFHI_(pp.y) * __builtin_amdgcn_rcpf(1.f + __builtin_amdgcn_exp2f(v3 * rl));
;       *(float4*)(g.h + idx) = hv;
;       uint2 o; o.x = pack2bf(hv.x, hv.y); o.y = pack2bf(hv.z, hv.w);
;       *(uint2*)(g.outb + idx) = o;
;       sq[q] += (hv.x * hv.x + hv.y * hv.y) + (hv.z * hv.z + hv.w * hv.w);
; __device__ __forceinline__ void gemm_phase(const int WV, const GemmArgs& g, int tile0) {
;     ...
;     EPI_CALL(0, 0) EPI_CALL(0, 1) EPI_CALL(0, 2) EPI_CALL(0, 3)
;     EPI_CALL(1, 0) EPI_CALL(1, 1) EPI_CALL(1, 2) EPI_CALL(1, 3)
	v_lshlrev_b32_e32 v248, 16, v194
	v_lshlrev_b32_e32 v249, 16, v195
	v_and_b32_e32 v194, 0xffff0000, v194
	v_and_b32_e32 v195, 0xffff0000, v195
	v_fma_f32 v82, v244, v248, v190
	v_fma_f32 v83, v245, v194, v191
	v_fma_f32 v84, v246, v249, v192
	v_fma_f32 v85, v247, v195, v193
	v_cvt_pk_bf16_f32 v244, v82, v83
	v_cvt_pk_bf16_f32 v245, v84, v85
	global_store_dwordx4 v151, v[82:85], s[72:73] offset:128
	global_store_dwordx2 v155, v[244:245], s[58:59] offset:64
	global_load_dwordx4 v[190:193], v149, s[72:73] offset:576
	global_load_dwordx2 v[194:195], v153, s[40:41] offset:288
	v_pk_mul_f32 v[82:83], v[82:83], v[82:83]
	v_pk_mul_f32 v[84:85], v[84:85], v[84:85]
	v_add_f32_e32 v82, v82, v83
	v_add_f32_e32 v84, v84, v85
	v_add_f32_e32 v82, v82, v84
	v_add_f32_e32 v143, v143, v82
	v_mul_f32_e32 v244, v78, v156
	v_mul_f32_e32 v245, v79, v156
	v_mul_f32_e32 v246, v80, v156
	v_mul_f32_e32 v247, v81, v156
	v_exp_f32_e32 v244, v244
	v_exp_f32_e32 v245, v245
	v_exp_f32_e32 v246, v246
	v_exp_f32_e32 v247, v247
	v_add_f32_e32 v244, 1.0, v244
	v_add_f32_e32 v245, 1.0, v245
	v_add_f32_e32 v246, 1.0, v246
	v_add_f32_e32 v247, 1.0, v247
	v_rcp_f32_e32 v244, v244
	v_rcp_f32_e32 v245, v245
	v_rcp_f32_e32 v246, v246
	v_rcp_f32_e32 v247, v247
	s_waitcnt vmcnt(36)
	v_lshlrev_b32_e32 v248, 16, v200
	v_lshlrev_b32_e32 v249, 16, v201
	v_and_b32_e32 v200, 0xffff0000, v200
	v_and_b32_e32 v201, 0xffff0000, v201
	v_fma_f32 v78, v244, v248, v196
	v_fma_f32 v79, v245, v200, v197
	v_fma_f32 v80, v246, v249, v198
	v_fma_f32 v81, v247, v201, v199
	v_cvt_pk_bf16_f32 v244, v78, v79
	v_cvt_pk_bf16_f32 v245, v80, v81
	global_store_dwordx4 v148, v[78:81], s[72:73] offset:192
	global_store_dwordx2 v152, v[244:245], s[58:59] offset:96
	global_load_dwordx4 v[196:199], v150, s[72:73] offset:576
	global_load_dwordx2 v[200:201], v154, s[40:41] offset:288
	v_pk_mul_f32 v[78:79], v[78:79], v[78:79]
	v_pk_mul_f32 v[80:81], v[80:81], v[80:81]
	v_add_f32_e32 v78, v78, v79
	v_add_f32_e32 v80, v80, v81
	v_add_f32_e32 v78, v78, v80
	v_add_f32_e32 v160, v160, v78
	v_mul_f32_e32 v244, v74, v157
	v_mul_f32_e32 v245, v75, v157
	v_mul_f32_e32 v246, v76, v157
	v_mul_f32_e32 v247, v77, v157
	v_exp_f32_e32 v244, v244
	v_exp_f32_e32 v245, v245
	v_exp_f32_e32 v246, v246
	v_exp_f32_e32 v247, v247
	v_add_f32_e32 v244, 1.0, v244
	v_add_f32_e32 v245, 1.0, v245
	v_add_f32_e32 v246, 1.0, v246
	v_add_f32_e32 v247, 1.0, v247
	v_rcp_f32_e32 v244, v244
	v_rcp_f32_e32 v245, v245
	v_rcp_f32_e32 v246, v246
	v_rcp_f32_e32 v247, v247
	s_waitcnt vmcnt(36)
	v_lshlrev_b32_e32 v248, 16, v206
	v_lshlrev_b32_e32 v249, 16, v207
	v_and_b32_e32 v206, 0xffff0000, v206
	v_and_b32_e32 v207, 0xffff0000, v207
	v_fma_f32 v74, v244, v248, v202
	v_fma_f32 v75, v245, v206, v203
	v_fma_f32 v76, v246, v249, v204
	v_fma_f32 v77, v247, v207, v205
	v_cvt_pk_bf16_f32 v244, v74, v75
	v_cvt_pk_bf16_f32 v245, v76, v77
	global_store_dwordx4 v149, v[74:77], s[72:73] offset:192
	global_store_dwordx2 v153, v[244:245], s[58:59] offset:96
	global_load_dwordx4 v[202:205], v151, s[72:73] offset:576
	global_load_dwordx2 v[206:207], v155, s[40:41] offset:288
	v_pk_mul_f32 v[74:75], v[74:75], v[74:75]
	v_pk_mul_f32 v[76:77], v[76:77], v[76:77]
	v_add_f32_e32 v74, v74, v75
	v_add_f32_e32 v76, v76, v77
	v_add_f32_e32 v74, v74, v76
	v_add_f32_e32 v161, v161, v74
	v_mul_f32_e32 v244, v70, v158
	v_mul_f32_e32 v245, v71, v158
	v_mul_f32_e32 v246, v72, v158
	v_mul_f32_e32 v247, v73, v158
	v_exp_f32_e32 v244, v244
	v_exp_f32_e32 v245, v245
	v_exp_f32_e32 v246, v246
	v_exp_f32_e32 v247, v247
	v_add_f32_e32 v244, 1.0, v244
	v_add_f32_e32 v245, 1.0, v245
	v_add_f32_e32 v246, 1.0, v246
	v_add_f32_e32 v247, 1.0, v247
	v_rcp_f32_e32 v244, v244
	v_rcp_f32_e32 v245, v245
	v_rcp_f32_e32 v246, v246
	v_rcp_f32_e32 v247, v247
	s_waitcnt vmcnt(36)
	v_lshlrev_b32_e32 v248, 16, v212
	v_lshlrev_b32_e32 v249, 16, v213
	v_and_b32_e32 v212, 0xffff0000, v212
	v_and_b32_e32 v213, 0xffff0000, v213
	v_fma_f32 v70, v244, v248, v208
	v_fma_f32 v71, v245, v212, v209
	v_fma_f32 v72, v246, v249, v210
	v_fma_f32 v73, v247, v213, v211
	v_cvt_pk_bf16_f32 v244, v70, v71
	v_cvt_pk_bf16_f32 v245, v72, v73
	global_store_dwordx4 v150, v[70:73], s[72:73] offset:192
	global_store_dwordx2 v154, v[244:245], s[58:59] offset:96
	global_load_dwordx4 v[208:211], v148, s[72:73] offset:640
	global_load_dwordx2 v[212:213], v152, s[40:41] offset:320
	v_pk_mul_f32 v[70:71], v[70:71], v[70:71]
	v_pk_mul_f32 v[72:73], v[72:73], v[72:73]
	v_add_f32_e32 v70, v70, v71
	v_add_f32_e32 v72, v72, v73
	v_add_f32_e32 v70, v70, v72
	v_add_f32_e32 v142, v142, v70
	v_mul_f32_e32 v244, v66, v159
	v_mul_f32_e32 v245, v67, v159
	v_mul_f32_e32 v246, v68, v159
	v_mul_f32_e32 v247, v69, v159
	v_exp_f32_e32 v244, v244
	v_exp_f32_e32 v245, v245
	v_exp_f32_e32 v246, v246
	v_exp_f32_e32 v247, v247
	v_add_f32_e32 v244, 1.0, v244
	v_add_f32_e32 v245, 1.0, v245
	v_add_f32_e32 v246, 1.0, v246
	v_add_f32_e32 v247, 1.0, v247
	v_rcp_f32_e32 v244, v244
	v_rcp_f32_e32 v245, v245
	v_rcp_f32_e32 v246, v246
	v_rcp_f32_e32 v247, v247
	s_waitcnt vmcnt(36)
; #define BFLO_(u) __uint_as_float((u) << 16)
; #define BFHI_(u) __uint_as_float((u) & 0xffff0000u)
; #define EPI_CALL(ai, m) epi_block(EPI, g, acc[ai][0][m][0], acc[ai][0][m][1], acc[ai][1][m][0], acc[ai][1][m][1], \
;       brow + ai * HALF + e_wr * 64 + m * 16 + e_fq * 4, tok0, rs, sq);
; __device__ __forceinline__ void epi_block(const int EPI, const GemmArgs& g, f32x4 a00, f32x4 a01, f32x4 a10, f32x4 a11,
;                                           const int fbase, const int tok0, const float (&rs)[4], float (&sq)[4]) {
;     ...
;     } else if (EPI == EPI_PLE) {
;       const size_t idx = (size_t)token * D_ + fbase;
;       const float r = rs[q];
;       float4 hv = *(const float4*)(g.h + idx);
;       uint2 pp = *(const uint2*)(g.pp + idx);
;       const float rl = -r * 1.4426950408889634f;
;       hv.x += BFLO_(pp.x) * __builtin_amdgcn_rcpf(1.f + __builtin_amdgcn_exp2f(v0 * rl));
;       hv.y += BFHI_(pp.x) * __builtin_amdgcn_rcpf(1.f + __builtin_amdgcn_exp2f(v1 * rl));
;       hv.z += BFLO_(pp.y) * __builtin_amdgcn_rcpf(1.f + __builtin_amdgcn_exp2f(v2 * rl));
;       hv.w += BFHI_(pp.y) * __builtin_amdgcn_rcpf(1.f + __builtin_amdgcn_exp2f(v3 * rl));
;       *(float4*)(g.h + idx) = hv;
;       uint2 o; o.x = pack2bf(hv.x, hv.y); o.y = pack2bf(hv.z, hv.w);
;       *(uint2*)(g.outb + idx) = o;
;       sq[q] += (hv.x * hv.x + hv.y * hv.y) + (hv.z * hv.z + hv.w * hv.w);
; __device__ __forceinline__ void gemm_phase(const int WV, const GemmArgs& g, int tile0) {
;     ...
;     EPI_CALL(0, 0) EPI_CALL(0, 1) EPI_CALL(0, 2) EPI_CALL(0, 3)
;     EPI_CALL(1, 0) EPI_CALL(1, 1) EPI_CALL(1, 2) EPI_CALL(1, 3)
	v_lshlrev_b32_e32 v248, 16, v218
	v_lshlrev_b32_e32 v249, 16, v219
	v_and_b32_e32 v218, 0xffff0000, v218
	v_and_b32_e32 v219, 0xffff0000, v219
	v_fma_f32 v66, v244, v248, v214
	v_fma_f32 v67, v245, v218, v215
	v_fma_f32 v68, v246, v249, v216
	v_fma_f32 v69, v247, v219, v217
	v_cvt_pk_bf16_f32 v244, v66, v67
	v_cvt_pk_bf16_f32 v245, v68, v69
	global_store_dwordx4 v151, v[66:69], s[72:73] offset:192
	global_store_dwordx2 v155, v[244:245], s[58:59] offset:96
	global_load_dwordx4 v[214:217], v149, s[72:73] offset:640
	global_load_dwordx2 v[218:219], v153, s[40:41] offset:320
	v_pk_mul_f32 v[66:67], v[66:67], v[66:67]
	v_pk_mul_f32 v[68:69], v[68:69], v[68:69]
	v_add_f32_e32 v66, v66, v67
	v_add_f32_e32 v68, v68, v69
	v_add_f32_e32 v66, v66, v68
	v_add_f32_e32 v143, v143, v66
	v_mul_f32_e32 v244, v62, v156
	v_mul_f32_e32 v245, v63, v156
	v_mul_f32_e32 v246, v64, v156
	v_mul_f32_e32 v247, v65, v156
	v_exp_f32_e32 v244, v244
	v_exp_f32_e32 v245, v245
	v_exp_f32_e32 v246, v246
	v_exp_f32_e32 v247, v247
	v_add_f32_e32 v244, 1.0, v244
	v_add_f32_e32 v245, 1.0, v245
	v_add_f32_e32 v246, 1.0, v246
	v_add_f32_e32 v247, 1.0, v247
	v_rcp_f32_e32 v244, v244
	v_rcp_f32_e32 v245, v245
	v_rcp_f32_e32 v246, v246
	v_rcp_f32_e32 v247, v247
	s_waitcnt vmcnt(36)
	v_lshlrev_b32_e32 v248, 16, v224
	v_lshlrev_b32_e32 v249, 16, v225
	v_and_b32_e32 v224, 0xffff0000, v224
	v_and_b32_e32 v225, 0xffff0000, v225
	v_fma_f32 v62, v244, v248, v220
	v_fma_f32 v63, v245, v224, v221
	v_fma_f32 v64, v246, v249, v222
	v_fma_f32 v65, v247, v225, v223
	v_cvt_pk_bf16_f32 v244, v62, v63
	v_cvt_pk_bf16_f32 v245, v64, v65
	global_store_dwordx4 v148, v[62:65], s[72:73] offset:512
	global_store_dwordx2 v152, v[244:245], s[58:59] offset:256
	global_load_dwordx4 v[220:223], v150, s[72:73] offset:640
	global_load_dwordx2 v[224:225], v154, s[40:41] offset:320
	v_pk_mul_f32 v[62:63], v[62:63], v[62:63]
	v_pk_mul_f32 v[64:65], v[64:65], v[64:65]
	v_add_f32_e32 v62, v62, v63
	v_add_f32_e32 v64, v64, v65
	v_add_f32_e32 v62, v62, v64
	v_add_f32_e32 v160, v160, v62
	v_mul_f32_e32 v244, v58, v157
	v_mul_f32_e32 v245, v59, v157
	v_mul_f32_e32 v246, v60, v157
	v_mul_f32_e32 v247, v61, v157
	v_exp_f32_e32 v244, v244
	v_exp_f32_e32 v245, v245
	v_exp_f32_e32 v246, v246
	v_exp_f32_e32 v247, v247
	v_add_f32_e32 v244, 1.0, v244
	v_add_f32_e32 v245, 1.0, v245
	v_add_f32_e32 v246, 1.0, v246
	v_add_f32_e32 v247, 1.0, v247
	v_rcp_f32_e32 v244, v244
	v_rcp_f32_e32 v245, v245
	v_rcp_f32_e32 v246, v246
	v_rcp_f32_e32 v247, v247
	s_waitcnt vmcnt(36)
	v_lshlrev_b32_e32 v248, 16, v230
	v_lshlrev_b32_e32 v249, 16, v231
	v_and_b32_e32 v230, 0xffff0000, v230
	v_and_b32_e32 v231, 0xffff0000, v231
	v_fma_f32 v58, v244, v248, v226
	v_fma_f32 v59, v245, v230, v227
	v_fma_f32 v60, v246, v249, v228
	v_fma_f32 v61, v247, v231, v229
	v_cvt_pk_bf16_f32 v244, v58, v59
	v_cvt_pk_bf16_f32 v245, v60, v61
	global_store_dwordx4 v149, v[58:61], s[72:73] offset:512
	global_store_dwordx2 v153, v[244:245], s[58:59] offset:256
	global_load_dwordx4 v[226:229], v151, s[72:73] offset:640
	global_load_dwordx2 v[230:231], v155, s[40:41] offset:320
	v_pk_mul_f32 v[58:59], v[58:59], v[58:59]
	v_pk_mul_f32 v[60:61], v[60:61], v[60:61]
	v_add_f32_e32 v58, v58, v59
	v_add_f32_e32 v60, v60, v61
	v_add_f32_e32 v58, v58, v60
	v_add_f32_e32 v161, v161, v58
	v_mul_f32_e32 v244, v54, v158
	v_mul_f32_e32 v245, v55, v158
	v_mul_f32_e32 v246, v56, v158
	v_mul_f32_e32 v247, v57, v158
	v_exp_f32_e32 v244, v244
	v_exp_f32_e32 v245, v245
	v_exp_f32_e32 v246, v246
	v_exp_f32_e32 v247, v247
	v_add_f32_e32 v244, 1.0, v244
	v_add_f32_e32 v245, 1.0, v245
	v_add_f32_e32 v246, 1.0, v246
	v_add_f32_e32 v247, 1.0, v247
	v_rcp_f32_e32 v244, v244
	v_rcp_f32_e32 v245, v245
	v_rcp_f32_e32 v246, v246
	v_rcp_f32_e32 v247, v247
	s_waitcnt vmcnt(36)
	v_lshlrev_b32_e32 v248, 16, v236
	v_lshlrev_b32_e32 v249, 16, v237
	v_and_b32_e32 v236, 0xffff0000, v236
	v_and_b32_e32 v237, 0xffff0000, v237
	v_fma_f32 v54, v244, v248, v232
	v_fma_f32 v55, v245, v236, v233
	v_fma_f32 v56, v246, v249, v234
	v_fma_f32 v57, v247, v237, v235
	v_cvt_pk_bf16_f32 v244, v54, v55
	v_cvt_pk_bf16_f32 v245, v56, v57
	global_store_dwordx4 v150, v[54:57], s[72:73] offset:512
	global_store_dwordx2 v154, v[244:245], s[58:59] offset:256
	global_load_dwordx4 v[232:235], v148, s[72:73] offset:704
	global_load_dwordx2 v[236:237], v152, s[40:41] offset:352
	v_pk_mul_f32 v[54:55], v[54:55], v[54:55]
	v_pk_mul_f32 v[56:57], v[56:57], v[56:57]
	v_add_f32_e32 v54, v54, v55
	v_add_f32_e32 v56, v56, v57
	v_add_f32_e32 v54, v54, v56
	v_add_f32_e32 v142, v142, v54
	v_mul_f32_e32 v244, v50, v159
	v_mul_f32_e32 v245, v51, v159
	v_mul_f32_e32 v246, v52, v159
	v_mul_f32_e32 v247, v53, v159
	v_exp_f32_e32 v244, v244
	v_exp_f32_e32 v245, v245
	v_exp_f32_e32 v246, v246
	v_exp_f32_e32 v247, v247
	v_add_f32_e32 v244, 1.0, v244
	v_add_f32_e32 v245, 1.0, v245
	v_add_f32_e32 v246, 1.0, v246
	v_add_f32_e32 v247, 1.0, v247
	v_rcp_f32_e32 v244, v244
	v_rcp_f32_e32 v245, v245
	v_rcp_f32_e32 v246, v246
	v_rcp_f32_e32 v247, v247
	s_waitcnt vmcnt(36)
; #define BFLO_(u) __uint_as_float((u) << 16)
; #define BFHI_(u) __uint_as_float((u) & 0xffff0000u)
; #define EPI_CALL(ai, m) epi_block(EPI, g, acc[ai][0][m][0], acc[ai][0][m][1], acc[ai][1][m][0], acc[ai][1][m][1], \
;       brow + ai * HALF + e_wr * 64 + m * 16 + e_fq * 4, tok0, rs, sq);
; __device__ __forceinline__ void epi_block(const int EPI, const GemmArgs& g, f32x4 a00, f32x4 a01, f32x4 a10, f32x4 a11,
;                                           const int fbase, const int tok0, const float (&rs)[4], float (&sq)[4]) {
;     ...
;     } else if (EPI == EPI_PLE) {
;       const size_t idx = (size_t)token * D_ + fbase;
;       const float r = rs[q];
;       float4 hv = *(const float4*)(g.h + idx);
;       uint2 pp = *(const uint2*)(g.pp + idx);
;       const float rl = -r * 1.4426950408889634f;
;       hv.x += BFLO_(pp.x) * __builtin_amdgcn_rcpf(1.f + __builtin_amdgcn_exp2f(v0 * rl));
;       hv.y += BFHI_(pp.x) * __builtin_amdgcn_rcpf(1.f + __builtin_amdgcn_exp2f(v1 * rl));
;       hv.z += BFLO_(pp.y) * __builtin_amdgcn_rcpf(1.f + __builtin_amdgcn_exp2f(v2 * rl));
;       hv.w += BFHI_(pp.y) * __builtin_amdgcn_rcpf(1.f + __builtin_amdgcn_exp2f(v3 * rl));
;       *(float4*)(g.h + idx) = hv;
;       uint2 o; o.x = pack2bf(hv.x, hv.y); o.y = pack2bf(hv.z, hv.w);
;       *(uint2*)(g.outb + idx) = o;
;       sq[q] += (hv.x * hv.x + hv.y * hv.y) + (hv.z * hv.z + hv.w * hv.w);
; __device__ __forceinline__ void gemm_phase(const int WV, const GemmArgs& g, int tile0) {
;     ...
;     EPI_CALL(0, 0) EPI_CALL(0, 1) EPI_CALL(0, 2) EPI_CALL(0, 3)
;     EPI_CALL(1, 0) EPI_CALL(1, 1) EPI_CALL(1, 2) EPI_CALL(1, 3)
	v_lshlrev_b32_e32 v248, 16, v242
	v_lshlrev_b32_e32 v249, 16, v243
	v_and_b32_e32 v242, 0xffff0000, v242
	v_and_b32_e32 v243, 0xffff0000, v243
	v_fma_f32 v50, v244, v248, v238
	v_fma_f32 v51, v245, v242, v239
	v_fma_f32 v52, v246, v249, v240
	v_fma_f32 v53, v247, v243, v241
	v_cvt_pk_bf16_f32 v244, v50, v51
	v_cvt_pk_bf16_f32 v245, v52, v53
	global_store_dwordx4 v151, v[50:53], s[72:73] offset:512
	global_store_dwordx2 v155, v[244:245], s[58:59] offset:256
	global_load_dwordx4 v[238:241], v149, s[72:73] offset:704
	global_load_dwordx2 v[242:243], v153, s[40:41] offset:352
	v_pk_mul_f32 v[50:51], v[50:51], v[50:51]
	v_pk_mul_f32 v[52:53], v[52:53], v[52:53]
	v_add_f32_e32 v50, v50, v51
	v_add_f32_e32 v52, v52, v53
	v_add_f32_e32 v50, v50, v52
	v_add_f32_e32 v143, v143, v50
	v_mul_f32_e32 v244, v46, v156
	v_mul_f32_e32 v245, v47, v156
	v_mul_f32_e32 v246, v48, v156
	v_mul_f32_e32 v247, v49, v156
	v_exp_f32_e32 v244, v244
	v_exp_f32_e32 v245, v245
	v_exp_f32_e32 v246, v246
	v_exp_f32_e32 v247, v247
	v_add_f32_e32 v244, 1.0, v244
	v_add_f32_e32 v245, 1.0, v245
	v_add_f32_e32 v246, 1.0, v246
	v_add_f32_e32 v247, 1.0, v247
	v_rcp_f32_e32 v244, v244
	v_rcp_f32_e32 v245, v245
	v_rcp_f32_e32 v246, v246
	v_rcp_f32_e32 v247, v247
	s_waitcnt vmcnt(36)
	v_lshlrev_b32_e32 v248, 16, v188
	v_lshlrev_b32_e32 v249, 16, v189
	v_and_b32_e32 v188, 0xffff0000, v188
	v_and_b32_e32 v189, 0xffff0000, v189
	v_fma_f32 v46, v244, v248, v184
	v_fma_f32 v47, v245, v188, v185
	v_fma_f32 v48, v246, v249, v186
	v_fma_f32 v49, v247, v189, v187
	v_cvt_pk_bf16_f32 v244, v46, v47
	v_cvt_pk_bf16_f32 v245, v48, v49
	global_store_dwordx4 v148, v[46:49], s[72:73] offset:576
	global_store_dwordx2 v152, v[244:245], s[58:59] offset:288
	global_load_dwordx4 v[184:187], v150, s[72:73] offset:704
	global_load_dwordx2 v[188:189], v154, s[40:41] offset:352
	v_pk_mul_f32 v[46:47], v[46:47], v[46:47]
	v_pk_mul_f32 v[48:49], v[48:49], v[48:49]
	v_add_f32_e32 v46, v46, v47
	v_add_f32_e32 v48, v48, v49
	v_add_f32_e32 v46, v46, v48
	v_add_f32_e32 v160, v160, v46
	v_mul_f32_e32 v244, v42, v157
	v_mul_f32_e32 v245, v43, v157
	v_mul_f32_e32 v246, v44, v157
	v_mul_f32_e32 v247, v45, v157
	v_exp_f32_e32 v244, v244
	v_exp_f32_e32 v245, v245
	v_exp_f32_e32 v246, v246
	v_exp_f32_e32 v247, v247
	v_add_f32_e32 v244, 1.0, v244
	v_add_f32_e32 v245, 1.0, v245
	v_add_f32_e32 v246, 1.0, v246
	v_add_f32_e32 v247, 1.0, v247
	v_rcp_f32_e32 v244, v244
	v_rcp_f32_e32 v245, v245
	v_rcp_f32_e32 v246, v246
	v_rcp_f32_e32 v247, v247
	s_waitcnt vmcnt(36)
	v_lshlrev_b32_e32 v248, 16, v194
	v_lshlrev_b32_e32 v249, 16, v195
	v_and_b32_e32 v194, 0xffff0000, v194
	v_and_b32_e32 v195, 0xffff0000, v195
	v_fma_f32 v42, v244, v248, v190
	v_fma_f32 v43, v245, v194, v191
	v_fma_f32 v44, v246, v249, v192
	v_fma_f32 v45, v247, v195, v193
	v_cvt_pk_bf16_f32 v244, v42, v43
	v_cvt_pk_bf16_f32 v245, v44, v45
	global_store_dwordx4 v149, v[42:45], s[72:73] offset:576
	global_store_dwordx2 v153, v[244:245], s[58:59] offset:288
	global_load_dwordx4 v[190:193], v151, s[72:73] offset:704
	global_load_dwordx2 v[194:195], v155, s[40:41] offset:352
	v_pk_mul_f32 v[42:43], v[42:43], v[42:43]
	v_pk_mul_f32 v[44:45], v[44:45], v[44:45]
	v_add_f32_e32 v42, v42, v43
	v_add_f32_e32 v44, v44, v45
	v_add_f32_e32 v42, v42, v44
	v_add_f32_e32 v161, v161, v42
	v_mul_f32_e32 v244, v38, v158
	v_mul_f32_e32 v245, v39, v158
	v_mul_f32_e32 v246, v40, v158
	v_mul_f32_e32 v247, v41, v158
	v_exp_f32_e32 v244, v244
	v_exp_f32_e32 v245, v245
	v_exp_f32_e32 v246, v246
	v_exp_f32_e32 v247, v247
	v_add_f32_e32 v244, 1.0, v244
	v_add_f32_e32 v245, 1.0, v245
	v_add_f32_e32 v246, 1.0, v246
	v_add_f32_e32 v247, 1.0, v247
	v_rcp_f32_e32 v244, v244
	v_rcp_f32_e32 v245, v245
	v_rcp_f32_e32 v246, v246
	v_rcp_f32_e32 v247, v247
	s_waitcnt vmcnt(36)
	v_lshlrev_b32_e32 v248, 16, v200
	v_lshlrev_b32_e32 v249, 16, v201
	v_and_b32_e32 v200, 0xffff0000, v200
	v_and_b32_e32 v201, 0xffff0000, v201
	v_fma_f32 v38, v244, v248, v196
	v_fma_f32 v39, v245, v200, v197
	v_fma_f32 v40, v246, v249, v198
	v_fma_f32 v41, v247, v201, v199
	v_cvt_pk_bf16_f32 v244, v38, v39
	v_cvt_pk_bf16_f32 v245, v40, v41
	global_store_dwordx4 v150, v[38:41], s[72:73] offset:576
	global_store_dwordx2 v154, v[244:245], s[58:59] offset:288
	s_nop 1
	v_pk_mul_f32 v[38:39], v[38:39], v[38:39]
	v_pk_mul_f32 v[40:41], v[40:41], v[40:41]
	v_add_f32_e32 v38, v38, v39
	v_add_f32_e32 v40, v40, v41
	v_add_f32_e32 v38, v38, v40
	v_add_f32_e32 v142, v142, v38
	v_mul_f32_e32 v244, v34, v159
	v_mul_f32_e32 v245, v35, v159
	v_mul_f32_e32 v246, v36, v159
	v_mul_f32_e32 v247, v37, v159
	v_exp_f32_e32 v244, v244
	v_exp_f32_e32 v245, v245
	v_exp_f32_e32 v246, v246
	v_exp_f32_e32 v247, v247
	v_add_f32_e32 v244, 1.0, v244
	v_add_f32_e32 v245, 1.0, v245
	v_add_f32_e32 v246, 1.0, v246
	v_add_f32_e32 v247, 1.0, v247
	v_rcp_f32_e32 v244, v244
	v_rcp_f32_e32 v245, v245
	v_rcp_f32_e32 v246, v246
	v_rcp_f32_e32 v247, v247
	s_waitcnt vmcnt(34)
	v_lshlrev_b32_e32 v248, 16, v206
	v_lshlrev_b32_e32 v249, 16, v207
	v_and_b32_e32 v206, 0xffff0000, v206
	v_and_b32_e32 v207, 0xffff0000, v207
	v_fma_f32 v34, v244, v248, v202
	v_fma_f32 v35, v245, v206, v203
	v_fma_f32 v36, v246, v249, v204
	v_fma_f32 v37, v247, v207, v205
	v_cvt_pk_bf16_f32 v244, v34, v35
	v_cvt_pk_bf16_f32 v245, v36, v37
	global_store_dwordx4 v151, v[34:37], s[72:73] offset:576
	global_store_dwordx2 v155, v[244:245], s[58:59] offset:288
	s_nop 1
	v_pk_mul_f32 v[34:35], v[34:35], v[34:35]
	v_pk_mul_f32 v[36:37], v[36:37], v[36:37]
	v_add_f32_e32 v34, v34, v35
	v_add_f32_e32 v36, v36, v37
	v_add_f32_e32 v34, v34, v36
	v_add_f32_e32 v143, v143, v34
	v_mul_f32_e32 v244, v30, v156
	v_mul_f32_e32 v245, v31, v156
	v_mul_f32_e32 v246, v32, v156
	v_mul_f32_e32 v247, v33, v156
	v_exp_f32_e32 v244, v244
	v_exp_f32_e32 v245, v245
	v_exp_f32_e32 v246, v246
	v_exp_f32_e32 v247, v247
	v_add_f32_e32 v244, 1.0, v244
	v_add_f32_e32 v245, 1.0, v245
	v_add_f32_e32 v246, 1.0, v246
	v_add_f32_e32 v247, 1.0, v247
	v_rcp_f32_e32 v244, v244
	v_rcp_f32_e32 v245, v245
	v_rcp_f32_e32 v246, v246
	v_rcp_f32_e32 v247, v247
	s_waitcnt vmcnt(32)
; #define BFLO_(u) __uint_as_float((u) << 16)
; #define BFHI_(u) __uint_as_float((u) & 0xffff0000u)
; #define EPI_CALL(ai, m) epi_block(EPI, g, acc[ai][0][m][0], acc[ai][0][m][1], acc[ai][1][m][0], acc[ai][1][m][1], \
;       brow + ai * HALF + e_wr * 64 + m * 16 + e_fq * 4, tok0, rs, sq);
; __device__ __forceinline__ void epi_block(const int EPI, const GemmArgs& g, f32x4 a00, f32x4 a01, f32x4 a10, f32x4 a11,
;                                           const int fbase, const int tok0, const float (&rs)[4], float (&sq)[4]) {
;     ...
;     } else if (EPI == EPI_PLE) {
;       const size_t idx = (size_t)token * D_ + fbase;
;       const float r = rs[q];
;       float4 hv = *(const float4*)(g.h + idx);
;       uint2 pp = *(const uint2*)(g.pp + idx);
;       const float rl = -r * 1.4426950408889634f;
;       hv.x += BFLO_(pp.x) * __builtin_amdgcn_rcpf(1.f + __builtin_amdgcn_exp2f(v0 * rl));
;       hv.y += BFHI_(pp.x) * __builtin_amdgcn_rcpf(1.f + __builtin_amdgcn_exp2f(v1 * rl));
;       hv.z += BFLO_(pp.y) * __builtin_amdgcn_rcpf(1.f + __builtin_amdgcn_exp2f(v2 * rl));
;       hv.w += BFHI_(pp.y) * __builtin_amdgcn_rcpf(1.f + __builtin_amdgcn_exp2f(v3 * rl));
;       *(float4*)(g.h + idx) = hv;
;       uint2 o; o.x = pack2bf(hv.x, hv.y); o.y = pack2bf(hv.z, hv.w);
;       *(uint2*)(g.outb + idx) = o;
;       sq[q] += (hv.x * hv.x + hv.y * hv.y) + (hv.z * hv.z + hv.w * hv.w);
; __device__ __forceinline__ void gemm_phase(const int WV, const GemmArgs& g, int tile0) {
;     ...
;     EPI_CALL(0, 0) EPI_CALL(0, 1) EPI_CALL(0, 2) EPI_CALL(0, 3)
;     EPI_CALL(1, 0) EPI_CALL(1, 1) EPI_CALL(1, 2) EPI_CALL(1, 3)
	v_lshlrev_b32_e32 v248, 16, v212
	v_lshlrev_b32_e32 v249, 16, v213
	v_and_b32_e32 v212, 0xffff0000, v212
	v_and_b32_e32 v213, 0xffff0000, v213
	v_fma_f32 v30, v244, v248, v208
	v_fma_f32 v31, v245, v212, v209
	v_fma_f32 v32, v246, v249, v210
	v_fma_f32 v33, v247, v213, v211
	v_cvt_pk_bf16_f32 v244, v30, v31
	v_cvt_pk_bf16_f32 v245, v32, v33
	global_store_dwordx4 v148, v[30:33], s[72:73] offset:640
	global_store_dwordx2 v152, v[244:245], s[58:59] offset:320
	s_nop 1
	v_pk_mul_f32 v[30:31], v[30:31], v[30:31]
	v_pk_mul_f32 v[32:33], v[32:33], v[32:33]
	v_add_f32_e32 v30, v30, v31
	v_add_f32_e32 v32, v32, v33
	v_add_f32_e32 v30, v30, v32
	v_add_f32_e32 v160, v160, v30
	v_mul_f32_e32 v244, v26, v157
	v_mul_f32_e32 v245, v27, v157
	v_mul_f32_e32 v246, v28, v157
	v_mul_f32_e32 v247, v29, v157
	v_exp_f32_e32 v244, v244
	v_exp_f32_e32 v245, v245
	v_exp_f32_e32 v246, v246
	v_exp_f32_e32 v247, v247
	v_add_f32_e32 v244, 1.0, v244
	v_add_f32_e32 v245, 1.0, v245
	v_add_f32_e32 v246, 1.0, v246
	v_add_f32_e32 v247, 1.0, v247
	v_rcp_f32_e32 v244, v244
	v_rcp_f32_e32 v245, v245
	v_rcp_f32_e32 v246, v246
	v_rcp_f32_e32 v247, v247
	s_waitcnt vmcnt(30)
	v_lshlrev_b32_e32 v248, 16, v218
	v_lshlrev_b32_e32 v249, 16, v219
	v_and_b32_e32 v218, 0xffff0000, v218
	v_and_b32_e32 v219, 0xffff0000, v219
	v_fma_f32 v26, v244, v248, v214
	v_fma_f32 v27, v245, v218, v215
	v_fma_f32 v28, v246, v249, v216
	v_fma_f32 v29, v247, v219, v217
	v_cvt_pk_bf16_f32 v244, v26, v27
	v_cvt_pk_bf16_f32 v245, v28, v29
	global_store_dwordx4 v149, v[26:29], s[72:73] offset:640
	global_store_dwordx2 v153, v[244:245], s[58:59] offset:320
	s_nop 1
	v_pk_mul_f32 v[26:27], v[26:27], v[26:27]
	v_pk_mul_f32 v[28:29], v[28:29], v[28:29]
	v_add_f32_e32 v26, v26, v27
	v_add_f32_e32 v28, v28, v29
	v_add_f32_e32 v26, v26, v28
	v_add_f32_e32 v161, v161, v26
	v_mul_f32_e32 v244, v22, v158
	v_mul_f32_e32 v245, v23, v158
	v_mul_f32_e32 v246, v24, v158
	v_mul_f32_e32 v247, v25, v158
	v_exp_f32_e32 v244, v244
	v_exp_f32_e32 v245, v245
	v_exp_f32_e32 v246, v246
	v_exp_f32_e32 v247, v247
	v_add_f32_e32 v244, 1.0, v244
	v_add_f32_e32 v245, 1.0, v245
	v_add_f32_e32 v246, 1.0, v246
	v_add_f32_e32 v247, 1.0, v247
	v_rcp_f32_e32 v244, v244
	v_rcp_f32_e32 v245, v245
	v_rcp_f32_e32 v246, v246
	v_rcp_f32_e32 v247, v247
	s_waitcnt vmcnt(28)
	v_lshlrev_b32_e32 v248, 16, v224
	v_lshlrev_b32_e32 v249, 16, v225
	v_and_b32_e32 v224, 0xffff0000, v224
	v_and_b32_e32 v225, 0xffff0000, v225
	v_fma_f32 v22, v244, v248, v220
	v_fma_f32 v23, v245, v224, v221
	v_fma_f32 v24, v246, v249, v222
	v_fma_f32 v25, v247, v225, v223
	v_cvt_pk_bf16_f32 v244, v22, v23
	v_cvt_pk_bf16_f32 v245, v24, v25
	global_store_dwordx4 v150, v[22:25], s[72:73] offset:640
	global_store_dwordx2 v154, v[244:245], s[58:59] offset:320
	s_nop 1
	v_pk_mul_f32 v[22:23], v[22:23], v[22:23]
	v_pk_mul_f32 v[24:25], v[24:25], v[24:25]
	v_add_f32_e32 v22, v22, v23
	v_add_f32_e32 v24, v24, v25
	v_add_f32_e32 v22, v22, v24
	v_add_f32_e32 v142, v142, v22
	v_mul_f32_e32 v244, v18, v159
	v_mul_f32_e32 v245, v19, v159
	v_mul_f32_e32 v246, v20, v159
	v_mul_f32_e32 v247, v21, v159
	v_exp_f32_e32 v244, v244
	v_exp_f32_e32 v245, v245
	v_exp_f32_e32 v246, v246
	v_exp_f32_e32 v247, v247
	v_add_f32_e32 v244, 1.0, v244
	v_add_f32_e32 v245, 1.0, v245
	v_add_f32_e32 v246, 1.0, v246
	v_add_f32_e32 v247, 1.0, v247
	v_rcp_f32_e32 v244, v244
	v_rcp_f32_e32 v245, v245
	v_rcp_f32_e32 v246, v246
	v_rcp_f32_e32 v247, v247
	s_waitcnt vmcnt(26)
	v_lshlrev_b32_e32 v248, 16, v230
	v_lshlrev_b32_e32 v249, 16, v231
	v_and_b32_e32 v230, 0xffff0000, v230
	v_and_b32_e32 v231, 0xffff0000, v231
	v_fma_f32 v18, v244, v248, v226
	v_fma_f32 v19, v245, v230, v227
	v_fma_f32 v20, v246, v249, v228
	v_fma_f32 v21, v247, v231, v229
	v_cvt_pk_bf16_f32 v244, v18, v19
	v_cvt_pk_bf16_f32 v245, v20, v21
	global_store_dwordx4 v151, v[18:21], s[72:73] offset:640
	global_store_dwordx2 v155, v[244:245], s[58:59] offset:320
	s_nop 1
	v_pk_mul_f32 v[18:19], v[18:19], v[18:19]
	v_pk_mul_f32 v[20:21], v[20:21], v[20:21]
	v_add_f32_e32 v18, v18, v19
	v_add_f32_e32 v20, v20, v21
	v_add_f32_e32 v18, v18, v20
	v_add_f32_e32 v143, v143, v18
	v_mul_f32_e32 v244, v14, v156
	v_mul_f32_e32 v245, v15, v156
	v_mul_f32_e32 v246, v16, v156
	v_mul_f32_e32 v247, v17, v156
	v_exp_f32_e32 v244, v244
	v_exp_f32_e32 v245, v245
	v_exp_f32_e32 v246, v246
	v_exp_f32_e32 v247, v247
	v_add_f32_e32 v244, 1.0, v244
	v_add_f32_e32 v245, 1.0, v245
	v_add_f32_e32 v246, 1.0, v246
	v_add_f32_e32 v247, 1.0, v247
	v_rcp_f32_e32 v244, v244
	v_rcp_f32_e32 v245, v245
	v_rcp_f32_e32 v246, v246
	v_rcp_f32_e32 v247, v247
	s_waitcnt vmcnt(24)
; #define BFLO_(u) __uint_as_float((u) << 16)
; #define BFHI_(u) __uint_as_float((u) & 0xffff0000u)
; __device__ __forceinline__ void epi_block(const int EPI, const GemmArgs& g, f32x4 a00, f32x4 a01, f32x4 a10, f32x4 a11,
;                                           const int fbase, const int tok0, const float (&rs)[4], float (&sq)[4]) {
;     ...
;     } else if (EPI == EPI_PLE) {
;       const size_t idx = (size_t)token * D_ + fbase;
;       const float r = rs[q];
;       float4 hv = *(const float4*)(g.h + idx);
;       uint2 pp = *(const uint2*)(g.pp + idx);
;       const float rl = -r * 1.4426950408889634f;
;       hv.x += BFLO_(pp.x) * __builtin_amdgcn_rcpf(1.f + __builtin_amdgcn_exp2f(v0 * rl));
;       hv.y += BFHI_(pp.x) * __builtin_amdgcn_rcpf(1.f + __builtin_amdgcn_exp2f(v1 * rl));
;       hv.z += BFLO_(pp.y) * __builtin_amdgcn_rcpf(1.f + __builtin_amdgcn_exp2f(v2 * rl));
;       hv.w += BFHI_(pp.y) * __builtin_amdgcn_rcpf(1.f + __builtin_amdgcn_exp2f(v3 * rl));
;       *(float4*)(g.h + idx) = hv;
;       uint2 o; o.x = pack2bf(hv.x, hv.y); o.y = pack2bf(hv.z, hv.w);
;       *(uint2*)(g.outb + idx) = o;
;       sq[q] += (hv.x * hv.x + hv.y * hv.y) + (hv.z * hv.z + hv.w * hv.w);
; __device__ __forceinline__ void gemm_phase(const int WV, const GemmArgs& g, int tile0) {
;     ...
;     if (EPI == EPI_RES || EPI == EPI_PLE) {
; #pragma unroll
;       for (int q = 0; q < 4; ++q) {
;         float s = sq[q];
;         s += __shfl_xor(s, 16); s += __shfl_xor(s, 32);
;         if (e_fq == 0) atomicAdd(g.ssq_out + tok0 + (q >> 1) * HALF + (q & 1) * 16, s);
;       }
	v_lshlrev_b32_e32 v248, 16, v236
	v_lshlrev_b32_e32 v249, 16, v237
	v_and_b32_e32 v236, 0xffff0000, v236
	v_and_b32_e32 v237, 0xffff0000, v237
	v_fma_f32 v14, v244, v248, v232
	v_fma_f32 v15, v245, v236, v233
	v_fma_f32 v16, v246, v249, v234
	v_fma_f32 v17, v247, v237, v235
	v_cvt_pk_bf16_f32 v244, v14, v15
	v_cvt_pk_bf16_f32 v245, v16, v17
	global_store_dwordx4 v148, v[14:17], s[72:73] offset:704
	global_store_dwordx2 v152, v[244:245], s[58:59] offset:352
	s_nop 1
	v_pk_mul_f32 v[14:15], v[14:15], v[14:15]
	v_pk_mul_f32 v[16:17], v[16:17], v[16:17]
	v_add_f32_e32 v14, v14, v15
	v_add_f32_e32 v16, v16, v17
	v_add_f32_e32 v14, v14, v16
	v_add_f32_e32 v160, v160, v14
	v_mul_f32_e32 v244, v10, v157
	v_mul_f32_e32 v245, v11, v157
	v_mul_f32_e32 v246, v12, v157
	v_mul_f32_e32 v247, v13, v157
	v_exp_f32_e32 v244, v244
	v_exp_f32_e32 v245, v245
	v_exp_f32_e32 v246, v246
	v_exp_f32_e32 v247, v247
	v_add_f32_e32 v244, 1.0, v244
	v_add_f32_e32 v245, 1.0, v245
	v_add_f32_e32 v246, 1.0, v246
	v_add_f32_e32 v247, 1.0, v247
	v_rcp_f32_e32 v244, v244
	v_rcp_f32_e32 v245, v245
	v_rcp_f32_e32 v246, v246
	v_rcp_f32_e32 v247, v247
	s_waitcnt vmcnt(22)
	v_lshlrev_b32_e32 v248, 16, v242
	v_lshlrev_b32_e32 v249, 16, v243
	v_and_b32_e32 v242, 0xffff0000, v242
	v_and_b32_e32 v243, 0xffff0000, v243
	v_fma_f32 v10, v244, v248, v238
	v_fma_f32 v11, v245, v242, v239
	v_fma_f32 v12, v246, v249, v240
	v_fma_f32 v13, v247, v243, v241
	v_cvt_pk_bf16_f32 v244, v10, v11
	v_cvt_pk_bf16_f32 v245, v12, v13
	global_store_dwordx4 v149, v[10:13], s[72:73] offset:704
	global_store_dwordx2 v153, v[244:245], s[58:59] offset:352
	s_nop 1
	v_pk_mul_f32 v[10:11], v[10:11], v[10:11]
	v_pk_mul_f32 v[12:13], v[12:13], v[12:13]
	v_add_f32_e32 v10, v10, v11
	v_add_f32_e32 v12, v12, v13
	v_add_f32_e32 v10, v10, v12
	v_add_f32_e32 v161, v161, v10
	v_mul_f32_e32 v244, v6, v158
	v_mul_f32_e32 v245, v7, v158
	v_mul_f32_e32 v246, v8, v158
	v_mul_f32_e32 v247, v9, v158
	v_exp_f32_e32 v244, v244
	v_exp_f32_e32 v245, v245
	v_exp_f32_e32 v246, v246
	v_exp_f32_e32 v247, v247
	v_add_f32_e32 v244, 1.0, v244
	v_add_f32_e32 v245, 1.0, v245
	v_add_f32_e32 v246, 1.0, v246
	v_add_f32_e32 v247, 1.0, v247
	v_rcp_f32_e32 v244, v244
	v_rcp_f32_e32 v245, v245
	v_rcp_f32_e32 v246, v246
	v_rcp_f32_e32 v247, v247
	s_waitcnt vmcnt(20)
	v_lshlrev_b32_e32 v248, 16, v188
	v_lshlrev_b32_e32 v249, 16, v189
	v_and_b32_e32 v188, 0xffff0000, v188
	v_and_b32_e32 v189, 0xffff0000, v189
	v_fma_f32 v6, v244, v248, v184
	v_fma_f32 v7, v245, v188, v185
	v_fma_f32 v8, v246, v249, v186
	v_fma_f32 v9, v247, v189, v187
	v_cvt_pk_bf16_f32 v244, v6, v7
	v_cvt_pk_bf16_f32 v245, v8, v9
	global_store_dwordx4 v150, v[6:9], s[72:73] offset:704
	global_store_dwordx2 v154, v[244:245], s[58:59] offset:352
	s_nop 1
	v_pk_mul_f32 v[6:7], v[6:7], v[6:7]
	v_pk_mul_f32 v[8:9], v[8:9], v[8:9]
	v_add_f32_e32 v6, v6, v7
	v_add_f32_e32 v8, v8, v9
	v_add_f32_e32 v6, v6, v8
	v_add_f32_e32 v142, v142, v6
	v_mul_f32_e32 v244, v2, v159
	v_mul_f32_e32 v245, v3, v159
	v_mul_f32_e32 v246, v4, v159
	v_mul_f32_e32 v247, v5, v159
	v_exp_f32_e32 v244, v244
	v_exp_f32_e32 v245, v245
	v_exp_f32_e32 v246, v246
	v_exp_f32_e32 v247, v247
	v_add_f32_e32 v244, 1.0, v244
	v_add_f32_e32 v245, 1.0, v245
	v_add_f32_e32 v246, 1.0, v246
	v_add_f32_e32 v247, 1.0, v247
	v_rcp_f32_e32 v244, v244
	v_rcp_f32_e32 v245, v245
	v_rcp_f32_e32 v246, v246
	v_rcp_f32_e32 v247, v247
	s_waitcnt vmcnt(18)
	v_lshlrev_b32_e32 v248, 16, v194
	v_lshlrev_b32_e32 v249, 16, v195
	v_and_b32_e32 v194, 0xffff0000, v194
	v_and_b32_e32 v195, 0xffff0000, v195
	v_fma_f32 v2, v244, v248, v190
	v_fma_f32 v3, v245, v194, v191
	v_fma_f32 v4, v246, v249, v192
	v_fma_f32 v5, v247, v195, v193
	v_cvt_pk_bf16_f32 v244, v2, v3
	v_cvt_pk_bf16_f32 v245, v4, v5
	global_store_dwordx4 v151, v[2:5], s[72:73] offset:704
	global_store_dwordx2 v155, v[244:245], s[58:59] offset:352
	s_nop 1
	v_pk_mul_f32 v[2:3], v[2:3], v[2:3]
	v_pk_mul_f32 v[4:5], v[4:5], v[4:5]
	v_add_f32_e32 v2, v2, v3
	v_add_f32_e32 v4, v4, v5
	v_add_f32_e32 v2, v2, v4
	v_add_f32_e32 v143, v143, v2
	v_readlane_b32 s4, v250, 43
	v_readlane_b32 s5, v250, 44
	v_cmp_eq_u32_e32 vcc, 0, v183
	ds_bpermute_b32 v0, v163, v160
	s_waitcnt lgkmcnt(0)
	v_add_f32_e32 v0, v160, v0
	ds_bpermute_b32 v4, v164, v0
	v_lshl_add_u64 v[2:3], v[140:141], 2, s[4:5]
	s_and_saveexec_b64 s[8:9], vcc
	s_cbranch_execz .Lple_t0
	s_waitcnt lgkmcnt(0)
	v_add_f32_e32 v0, v0, v4
	global_atomic_add_f32 v[2:3], v0, off
.Lple_t0:
	s_or_b64 exec, exec, s[8:9]
	ds_bpermute_b32 v0, v163, v161
	s_waitcnt lgkmcnt(0)
	v_add_f32_e32 v0, v161, v0
	ds_bpermute_b32 v4, v164, v0
	s_and_saveexec_b64 s[8:9], vcc
	s_cbranch_execz .Lple_t1
	s_waitcnt lgkmcnt(0)
	v_add_f32_e32 v0, v0, v4
	global_atomic_add_f32 v[2:3], v0, off offset:64
.Lple_t1:
	s_or_b64 exec, exec, s[8:9]
	ds_bpermute_b32 v0, v163, v142
	s_waitcnt lgkmcnt(0)
	v_add_f32_e32 v0, v142, v0
	ds_bpermute_b32 v4, v164, v0
	s_and_saveexec_b64 s[8:9], vcc
	s_cbranch_execz .Lple_t2
	s_waitcnt lgkmcnt(0)
	v_add_f32_e32 v0, v0, v4
	global_atomic_add_f32 v[2:3], v0, off offset:512
.Lple_t2:
	s_or_b64 exec, exec, s[8:9]
	ds_bpermute_b32 v0, v163, v143
	s_waitcnt lgkmcnt(0)
	v_add_f32_e32 v0, v143, v0
	ds_bpermute_b32 v4, v164, v0
	s_and_saveexec_b64 s[8:9], vcc
	s_cbranch_execz .Lple_t3
	s_waitcnt lgkmcnt(0)
	v_add_f32_e32 v0, v0, v4
	global_atomic_add_f32 v[2:3], v0, off offset:576

; #define EPI_CALL(ai, m) epi_block(EPI, g, acc[ai][0][m][0], acc[ai][0][m][1], acc[ai][1][m][0], acc[ai][1][m][1], \
;       brow + ai * HALF + e_wr * 64 + m * 16 + e_fq * 4, tok0, rs, sq);
; __device__ __forceinline__ void gemm_phase(const int WV, const GemmArgs& g, int tile0) {
;     ...
;     const int e_wr = tid2 >> 8, e_wc = (tid2 >> 6) & 3, e_fr = tid2 & 15, e_fq = (tid2 >> 4) & 3;
;     const int tok0 = bcol + e_wc * 32 + e_fr;
;     float rs[4] = {1.f, 1.f, 1.f, 1.f}, sq[4] = {0.f, 0.f, 0.f, 0.f};
;     if (EPI == EPI_IN || EPI == EPI_FF1 || EPI == EPI_PLE) {
; #pragma unroll
;       for (int q = 0; q < 4; ++q) rs[q] = rsqrtf(g.ssq_in[tok0 + (q >> 1) * HALF + (q & 1) * 16] * (1.f / D_) + NEPS);
;     }
;     ...
;     EPI_CALL(0, 0) EPI_CALL(0, 1) EPI_CALL(0, 2) EPI_CALL(0, 3)
;     EPI_CALL(1, 0) EPI_CALL(1, 1) EPI_CALL(1, 2) EPI_CALL(1, 3)
.LBB0_446:
	v_bfe_u32 v183, v0, 4, 2
	v_ashrrev_i32_e32 v0, 2, v0
	v_and_b32_e32 v142, 0xffffffc0, v0
	v_add_u32_e32 v143, s50, v142
	v_lshlrev_b32_e32 v0, 2, v183
	v_or_b32_e32 v148, v143, v0
	v_ashrrev_i32_e32 v149, 31, v148
	s_cmp_eq_u32 s55, 1
	s_cbranch_scc1 .Lres_epi
	s_cmp_eq_u32 s55, 4
	s_cbranch_scc1 .Lple_epi
	v_cmp_gt_i32_e64 s[10:11], s77, v148
	v_cmp_lt_i32_e64 s[8:9], s60, v148
	s_cmp_lt_i32 s55, 3
	s_mov_b64 s[12:13], -1
	s_cbranch_scc1 .LBB0_452
	s_cmp_gt_i32 s55, 3
	s_cbranch_scc0 .LBB0_449

; __device__ __forceinline__ void epi_block(const int EPI, const GemmArgs& g, f32x4 a00, f32x4 a01, f32x4 a10, f32x4 a11,
;                                           const int fbase, const int tok0, const float (&rs)[4], float (&sq)[4]) {
; #pragma unroll
;   for (int q = 0; q < 4; ++q) {
;     const f32x4 av = q == 0 ? a00 : q == 1 ? a01 : q == 2 ? a10 : a11;
;     const int token = tok0 + (q >> 1) * HALF + (q & 1) * 16;
;     float v0 = av[0], v1 = av[1], v2 = av[2], v3 = av[3];
;     if (EPI == EPI_IN) {
;       if (fbase < DIN) {
;         const float r = rs[q];
;         v0 *= r; v1 *= r; v2 *= r; v3 *= r;
;         uint2 o; o.x = pack2bf(v0, v1); o.y = pack2bf(v2, v3);
;         *(uint2*)(g.outb + (size_t)token * DIN + fbase) = o;
;         if (fbase < NSH && (token & 31) == 31) *(uint2*)(g.bnd + (size_t)(token >> 5) * NSH + fbase) = o;
;         if (fbase >= DIN - 16) {
;           const int hh = fbase - (DIN - 16);
;           const int bb = token >> 14, ss = token & (S_ - 1);
;           float vv[4] = {v0, v1, v2, v3};
; #pragma unroll
;           for (int j = 0; j < 4; ++j) {
;             float xx = vv[j] + g.b_f[hh + j];
;             g.lf[((size_t)(bb * 16 + hh + j) << 14) + ss] = fminf(xx, 0.f) - log1pf(__expf(-fabsf(xx)));
;           }
;         }
;       }
;     } else if (EPI == EPI_RES) {
;       const size_t idx = (size_t)token * D_ + fbase;
;       float4 hv = *(const float4*)(g.h + idx);
;       hv.x += v0; hv.y += v1; hv.z += v2; hv.w += v3;
;       *(float4*)(g.h + idx) = hv;
;       uint2 o; o.x = pack2bf(hv.x, hv.y); o.y = pack2bf(hv.z, hv.w);
;       *(uint2*)(g.outb + idx) = o;
;       sq[q] += (hv.x * hv.x + hv.y * hv.y) + (hv.z * hv.z + hv.w * hv.w);
;     } else if (EPI == EPI_FF1) {
;       const float r = rs[q];
;       v0 = fmaxf(v0 * r, 0.f); v1 = fmaxf(v1 * r, 0.f); v2 = fmaxf(v2 * r, 0.f); v3 = fmaxf(v3 * r, 0.f);
;       uint2 o; o.x = pack2bf(v0 * v0, v1 * v1); o.y = pack2bf(v2 * v2, v3 * v3);
;       *(uint2*)(g.outb + (size_t)token * DFF + fbase) = o;
;     } else if (EPI == EPI_PP) {
;       uint2 o; o.x = pack2bf(v0, v1); o.y = pack2bf(v2, v3);
;       *(uint2*)(g.outb + (size_t)token * D_ + fbase) = o;
;     } else if (EPI == EPI_PLE) {
;       const size_t idx = (size_t)token * D_ + fbase;
;       const float r = rs[q];
;       float4 hv = *(const float4*)(g.h + idx);
.LBB0_461:
	s_andn2_b64 vcc, exec, s[12:13]
	v_mov_b32_e32 v143, 0
	s_cbranch_vccnz .LBB0_463
.LBB0_463:
	v_or_b32_e32 v126, 16, v140
	v_cmp_gt_i32_e64 s[12:13], s95, v148
	s_cmp_lt_i32 s55, 3
	s_mov_b64 s[20:21], -1
	s_cbranch_scc1 .LBB0_469
	s_cmp_gt_i32 s55, 3
	s_cbranch_scc0 .LBB0_466
.LBB0_466:
	s_andn2_b64 vcc, exec, s[20:21]
	s_cbranch_vccnz .LBB0_468
	v_ashrrev_i32_e32 v127, 31, v126
	v_lshlrev_b64 v[152:153], 12, v[126:127]
	v_lshl_add_u64 v[152:153], s[58:59], 0, v[152:153]
	v_cvt_pk_bf16_f32 v128, v122, v123
	v_cvt_pk_bf16_f32 v129, v124, v125
	v_lshl_add_u64 v[152:153], v[148:149], 1, v[152:153]
	v_mov_b32_e32 v158, 0
	global_store_dwordx2 v[152:153], v[128:129], off

; __device__ __forceinline__ void epi_block(const int EPI, const GemmArgs& g, f32x4 a00, f32x4 a01, f32x4 a10, f32x4 a11,
;                                           const int fbase, const int tok0, const float (&rs)[4], float (&sq)[4]) {
; #pragma unroll
;   for (int q = 0; q < 4; ++q) {
;     const f32x4 av = q == 0 ? a00 : q == 1 ? a01 : q == 2 ? a10 : a11;
;     const int token = tok0 + (q >> 1) * HALF + (q & 1) * 16;
;     float v0 = av[0], v1 = av[1], v2 = av[2], v3 = av[3];
;     if (EPI == EPI_IN) {
;       if (fbase < DIN) {
;         const float r = rs[q];
;         v0 *= r; v1 *= r; v2 *= r; v3 *= r;
;         uint2 o; o.x = pack2bf(v0, v1); o.y = pack2bf(v2, v3);
;         *(uint2*)(g.outb + (size_t)token * DIN + fbase) = o;
;         if (fbase < NSH && (token & 31) == 31) *(uint2*)(g.bnd + (size_t)(token >> 5) * NSH + fbase) = o;
;         if (fbase >= DIN - 16) {
;           const int hh = fbase - (DIN - 16);
;           const int bb = token >> 14, ss = token & (S_ - 1);
;           float vv[4] = {v0, v1, v2, v3};
; #pragma unroll
;           for (int j = 0; j < 4; ++j) {
;             float xx = vv[j] + g.b_f[hh + j];
;             g.lf[((size_t)(bb * 16 + hh + j) << 14) + ss] = fminf(xx, 0.f) - log1pf(__expf(-fabsf(xx)));
;           }
;         }
;       }
;     } else if (EPI == EPI_RES) {
;       const size_t idx = (size_t)token * D_ + fbase;
;       float4 hv = *(const float4*)(g.h + idx);
;       hv.x += v0; hv.y += v1; hv.z += v2; hv.w += v3;
;       *(float4*)(g.h + idx) = hv;
;       uint2 o; o.x = pack2bf(hv.x, hv.y); o.y = pack2bf(hv.z, hv.w);
;       *(uint2*)(g.outb + idx) = o;
;       sq[q] += (hv.x * hv.x + hv.y * hv.y) + (hv.z * hv.z + hv.w * hv.w);
;     } else if (EPI == EPI_FF1) {
;       const float r = rs[q];
;       v0 = fmaxf(v0 * r, 0.f); v1 = fmaxf(v1 * r, 0.f); v2 = fmaxf(v2 * r, 0.f); v3 = fmaxf(v3 * r, 0.f);
;       uint2 o; o.x = pack2bf(v0 * v0, v1 * v1); o.y = pack2bf(v2 * v2, v3 * v3);
;       *(uint2*)(g.outb + (size_t)token * DFF + fbase) = o;
;     } else if (EPI == EPI_PP) {
;       uint2 o; o.x = pack2bf(v0, v1); o.y = pack2bf(v2, v3);
;       *(uint2*)(g.outb + (size_t)token * D_ + fbase) = o;
;     } else if (EPI == EPI_PLE) {
;       const size_t idx = (size_t)token * D_ + fbase;
;       const float r = rs[q];
;       float4 hv = *(const float4*)(g.h + idx);
.LBB0_480:
	s_andn2_b64 vcc, exec, s[20:21]
	v_mov_b32_e32 v158, 0
	s_cbranch_vccnz .LBB0_482
.LBB0_482:
	v_or_b32_e32 v122, 0x80, v140
	s_cmp_lt_i32 s55, 3
	s_mov_b64 s[20:21], -1
	s_cbranch_scc1 .LBB0_488
	s_cmp_gt_i32 s55, 3
	s_cbranch_scc0 .LBB0_485
.LBB0_485:
	s_andn2_b64 vcc, exec, s[20:21]
	s_cbranch_vccnz .LBB0_487
	v_ashrrev_i32_e32 v123, 31, v122
	v_lshlrev_b64 v[128:129], 12, v[122:123]
	v_lshl_add_u64 v[128:129], s[58:59], 0, v[128:129]
	v_cvt_pk_bf16_f32 v124, v118, v119
	v_cvt_pk_bf16_f32 v125, v120, v121
	v_lshl_add_u64 v[128:129], v[148:149], 1, v[128:129]
	v_mov_b32_e32 v154, 0
	global_store_dwordx2 v[128:129], v[124:125], off

; __device__ __forceinline__ void epi_block(const int EPI, const GemmArgs& g, f32x4 a00, f32x4 a01, f32x4 a10, f32x4 a11,
;                                           const int fbase, const int tok0, const float (&rs)[4], float (&sq)[4]) {
; #pragma unroll
;   for (int q = 0; q < 4; ++q) {
;     const f32x4 av = q == 0 ? a00 : q == 1 ? a01 : q == 2 ? a10 : a11;
;     const int token = tok0 + (q >> 1) * HALF + (q & 1) * 16;
;     float v0 = av[0], v1 = av[1], v2 = av[2], v3 = av[3];
;     if (EPI == EPI_IN) {
;       if (fbase < DIN) {
;         const float r = rs[q];
;         v0 *= r; v1 *= r; v2 *= r; v3 *= r;
;         uint2 o; o.x = pack2bf(v0, v1); o.y = pack2bf(v2, v3);
;         *(uint2*)(g.outb + (size_t)token * DIN + fbase) = o;
;         if (fbase < NSH && (token & 31) == 31) *(uint2*)(g.bnd + (size_t)(token >> 5) * NSH + fbase) = o;
;         if (fbase >= DIN - 16) {
;           const int hh = fbase - (DIN - 16);
;           const int bb = token >> 14, ss = token & (S_ - 1);
;           float vv[4] = {v0, v1, v2, v3};
; #pragma unroll
;           for (int j = 0; j < 4; ++j) {
;             float xx = vv[j] + g.b_f[hh + j];
;             g.lf[((size_t)(bb * 16 + hh + j) << 14) + ss] = fminf(xx, 0.f) - log1pf(__expf(-fabsf(xx)));
;           }
;         }
;       }
;     } else if (EPI == EPI_RES) {
;       const size_t idx = (size_t)token * D_ + fbase;
;       float4 hv = *(const float4*)(g.h + idx);
;       hv.x += v0; hv.y += v1; hv.z += v2; hv.w += v3;
;       *(float4*)(g.h + idx) = hv;
;       uint2 o; o.x = pack2bf(hv.x, hv.y); o.y = pack2bf(hv.z, hv.w);
;       *(uint2*)(g.outb + idx) = o;
;       sq[q] += (hv.x * hv.x + hv.y * hv.y) + (hv.z * hv.z + hv.w * hv.w);
;     } else if (EPI == EPI_FF1) {
;       const float r = rs[q];
;       v0 = fmaxf(v0 * r, 0.f); v1 = fmaxf(v1 * r, 0.f); v2 = fmaxf(v2 * r, 0.f); v3 = fmaxf(v3 * r, 0.f);
;       uint2 o; o.x = pack2bf(v0 * v0, v1 * v1); o.y = pack2bf(v2 * v2, v3 * v3);
;       *(uint2*)(g.outb + (size_t)token * DFF + fbase) = o;
;     } else if (EPI == EPI_PP) {
;       uint2 o; o.x = pack2bf(v0, v1); o.y = pack2bf(v2, v3);
;       *(uint2*)(g.outb + (size_t)token * D_ + fbase) = o;
;     } else if (EPI == EPI_PLE) {
;       const size_t idx = (size_t)token * D_ + fbase;
;       const float r = rs[q];
;       float4 hv = *(const float4*)(g.h + idx);
.LBB0_497:
	s_andn2_b64 vcc, exec, s[20:21]
	v_mov_b32_e32 v154, 0
	s_cbranch_vccnz .LBB0_499
.LBB0_499:
	v_or_b32_e32 v118, 0x90, v140
	s_cmp_lt_i32 s55, 3
	s_mov_b64 s[20:21], -1
	s_cbranch_scc1 .LBB0_505
	s_cmp_gt_i32 s55, 3
	s_cbranch_scc0 .LBB0_502
.LBB0_502:
	s_andn2_b64 vcc, exec, s[20:21]
	s_cbranch_vccnz .LBB0_504
	v_ashrrev_i32_e32 v119, 31, v118
	v_lshlrev_b64 v[124:125], 12, v[118:119]
	v_lshl_add_u64 v[124:125], s[58:59], 0, v[124:125]
	v_cvt_pk_bf16_f32 v120, v114, v115
	v_cvt_pk_bf16_f32 v121, v116, v117
	v_lshl_add_u64 v[124:125], v[148:149], 1, v[124:125]
	v_mov_b32_e32 v152, 0
	global_store_dwordx2 v[124:125], v[120:121], off

; __device__ __forceinline__ void epi_block(const int EPI, const GemmArgs& g, f32x4 a00, f32x4 a01, f32x4 a10, f32x4 a11,
;                                           const int fbase, const int tok0, const float (&rs)[4], float (&sq)[4]) {
; #pragma unroll
;   for (int q = 0; q < 4; ++q) {
;     const f32x4 av = q == 0 ? a00 : q == 1 ? a01 : q == 2 ? a10 : a11;
;     const int token = tok0 + (q >> 1) * HALF + (q & 1) * 16;
;     float v0 = av[0], v1 = av[1], v2 = av[2], v3 = av[3];
;     if (EPI == EPI_IN) {
;       if (fbase < DIN) {
;         const float r = rs[q];
;         v0 *= r; v1 *= r; v2 *= r; v3 *= r;
;         uint2 o; o.x = pack2bf(v0, v1); o.y = pack2bf(v2, v3);
;         *(uint2*)(g.outb + (size_t)token * DIN + fbase) = o;
;         if (fbase < NSH && (token & 31) == 31) *(uint2*)(g.bnd + (size_t)(token >> 5) * NSH + fbase) = o;
;         if (fbase >= DIN - 16) {
;           const int hh = fbase - (DIN - 16);
;           const int bb = token >> 14, ss = token & (S_ - 1);
;           float vv[4] = {v0, v1, v2, v3};
; #pragma unroll
;           for (int j = 0; j < 4; ++j) {
;             float xx = vv[j] + g.b_f[hh + j];
;             g.lf[((size_t)(bb * 16 + hh + j) << 14) + ss] = fminf(xx, 0.f) - log1pf(__expf(-fabsf(xx)));
;           }
;         }
;       }
;     } else if (EPI == EPI_RES) {
;       const size_t idx = (size_t)token * D_ + fbase;
;       float4 hv = *(const float4*)(g.h + idx);
;       hv.x += v0; hv.y += v1; hv.z += v2; hv.w += v3;
;       *(float4*)(g.h + idx) = hv;
;       uint2 o; o.x = pack2bf(hv.x, hv.y); o.y = pack2bf(hv.z, hv.w);
;       *(uint2*)(g.outb + idx) = o;
;       sq[q] += (hv.x * hv.x + hv.y * hv.y) + (hv.z * hv.z + hv.w * hv.w);
;     } else if (EPI == EPI_FF1) {
;       const float r = rs[q];
;       v0 = fmaxf(v0 * r, 0.f); v1 = fmaxf(v1 * r, 0.f); v2 = fmaxf(v2 * r, 0.f); v3 = fmaxf(v3 * r, 0.f);
;       uint2 o; o.x = pack2bf(v0 * v0, v1 * v1); o.y = pack2bf(v2 * v2, v3 * v3);
;       *(uint2*)(g.outb + (size_t)token * DFF + fbase) = o;
;     } else if (EPI == EPI_PP) {
;       uint2 o; o.x = pack2bf(v0, v1); o.y = pack2bf(v2, v3);
;       *(uint2*)(g.outb + (size_t)token * D_ + fbase) = o;
;     } else if (EPI == EPI_PLE) {
;       const size_t idx = (size_t)token * D_ + fbase;
;       const float r = rs[q];
;       float4 hv = *(const float4*)(g.h + idx);
.LBB0_516:
	s_andn2_b64 vcc, exec, s[20:21]
	v_mov_b32_e32 v152, 0
	s_cbranch_vccnz .LBB0_518
.LBB0_518:
	v_or_b32_e32 v119, 16, v148
	v_cmp_gt_i32_e64 s[10:11], s77, v119
	v_cmp_lt_i32_e64 s[8:9], s60, v119
	s_cmp_lt_i32 s55, 3
	s_mov_b64 s[12:13], -1
	s_cbranch_scc1 .LBB0_542
	s_cmp_gt_i32 s55, 3
	s_cbranch_scc0 .LBB0_521
.LBB0_521:
	s_andn2_b64 vcc, exec, s[12:13]
	s_cbranch_vccnz .LBB0_523
	v_lshlrev_b64 v[116:117], 12, v[140:141]
	v_lshl_add_u64 v[116:117], s[58:59], 0, v[116:117]
	v_cvt_pk_bf16_f32 v114, v110, v111
	v_cvt_pk_bf16_f32 v115, v112, v113
	v_lshl_add_u64 v[116:117], v[148:149], 1, v[116:117]
	v_mov_b32_e32 v128, v143
	global_store_dwordx2 v[116:117], v[114:115], off offset:32

; __device__ __forceinline__ void epi_block(const int EPI, const GemmArgs& g, f32x4 a00, f32x4 a01, f32x4 a10, f32x4 a11,
;                                           const int fbase, const int tok0, const float (&rs)[4], float (&sq)[4]) {
; #pragma unroll
;   for (int q = 0; q < 4; ++q) {
;     const f32x4 av = q == 0 ? a00 : q == 1 ? a01 : q == 2 ? a10 : a11;
;     const int token = tok0 + (q >> 1) * HALF + (q & 1) * 16;
;     float v0 = av[0], v1 = av[1], v2 = av[2], v3 = av[3];
;     if (EPI == EPI_IN) {
;       if (fbase < DIN) {
;         const float r = rs[q];
;         v0 *= r; v1 *= r; v2 *= r; v3 *= r;
;         uint2 o; o.x = pack2bf(v0, v1); o.y = pack2bf(v2, v3);
;         *(uint2*)(g.outb + (size_t)token * DIN + fbase) = o;
;         if (fbase < NSH && (token & 31) == 31) *(uint2*)(g.bnd + (size_t)(token >> 5) * NSH + fbase) = o;
;         if (fbase >= DIN - 16) {
;           const int hh = fbase - (DIN - 16);
;           const int bb = token >> 14, ss = token & (S_ - 1);
;           float vv[4] = {v0, v1, v2, v3};
; #pragma unroll
;           for (int j = 0; j < 4; ++j) {
;             float xx = vv[j] + g.b_f[hh + j];
;             g.lf[((size_t)(bb * 16 + hh + j) << 14) + ss] = fminf(xx, 0.f) - log1pf(__expf(-fabsf(xx)));
;           }
;         }
;       }
;     } else if (EPI == EPI_RES) {
;       const size_t idx = (size_t)token * D_ + fbase;
;       float4 hv = *(const float4*)(g.h + idx);
;       hv.x += v0; hv.y += v1; hv.z += v2; hv.w += v3;
;       *(float4*)(g.h + idx) = hv;
;       uint2 o; o.x = pack2bf(hv.x, hv.y); o.y = pack2bf(hv.z, hv.w);
;       *(uint2*)(g.outb + idx) = o;
;       sq[q] += (hv.x * hv.x + hv.y * hv.y) + (hv.z * hv.z + hv.w * hv.w);
;     } else if (EPI == EPI_FF1) {
;       const float r = rs[q];
;       v0 = fmaxf(v0 * r, 0.f); v1 = fmaxf(v1 * r, 0.f); v2 = fmaxf(v2 * r, 0.f); v3 = fmaxf(v3 * r, 0.f);
;       uint2 o; o.x = pack2bf(v0 * v0, v1 * v1); o.y = pack2bf(v2 * v2, v3 * v3);
;       *(uint2*)(g.outb + (size_t)token * DFF + fbase) = o;
;     } else if (EPI == EPI_PP) {
;       uint2 o; o.x = pack2bf(v0, v1); o.y = pack2bf(v2, v3);
;       *(uint2*)(g.outb + (size_t)token * D_ + fbase) = o;
;     } else if (EPI == EPI_PLE) {
;       const size_t idx = (size_t)token * D_ + fbase;
;       const float r = rs[q];
;       float4 hv = *(const float4*)(g.h + idx);
.LBB0_525:
	s_cmp_gt_i32 s55, 3
	s_cbranch_scc0 .LBB0_527
.LBB0_527:
	s_andn2_b64 vcc, exec, s[20:21]
	s_cbranch_vccnz .LBB0_529
	v_ashrrev_i32_e32 v127, 31, v126
	v_lshlrev_b64 v[112:113], 12, v[126:127]
	v_lshl_add_u64 v[112:113], s[58:59], 0, v[112:113]
	v_cvt_pk_bf16_f32 v110, v106, v107
	v_cvt_pk_bf16_f32 v111, v108, v109
	v_lshl_add_u64 v[112:113], v[148:149], 1, v[112:113]
	v_mov_b32_e32 v120, v158
	global_store_dwordx2 v[112:113], v[110:111], off offset:32

; __device__ __forceinline__ void epi_block(const int EPI, const GemmArgs& g, f32x4 a00, f32x4 a01, f32x4 a10, f32x4 a11,
;                                           const int fbase, const int tok0, const float (&rs)[4], float (&sq)[4]) {
; #pragma unroll
;   for (int q = 0; q < 4; ++q) {
;     const f32x4 av = q == 0 ? a00 : q == 1 ? a01 : q == 2 ? a10 : a11;
;     const int token = tok0 + (q >> 1) * HALF + (q & 1) * 16;
;     float v0 = av[0], v1 = av[1], v2 = av[2], v3 = av[3];
;     if (EPI == EPI_IN) {
;       if (fbase < DIN) {
;         const float r = rs[q];
;         v0 *= r; v1 *= r; v2 *= r; v3 *= r;
;         uint2 o; o.x = pack2bf(v0, v1); o.y = pack2bf(v2, v3);
;         *(uint2*)(g.outb + (size_t)token * DIN + fbase) = o;
;         if (fbase < NSH && (token & 31) == 31) *(uint2*)(g.bnd + (size_t)(token >> 5) * NSH + fbase) = o;
;         if (fbase >= DIN - 16) {
;           const int hh = fbase - (DIN - 16);
;           const int bb = token >> 14, ss = token & (S_ - 1);
;           float vv[4] = {v0, v1, v2, v3};
; #pragma unroll
;           for (int j = 0; j < 4; ++j) {
;             float xx = vv[j] + g.b_f[hh + j];
;             g.lf[((size_t)(bb * 16 + hh + j) << 14) + ss] = fminf(xx, 0.f) - log1pf(__expf(-fabsf(xx)));
;           }
;         }
;       }
;     } else if (EPI == EPI_RES) {
;       const size_t idx = (size_t)token * D_ + fbase;
;       float4 hv = *(const float4*)(g.h + idx);
;       hv.x += v0; hv.y += v1; hv.z += v2; hv.w += v3;
;       *(float4*)(g.h + idx) = hv;
;       uint2 o; o.x = pack2bf(hv.x, hv.y); o.y = pack2bf(hv.z, hv.w);
;       *(uint2*)(g.outb + idx) = o;
;       sq[q] += (hv.x * hv.x + hv.y * hv.y) + (hv.z * hv.z + hv.w * hv.w);
;     } else if (EPI == EPI_FF1) {
;       const float r = rs[q];
;       v0 = fmaxf(v0 * r, 0.f); v1 = fmaxf(v1 * r, 0.f); v2 = fmaxf(v2 * r, 0.f); v3 = fmaxf(v3 * r, 0.f);
;       uint2 o; o.x = pack2bf(v0 * v0, v1 * v1); o.y = pack2bf(v2 * v2, v3 * v3);
;       *(uint2*)(g.outb + (size_t)token * DFF + fbase) = o;
;     } else if (EPI == EPI_PP) {
;       uint2 o; o.x = pack2bf(v0, v1); o.y = pack2bf(v2, v3);
;       *(uint2*)(g.outb + (size_t)token * D_ + fbase) = o;
;     } else if (EPI == EPI_PLE) {
;       const size_t idx = (size_t)token * D_ + fbase;
;       const float r = rs[q];
;       float4 hv = *(const float4*)(g.h + idx);
.LBB0_531:
	s_cmp_gt_i32 s55, 3
	s_cbranch_scc0 .LBB0_533
.LBB0_533:
	s_andn2_b64 vcc, exec, s[20:21]
	s_cbranch_vccnz .LBB0_535
	v_ashrrev_i32_e32 v123, 31, v122
	v_lshlrev_b64 v[108:109], 12, v[122:123]
	v_lshl_add_u64 v[108:109], s[58:59], 0, v[108:109]
	v_cvt_pk_bf16_f32 v106, v102, v103
	v_cvt_pk_bf16_f32 v107, v104, v105
	v_lshl_add_u64 v[108:109], v[148:149], 1, v[108:109]
	v_mov_b32_e32 v112, v154
	global_store_dwordx2 v[108:109], v[106:107], off offset:32

; __device__ __forceinline__ void epi_block(const int EPI, const GemmArgs& g, f32x4 a00, f32x4 a01, f32x4 a10, f32x4 a11,
;                                           const int fbase, const int tok0, const float (&rs)[4], float (&sq)[4]) {
; #pragma unroll
;   for (int q = 0; q < 4; ++q) {
;     const f32x4 av = q == 0 ? a00 : q == 1 ? a01 : q == 2 ? a10 : a11;
;     const int token = tok0 + (q >> 1) * HALF + (q & 1) * 16;
;     float v0 = av[0], v1 = av[1], v2 = av[2], v3 = av[3];
;     if (EPI == EPI_IN) {
;       if (fbase < DIN) {
;         const float r = rs[q];
;         v0 *= r; v1 *= r; v2 *= r; v3 *= r;
;         uint2 o; o.x = pack2bf(v0, v1); o.y = pack2bf(v2, v3);
;         *(uint2*)(g.outb + (size_t)token * DIN + fbase) = o;
;         if (fbase < NSH && (token & 31) == 31) *(uint2*)(g.bnd + (size_t)(token >> 5) * NSH + fbase) = o;
;         if (fbase >= DIN - 16) {
;           const int hh = fbase - (DIN - 16);
;           const int bb = token >> 14, ss = token & (S_ - 1);
;           float vv[4] = {v0, v1, v2, v3};
; #pragma unroll
;           for (int j = 0; j < 4; ++j) {
;             float xx = vv[j] + g.b_f[hh + j];
;             g.lf[((size_t)(bb * 16 + hh + j) << 14) + ss] = fminf(xx, 0.f) - log1pf(__expf(-fabsf(xx)));
;           }
;         }
;       }
;     } else if (EPI == EPI_RES) {
;       const size_t idx = (size_t)token * D_ + fbase;
;       float4 hv = *(const float4*)(g.h + idx);
;       hv.x += v0; hv.y += v1; hv.z += v2; hv.w += v3;
;       *(float4*)(g.h + idx) = hv;
;       uint2 o; o.x = pack2bf(hv.x, hv.y); o.y = pack2bf(hv.z, hv.w);
;       *(uint2*)(g.outb + idx) = o;
;       sq[q] += (hv.x * hv.x + hv.y * hv.y) + (hv.z * hv.z + hv.w * hv.w);
;     } else if (EPI == EPI_FF1) {
;       const float r = rs[q];
;       v0 = fmaxf(v0 * r, 0.f); v1 = fmaxf(v1 * r, 0.f); v2 = fmaxf(v2 * r, 0.f); v3 = fmaxf(v3 * r, 0.f);
;       uint2 o; o.x = pack2bf(v0 * v0, v1 * v1); o.y = pack2bf(v2 * v2, v3 * v3);
;       *(uint2*)(g.outb + (size_t)token * DFF + fbase) = o;
;     } else if (EPI == EPI_PP) {
;       uint2 o; o.x = pack2bf(v0, v1); o.y = pack2bf(v2, v3);
;       *(uint2*)(g.outb + (size_t)token * D_ + fbase) = o;
;     } else if (EPI == EPI_PLE) {
;       const size_t idx = (size_t)token * D_ + fbase;
;       const float r = rs[q];
;       float4 hv = *(const float4*)(g.h + idx);
.LBB0_537:
	s_cmp_gt_i32 s55, 3
	s_cbranch_scc0 .LBB0_539
.LBB0_539:
	s_andn2_b64 vcc, exec, s[20:21]
	s_cbranch_vccnz .LBB0_541
	v_ashrrev_i32_e32 v119, 31, v118
	v_lshlrev_b64 v[104:105], 12, v[118:119]
	v_lshl_add_u64 v[104:105], s[58:59], 0, v[104:105]
	v_cvt_pk_bf16_f32 v102, v98, v99
	v_cvt_pk_bf16_f32 v103, v100, v101
	v_lshl_add_u64 v[104:105], v[148:149], 1, v[104:105]
	v_mov_b32_e32 v110, v152
	global_store_dwordx2 v[104:105], v[102:103], off offset:32

; __device__ __forceinline__ void epi_block(const int EPI, const GemmArgs& g, f32x4 a00, f32x4 a01, f32x4 a10, f32x4 a11,
;                                           const int fbase, const int tok0, const float (&rs)[4], float (&sq)[4]) {
; #pragma unroll
;   for (int q = 0; q < 4; ++q) {
;     const f32x4 av = q == 0 ? a00 : q == 1 ? a01 : q == 2 ? a10 : a11;
;     const int token = tok0 + (q >> 1) * HALF + (q & 1) * 16;
;     float v0 = av[0], v1 = av[1], v2 = av[2], v3 = av[3];
;     if (EPI == EPI_IN) {
;       if (fbase < DIN) {
;         const float r = rs[q];
;         v0 *= r; v1 *= r; v2 *= r; v3 *= r;
;         uint2 o; o.x = pack2bf(v0, v1); o.y = pack2bf(v2, v3);
;         *(uint2*)(g.outb + (size_t)token * DIN + fbase) = o;
;         if (fbase < NSH && (token & 31) == 31) *(uint2*)(g.bnd + (size_t)(token >> 5) * NSH + fbase) = o;
;         if (fbase >= DIN - 16) {
;           const int hh = fbase - (DIN - 16);
;           const int bb = token >> 14, ss = token & (S_ - 1);
;           float vv[4] = {v0, v1, v2, v3};
; #pragma unroll
;           for (int j = 0; j < 4; ++j) {
;             float xx = vv[j] + g.b_f[hh + j];
;             g.lf[((size_t)(bb * 16 + hh + j) << 14) + ss] = fminf(xx, 0.f) - log1pf(__expf(-fabsf(xx)));
;           }
;         }
;       }
;     } else if (EPI == EPI_RES) {
;       const size_t idx = (size_t)token * D_ + fbase;
;       float4 hv = *(const float4*)(g.h + idx);
;       hv.x += v0; hv.y += v1; hv.z += v2; hv.w += v3;
;       *(float4*)(g.h + idx) = hv;
;       uint2 o; o.x = pack2bf(hv.x, hv.y); o.y = pack2bf(hv.z, hv.w);
;       *(uint2*)(g.outb + idx) = o;
;       sq[q] += (hv.x * hv.x + hv.y * hv.y) + (hv.z * hv.z + hv.w * hv.w);
;     } else if (EPI == EPI_FF1) {
;       const float r = rs[q];
;       v0 = fmaxf(v0 * r, 0.f); v1 = fmaxf(v1 * r, 0.f); v2 = fmaxf(v2 * r, 0.f); v3 = fmaxf(v3 * r, 0.f);
;       uint2 o; o.x = pack2bf(v0 * v0, v1 * v1); o.y = pack2bf(v2 * v2, v3 * v3);
;       *(uint2*)(g.outb + (size_t)token * DFF + fbase) = o;
;     } else if (EPI == EPI_PP) {
;       uint2 o; o.x = pack2bf(v0, v1); o.y = pack2bf(v2, v3);
;       *(uint2*)(g.outb + (size_t)token * D_ + fbase) = o;
;     } else if (EPI == EPI_PLE) {
;       const size_t idx = (size_t)token * D_ + fbase;
;       const float r = rs[q];
;       float4 hv = *(const float4*)(g.h + idx);
.LBB0_551:
	s_andn2_b64 vcc, exec, s[12:13]
	s_cbranch_vccnz .LBB0_553
.LBB0_553:
	v_mov_b32_e32 v128, v143
	v_cmp_gt_i32_e64 s[12:13], s95, v119
	s_cmp_lt_i32 s55, 3
	s_mov_b64 s[20:21], -1
	s_cbranch_scc0 .LBB0_525

; __device__ __forceinline__ void epi_block(const int EPI, const GemmArgs& g, f32x4 a00, f32x4 a01, f32x4 a10, f32x4 a11,
;                                           const int fbase, const int tok0, const float (&rs)[4], float (&sq)[4]) {
; #pragma unroll
;   for (int q = 0; q < 4; ++q) {
;     const f32x4 av = q == 0 ? a00 : q == 1 ? a01 : q == 2 ? a10 : a11;
;     const int token = tok0 + (q >> 1) * HALF + (q & 1) * 16;
;     float v0 = av[0], v1 = av[1], v2 = av[2], v3 = av[3];
;     if (EPI == EPI_IN) {
;       if (fbase < DIN) {
;         const float r = rs[q];
;         v0 *= r; v1 *= r; v2 *= r; v3 *= r;
;         uint2 o; o.x = pack2bf(v0, v1); o.y = pack2bf(v2, v3);
;         *(uint2*)(g.outb + (size_t)token * DIN + fbase) = o;
;         if (fbase < NSH && (token & 31) == 31) *(uint2*)(g.bnd + (size_t)(token >> 5) * NSH + fbase) = o;
;         if (fbase >= DIN - 16) {
;           const int hh = fbase - (DIN - 16);
;           const int bb = token >> 14, ss = token & (S_ - 1);
;           float vv[4] = {v0, v1, v2, v3};
; #pragma unroll
;           for (int j = 0; j < 4; ++j) {
;             float xx = vv[j] + g.b_f[hh + j];
;             g.lf[((size_t)(bb * 16 + hh + j) << 14) + ss] = fminf(xx, 0.f) - log1pf(__expf(-fabsf(xx)));
;           }
;         }
;       }
;     } else if (EPI == EPI_RES) {
;       const size_t idx = (size_t)token * D_ + fbase;
;       float4 hv = *(const float4*)(g.h + idx);
;       hv.x += v0; hv.y += v1; hv.z += v2; hv.w += v3;
;       *(float4*)(g.h + idx) = hv;
;       uint2 o; o.x = pack2bf(hv.x, hv.y); o.y = pack2bf(hv.z, hv.w);
;       *(uint2*)(g.outb + idx) = o;
;       sq[q] += (hv.x * hv.x + hv.y * hv.y) + (hv.z * hv.z + hv.w * hv.w);
;     } else if (EPI == EPI_FF1) {
;       const float r = rs[q];
;       v0 = fmaxf(v0 * r, 0.f); v1 = fmaxf(v1 * r, 0.f); v2 = fmaxf(v2 * r, 0.f); v3 = fmaxf(v3 * r, 0.f);
;       uint2 o; o.x = pack2bf(v0 * v0, v1 * v1); o.y = pack2bf(v2 * v2, v3 * v3);
;       *(uint2*)(g.outb + (size_t)token * DFF + fbase) = o;
;     } else if (EPI == EPI_PP) {
;       uint2 o; o.x = pack2bf(v0, v1); o.y = pack2bf(v2, v3);
;       *(uint2*)(g.outb + (size_t)token * D_ + fbase) = o;
;     } else if (EPI == EPI_PLE) {
;       const size_t idx = (size_t)token * D_ + fbase;
;       const float r = rs[q];
;       float4 hv = *(const float4*)(g.h + idx);
.LBB0_565:
	s_andn2_b64 vcc, exec, s[20:21]
	s_cbranch_vccnz .LBB0_567
.LBB0_567:
	v_mov_b32_e32 v120, v158
	s_cmp_lt_i32 s55, 3
	s_mov_b64 s[20:21], -1
	s_cbranch_scc0 .LBB0_531

; __device__ __forceinline__ void epi_block(const int EPI, const GemmArgs& g, f32x4 a00, f32x4 a01, f32x4 a10, f32x4 a11,
;                                           const int fbase, const int tok0, const float (&rs)[4], float (&sq)[4]) {
;     ...
;     } else if (EPI == EPI_RES) {
;       const size_t idx = (size_t)token * D_ + fbase;
;       float4 hv = *(const float4*)(g.h + idx);
;       hv.x += v0; hv.y += v1; hv.z += v2; hv.w += v3;
;       *(float4*)(g.h + idx) = hv;
;       uint2 o; o.x = pack2bf(hv.x, hv.y); o.y = pack2bf(hv.z, hv.w);
;       *(uint2*)(g.outb + idx) = o;
;       sq[q] += (hv.x * hv.x + hv.y * hv.y) + (hv.z * hv.z + hv.w * hv.w);
.LBB0_577:
	s_andn2_b64 vcc, exec, s[20:21]
	s_cbranch_vccnz .LBB0_579
.LBB0_579:
	v_mov_b32_e32 v112, v154
	s_cmp_lt_i32 s55, 3
	s_mov_b64 s[20:21], -1
	s_cbranch_scc0 .LBB0_537

; #define BFLO_(u) __uint_as_float((u) << 16)
; #define BFHI_(u) __uint_as_float((u) & 0xffff0000u)
; __device__ __forceinline__ void epi_block(const int EPI, const GemmArgs& g, f32x4 a00, f32x4 a01, f32x4 a10, f32x4 a11,
;                                           const int fbase, const int tok0, const float (&rs)[4], float (&sq)[4]) {
;     ...
;     } else if (EPI == EPI_RES) {
;       const size_t idx = (size_t)token * D_ + fbase;
;       float4 hv = *(const float4*)(g.h + idx);
;       hv.x += v0; hv.y += v1; hv.z += v2; hv.w += v3;
;       *(float4*)(g.h + idx) = hv;
;       uint2 o; o.x = pack2bf(hv.x, hv.y); o.y = pack2bf(hv.z, hv.w);
;       *(uint2*)(g.outb + idx) = o;
;       sq[q] += (hv.x * hv.x + hv.y * hv.y) + (hv.z * hv.z + hv.w * hv.w);
;     } else if (EPI == EPI_FF1) {
;       const float r = rs[q];
;       v0 = fmaxf(v0 * r, 0.f); v1 = fmaxf(v1 * r, 0.f); v2 = fmaxf(v2 * r, 0.f); v3 = fmaxf(v3 * r, 0.f);
;       uint2 o; o.x = pack2bf(v0 * v0, v1 * v1); o.y = pack2bf(v2 * v2, v3 * v3);
;       *(uint2*)(g.outb + (size_t)token * DFF + fbase) = o;
;     } else if (EPI == EPI_PP) {
;       uint2 o; o.x = pack2bf(v0, v1); o.y = pack2bf(v2, v3);
;       *(uint2*)(g.outb + (size_t)token * D_ + fbase) = o;
;     } else if (EPI == EPI_PLE) {
;       const size_t idx = (size_t)token * D_ + fbase;
;       const float r = rs[q];
;       float4 hv = *(const float4*)(g.h + idx);
;       uint2 pp = *(const uint2*)(g.pp + idx);
;       const float rl = -r * 1.4426950408889634f;
;       hv.x += BFLO_(pp.x) * __builtin_amdgcn_rcpf(1.f + __builtin_amdgcn_exp2f(v0 * rl));
;       hv.y += BFHI_(pp.x) * __builtin_amdgcn_rcpf(1.f + __builtin_amdgcn_exp2f(v1 * rl));
;       hv.z += BFLO_(pp.y) * __builtin_amdgcn_rcpf(1.f + __builtin_amdgcn_exp2f(v2 * rl));
;       hv.w += BFHI_(pp.y) * __builtin_amdgcn_rcpf(1.f + __builtin_amdgcn_exp2f(v3 * rl));
;       *(float4*)(g.h + idx) = hv;
;       uint2 o; o.x = pack2bf(hv.x, hv.y); o.y = pack2bf(hv.z, hv.w);
;       *(uint2*)(g.outb + idx) = o;
;       sq[q] += (hv.x * hv.x + hv.y * hv.y) + (hv.z * hv.z + hv.w * hv.w);
.LBB0_591:
	s_andn2_b64 vcc, exec, s[20:21]
	s_cbranch_vccnz .LBB0_593
.LBB0_593:
	v_mov_b32_e32 v110, v152
.LBB0_594:
	v_or_b32_e32 v111, 32, v148
	v_cmp_gt_i32_e64 s[10:11], s77, v111
	v_cmp_lt_i32_e64 s[8:9], s60, v111
	s_cmp_lt_i32 s55, 3
	s_mov_b64 s[12:13], -1
	s_cbranch_scc1 .LBB0_618
	s_cmp_gt_i32 s55, 3
	s_cbranch_scc0 .LBB0_597
.LBB0_597:
	s_andn2_b64 vcc, exec, s[12:13]
	s_cbranch_vccnz .LBB0_599
	v_lshlrev_b64 v[100:101], 12, v[140:141]
	v_lshl_add_u64 v[100:101], s[58:59], 0, v[100:101]
	v_cvt_pk_bf16_f32 v98, v94, v95
	v_cvt_pk_bf16_f32 v99, v96, v97
	v_lshl_add_u64 v[100:101], v[148:149], 1, v[100:101]
	v_mov_b32_e32 v106, v128
	global_store_dwordx2 v[100:101], v[98:99], off offset:64

; #define BFLO_(u) __uint_as_float((u) << 16)
; #define BFHI_(u) __uint_as_float((u) & 0xffff0000u)
; __device__ __forceinline__ void epi_block(const int EPI, const GemmArgs& g, f32x4 a00, f32x4 a01, f32x4 a10, f32x4 a11,
;                                           const int fbase, const int tok0, const float (&rs)[4], float (&sq)[4]) {
;     ...
;     } else if (EPI == EPI_PP) {
;       uint2 o; o.x = pack2bf(v0, v1); o.y = pack2bf(v2, v3);
;       *(uint2*)(g.outb + (size_t)token * D_ + fbase) = o;
;     } else if (EPI == EPI_PLE) {
;       const size_t idx = (size_t)token * D_ + fbase;
;       const float r = rs[q];
;       float4 hv = *(const float4*)(g.h + idx);
;       uint2 pp = *(const uint2*)(g.pp + idx);
;       const float rl = -r * 1.4426950408889634f;
;       hv.x += BFLO_(pp.x) * __builtin_amdgcn_rcpf(1.f + __builtin_amdgcn_exp2f(v0 * rl));
;       hv.y += BFHI_(pp.x) * __builtin_amdgcn_rcpf(1.f + __builtin_amdgcn_exp2f(v1 * rl));
;       hv.z += BFLO_(pp.y) * __builtin_amdgcn_rcpf(1.f + __builtin_amdgcn_exp2f(v2 * rl));
;       hv.w += BFHI_(pp.y) * __builtin_amdgcn_rcpf(1.f + __builtin_amdgcn_exp2f(v3 * rl));
;       *(float4*)(g.h + idx) = hv;
;       uint2 o; o.x = pack2bf(hv.x, hv.y); o.y = pack2bf(hv.z, hv.w);
;       *(uint2*)(g.outb + idx) = o;
;       sq[q] += (hv.x * hv.x + hv.y * hv.y) + (hv.z * hv.z + hv.w * hv.w);
.LBB0_601:
	s_cmp_gt_i32 s55, 3
	s_cbranch_scc0 .LBB0_603
.LBB0_603:
	s_andn2_b64 vcc, exec, s[20:21]
	s_cbranch_vccnz .LBB0_605
	v_ashrrev_i32_e32 v127, 31, v126
	v_lshlrev_b64 v[96:97], 12, v[126:127]
	v_lshl_add_u64 v[96:97], s[58:59], 0, v[96:97]
	v_cvt_pk_bf16_f32 v94, v90, v91
	v_cvt_pk_bf16_f32 v95, v92, v93
	v_lshl_add_u64 v[96:97], v[148:149], 1, v[96:97]
	v_mov_b32_e32 v102, v120
	global_store_dwordx2 v[96:97], v[94:95], off offset:64

; #define BFLO_(u) __uint_as_float((u) << 16)
; #define BFHI_(u) __uint_as_float((u) & 0xffff0000u)
; __device__ __forceinline__ void epi_block(const int EPI, const GemmArgs& g, f32x4 a00, f32x4 a01, f32x4 a10, f32x4 a11,
;                                           const int fbase, const int tok0, const float (&rs)[4], float (&sq)[4]) {
;     ...
;     } else if (EPI == EPI_PP) {
;       uint2 o; o.x = pack2bf(v0, v1); o.y = pack2bf(v2, v3);
;       *(uint2*)(g.outb + (size_t)token * D_ + fbase) = o;
;     } else if (EPI == EPI_PLE) {
;       const size_t idx = (size_t)token * D_ + fbase;
;       const float r = rs[q];
;       float4 hv = *(const float4*)(g.h + idx);
;       uint2 pp = *(const uint2*)(g.pp + idx);
;       const float rl = -r * 1.4426950408889634f;
;       hv.x += BFLO_(pp.x) * __builtin_amdgcn_rcpf(1.f + __builtin_amdgcn_exp2f(v0 * rl));
;       hv.y += BFHI_(pp.x) * __builtin_amdgcn_rcpf(1.f + __builtin_amdgcn_exp2f(v1 * rl));
;       hv.z += BFLO_(pp.y) * __builtin_amdgcn_rcpf(1.f + __builtin_amdgcn_exp2f(v2 * rl));
;       hv.w += BFHI_(pp.y) * __builtin_amdgcn_rcpf(1.f + __builtin_amdgcn_exp2f(v3 * rl));
;       *(float4*)(g.h + idx) = hv;
;       uint2 o; o.x = pack2bf(hv.x, hv.y); o.y = pack2bf(hv.z, hv.w);
;       *(uint2*)(g.outb + idx) = o;
;       sq[q] += (hv.x * hv.x + hv.y * hv.y) + (hv.z * hv.z + hv.w * hv.w);
.LBB0_607:
	s_cmp_gt_i32 s55, 3
	s_cbranch_scc0 .LBB0_609
.LBB0_609:
	s_andn2_b64 vcc, exec, s[20:21]
	s_cbranch_vccnz .LBB0_611
	v_ashrrev_i32_e32 v123, 31, v122
	v_lshlrev_b64 v[92:93], 12, v[122:123]
	v_lshl_add_u64 v[92:93], s[58:59], 0, v[92:93]
	v_cvt_pk_bf16_f32 v90, v86, v87
	v_cvt_pk_bf16_f32 v91, v88, v89
	v_lshl_add_u64 v[92:93], v[148:149], 1, v[92:93]
	v_mov_b32_e32 v96, v112
	global_store_dwordx2 v[92:93], v[90:91], off offset:64

; #define BFLO_(u) __uint_as_float((u) << 16)
; #define BFHI_(u) __uint_as_float((u) & 0xffff0000u)
; __device__ __forceinline__ void epi_block(const int EPI, const GemmArgs& g, f32x4 a00, f32x4 a01, f32x4 a10, f32x4 a11,
;                                           const int fbase, const int tok0, const float (&rs)[4], float (&sq)[4]) {
;     ...
;     } else if (EPI == EPI_PP) {
;       uint2 o; o.x = pack2bf(v0, v1); o.y = pack2bf(v2, v3);
;       *(uint2*)(g.outb + (size_t)token * D_ + fbase) = o;
;     } else if (EPI == EPI_PLE) {
;       const size_t idx = (size_t)token * D_ + fbase;
;       const float r = rs[q];
;       float4 hv = *(const float4*)(g.h + idx);
;       uint2 pp = *(const uint2*)(g.pp + idx);
;       const float rl = -r * 1.4426950408889634f;
;       hv.x += BFLO_(pp.x) * __builtin_amdgcn_rcpf(1.f + __builtin_amdgcn_exp2f(v0 * rl));
;       hv.y += BFHI_(pp.x) * __builtin_amdgcn_rcpf(1.f + __builtin_amdgcn_exp2f(v1 * rl));
;       hv.z += BFLO_(pp.y) * __builtin_amdgcn_rcpf(1.f + __builtin_amdgcn_exp2f(v2 * rl));
;       hv.w += BFHI_(pp.y) * __builtin_amdgcn_rcpf(1.f + __builtin_amdgcn_exp2f(v3 * rl));
;       *(float4*)(g.h + idx) = hv;
;       uint2 o; o.x = pack2bf(hv.x, hv.y); o.y = pack2bf(hv.z, hv.w);
;       *(uint2*)(g.outb + idx) = o;
;       sq[q] += (hv.x * hv.x + hv.y * hv.y) + (hv.z * hv.z + hv.w * hv.w);
.LBB0_613:
	s_cmp_gt_i32 s55, 3
	s_cbranch_scc0 .LBB0_615
.LBB0_615:
	s_andn2_b64 vcc, exec, s[20:21]
	s_cbranch_vccnz .LBB0_617
	v_ashrrev_i32_e32 v119, 31, v118
	v_lshlrev_b64 v[88:89], 12, v[118:119]
	v_lshl_add_u64 v[88:89], s[58:59], 0, v[88:89]
	v_cvt_pk_bf16_f32 v86, v82, v83
	v_cvt_pk_bf16_f32 v87, v84, v85
	v_lshl_add_u64 v[88:89], v[148:149], 1, v[88:89]
	v_mov_b32_e32 v94, v110
	global_store_dwordx2 v[88:89], v[86:87], off offset:64

; __device__ __forceinline__ void epi_block(const int EPI, const GemmArgs& g, f32x4 a00, f32x4 a01, f32x4 a10, f32x4 a11,
;                                           const int fbase, const int tok0, const float (&rs)[4], float (&sq)[4]) {
;     ...
;     } else if (EPI == EPI_RES) {
;       const size_t idx = (size_t)token * D_ + fbase;
;       float4 hv = *(const float4*)(g.h + idx);
;       hv.x += v0; hv.y += v1; hv.z += v2; hv.w += v3;
;       *(float4*)(g.h + idx) = hv;
;       uint2 o; o.x = pack2bf(hv.x, hv.y); o.y = pack2bf(hv.z, hv.w);
;       *(uint2*)(g.outb + idx) = o;
;       sq[q] += (hv.x * hv.x + hv.y * hv.y) + (hv.z * hv.z + hv.w * hv.w);
.LBB0_627:
	s_andn2_b64 vcc, exec, s[12:13]
	s_cbranch_vccnz .LBB0_629
.LBB0_629:
	v_mov_b32_e32 v106, v128
	v_cmp_gt_i32_e64 s[12:13], s95, v111
	s_cmp_lt_i32 s55, 3
	s_mov_b64 s[20:21], -1
	s_cbranch_scc0 .LBB0_601

; __device__ __forceinline__ void epi_block(const int EPI, const GemmArgs& g, f32x4 a00, f32x4 a01, f32x4 a10, f32x4 a11,
;                                           const int fbase, const int tok0, const float (&rs)[4], float (&sq)[4]) {
;     ...
;     } else if (EPI == EPI_RES) {
;       const size_t idx = (size_t)token * D_ + fbase;
;       float4 hv = *(const float4*)(g.h + idx);
;       hv.x += v0; hv.y += v1; hv.z += v2; hv.w += v3;
;       *(float4*)(g.h + idx) = hv;
;       uint2 o; o.x = pack2bf(hv.x, hv.y); o.y = pack2bf(hv.z, hv.w);
;       *(uint2*)(g.outb + idx) = o;
;       sq[q] += (hv.x * hv.x + hv.y * hv.y) + (hv.z * hv.z + hv.w * hv.w);
.LBB0_641:
	s_andn2_b64 vcc, exec, s[20:21]
	s_cbranch_vccnz .LBB0_643
.LBB0_643:
	v_mov_b32_e32 v102, v120
	s_cmp_lt_i32 s55, 3
	s_mov_b64 s[20:21], -1
	s_cbranch_scc0 .LBB0_607

; __device__ __forceinline__ void epi_block(const int EPI, const GemmArgs& g, f32x4 a00, f32x4 a01, f32x4 a10, f32x4 a11,
;                                           const int fbase, const int tok0, const float (&rs)[4], float (&sq)[4]) {
;     ...
;     } else if (EPI == EPI_RES) {
;       const size_t idx = (size_t)token * D_ + fbase;
;       float4 hv = *(const float4*)(g.h + idx);
;       hv.x += v0; hv.y += v1; hv.z += v2; hv.w += v3;
;       *(float4*)(g.h + idx) = hv;
;       uint2 o; o.x = pack2bf(hv.x, hv.y); o.y = pack2bf(hv.z, hv.w);
;       *(uint2*)(g.outb + idx) = o;
;       sq[q] += (hv.x * hv.x + hv.y * hv.y) + (hv.z * hv.z + hv.w * hv.w);
.LBB0_653:
	s_andn2_b64 vcc, exec, s[20:21]
	s_cbranch_vccnz .LBB0_655
.LBB0_655:
	v_mov_b32_e32 v96, v112
	s_cmp_lt_i32 s55, 3
	s_mov_b64 s[20:21], -1
	s_cbranch_scc0 .LBB0_613

; #define BFLO_(u) __uint_as_float((u) << 16)
; #define BFHI_(u) __uint_as_float((u) & 0xffff0000u)
; __device__ __forceinline__ void epi_block(const int EPI, const GemmArgs& g, f32x4 a00, f32x4 a01, f32x4 a10, f32x4 a11,
;                                           const int fbase, const int tok0, const float (&rs)[4], float (&sq)[4]) {
;     ...
;     } else if (EPI == EPI_RES) {
;       const size_t idx = (size_t)token * D_ + fbase;
;       float4 hv = *(const float4*)(g.h + idx);
;       hv.x += v0; hv.y += v1; hv.z += v2; hv.w += v3;
;       *(float4*)(g.h + idx) = hv;
;       uint2 o; o.x = pack2bf(hv.x, hv.y); o.y = pack2bf(hv.z, hv.w);
;       *(uint2*)(g.outb + idx) = o;
;       sq[q] += (hv.x * hv.x + hv.y * hv.y) + (hv.z * hv.z + hv.w * hv.w);
;     } else if (EPI == EPI_FF1) {
;       const float r = rs[q];
;       v0 = fmaxf(v0 * r, 0.f); v1 = fmaxf(v1 * r, 0.f); v2 = fmaxf(v2 * r, 0.f); v3 = fmaxf(v3 * r, 0.f);
;       uint2 o; o.x = pack2bf(v0 * v0, v1 * v1); o.y = pack2bf(v2 * v2, v3 * v3);
;       *(uint2*)(g.outb + (size_t)token * DFF + fbase) = o;
;     } else if (EPI == EPI_PP) {
;       uint2 o; o.x = pack2bf(v0, v1); o.y = pack2bf(v2, v3);
;       *(uint2*)(g.outb + (size_t)token * D_ + fbase) = o;
;     } else if (EPI == EPI_PLE) {
;       const size_t idx = (size_t)token * D_ + fbase;
;       const float r = rs[q];
;       float4 hv = *(const float4*)(g.h + idx);
;       uint2 pp = *(const uint2*)(g.pp + idx);
;       const float rl = -r * 1.4426950408889634f;
;       hv.x += BFLO_(pp.x) * __builtin_amdgcn_rcpf(1.f + __builtin_amdgcn_exp2f(v0 * rl));
;       hv.y += BFHI_(pp.x) * __builtin_amdgcn_rcpf(1.f + __builtin_amdgcn_exp2f(v1 * rl));
;       hv.z += BFLO_(pp.y) * __builtin_amdgcn_rcpf(1.f + __builtin_amdgcn_exp2f(v2 * rl));
;       hv.w += BFHI_(pp.y) * __builtin_amdgcn_rcpf(1.f + __builtin_amdgcn_exp2f(v3 * rl));
;       *(float4*)(g.h + idx) = hv;
;       uint2 o; o.x = pack2bf(hv.x, hv.y); o.y = pack2bf(hv.z, hv.w);
;       *(uint2*)(g.outb + idx) = o;
;       sq[q] += (hv.x * hv.x + hv.y * hv.y) + (hv.z * hv.z + hv.w * hv.w);
.LBB0_667:
	s_andn2_b64 vcc, exec, s[20:21]
	s_cbranch_vccnz .LBB0_669
.LBB0_669:
	v_mov_b32_e32 v94, v110
.LBB0_670:
	v_or_b32_e32 v95, 48, v148
	v_cmp_gt_i32_e64 s[10:11], s77, v95
	v_cmp_lt_i32_e64 s[8:9], s60, v95
	s_cmp_lt_i32 s55, 3
	s_mov_b64 s[12:13], -1
	s_cbranch_scc1 .LBB0_694
	s_cmp_gt_i32 s55, 3
	s_cbranch_scc0 .LBB0_673
.LBB0_673:
	s_andn2_b64 vcc, exec, s[12:13]
	s_cbranch_vccnz .LBB0_675
	v_lshlrev_b64 v[84:85], 12, v[140:141]
	v_lshl_add_u64 v[84:85], s[58:59], 0, v[84:85]
	v_cvt_pk_bf16_f32 v82, v78, v79
	v_cvt_pk_bf16_f32 v83, v80, v81
	v_lshl_add_u64 v[84:85], v[148:149], 1, v[84:85]
	v_mov_b32_e32 v90, v106
	global_store_dwordx2 v[84:85], v[82:83], off offset:96

; #define BFLO_(u) __uint_as_float((u) << 16)
; #define BFHI_(u) __uint_as_float((u) & 0xffff0000u)
; __device__ __forceinline__ void epi_block(const int EPI, const GemmArgs& g, f32x4 a00, f32x4 a01, f32x4 a10, f32x4 a11,
;                                           const int fbase, const int tok0, const float (&rs)[4], float (&sq)[4]) {
;     ...
;     } else if (EPI == EPI_PP) {
;       uint2 o; o.x = pack2bf(v0, v1); o.y = pack2bf(v2, v3);
;       *(uint2*)(g.outb + (size_t)token * D_ + fbase) = o;
;     } else if (EPI == EPI_PLE) {
;       const size_t idx = (size_t)token * D_ + fbase;
;       const float r = rs[q];
;       float4 hv = *(const float4*)(g.h + idx);
;       uint2 pp = *(const uint2*)(g.pp + idx);
;       const float rl = -r * 1.4426950408889634f;
;       hv.x += BFLO_(pp.x) * __builtin_amdgcn_rcpf(1.f + __builtin_amdgcn_exp2f(v0 * rl));
;       hv.y += BFHI_(pp.x) * __builtin_amdgcn_rcpf(1.f + __builtin_amdgcn_exp2f(v1 * rl));
;       hv.z += BFLO_(pp.y) * __builtin_amdgcn_rcpf(1.f + __builtin_amdgcn_exp2f(v2 * rl));
;       hv.w += BFHI_(pp.y) * __builtin_amdgcn_rcpf(1.f + __builtin_amdgcn_exp2f(v3 * rl));
;       *(float4*)(g.h + idx) = hv;
;       uint2 o; o.x = pack2bf(hv.x, hv.y); o.y = pack2bf(hv.z, hv.w);
;       *(uint2*)(g.outb + idx) = o;
;       sq[q] += (hv.x * hv.x + hv.y * hv.y) + (hv.z * hv.z + hv.w * hv.w);
.LBB0_677:
	s_cmp_gt_i32 s55, 3
	s_cbranch_scc0 .LBB0_679
.LBB0_679:
	s_andn2_b64 vcc, exec, s[20:21]
	s_cbranch_vccnz .LBB0_681
	v_ashrrev_i32_e32 v127, 31, v126
	v_lshlrev_b64 v[80:81], 12, v[126:127]
	v_lshl_add_u64 v[80:81], s[58:59], 0, v[80:81]
	v_cvt_pk_bf16_f32 v78, v74, v75
	v_cvt_pk_bf16_f32 v79, v76, v77
	v_lshl_add_u64 v[80:81], v[148:149], 1, v[80:81]
	v_mov_b32_e32 v86, v102
	global_store_dwordx2 v[80:81], v[78:79], off offset:96

; #define BFLO_(u) __uint_as_float((u) << 16)
; #define BFHI_(u) __uint_as_float((u) & 0xffff0000u)
; __device__ __forceinline__ void epi_block(const int EPI, const GemmArgs& g, f32x4 a00, f32x4 a01, f32x4 a10, f32x4 a11,
;                                           const int fbase, const int tok0, const float (&rs)[4], float (&sq)[4]) {
;     ...
;     } else if (EPI == EPI_PP) {
;       uint2 o; o.x = pack2bf(v0, v1); o.y = pack2bf(v2, v3);
;       *(uint2*)(g.outb + (size_t)token * D_ + fbase) = o;
;     } else if (EPI == EPI_PLE) {
;       const size_t idx = (size_t)token * D_ + fbase;
;       const float r = rs[q];
;       float4 hv = *(const float4*)(g.h + idx);
;       uint2 pp = *(const uint2*)(g.pp + idx);
;       const float rl = -r * 1.4426950408889634f;
;       hv.x += BFLO_(pp.x) * __builtin_amdgcn_rcpf(1.f + __builtin_amdgcn_exp2f(v0 * rl));
;       hv.y += BFHI_(pp.x) * __builtin_amdgcn_rcpf(1.f + __builtin_amdgcn_exp2f(v1 * rl));
;       hv.z += BFLO_(pp.y) * __builtin_amdgcn_rcpf(1.f + __builtin_amdgcn_exp2f(v2 * rl));
;       hv.w += BFHI_(pp.y) * __builtin_amdgcn_rcpf(1.f + __builtin_amdgcn_exp2f(v3 * rl));
;       *(float4*)(g.h + idx) = hv;
;       uint2 o; o.x = pack2bf(hv.x, hv.y); o.y = pack2bf(hv.z, hv.w);
;       *(uint2*)(g.outb + idx) = o;
;       sq[q] += (hv.x * hv.x + hv.y * hv.y) + (hv.z * hv.z + hv.w * hv.w);
.LBB0_683:
	s_cmp_gt_i32 s55, 3
	s_cbranch_scc0 .LBB0_685
.LBB0_685:
	s_andn2_b64 vcc, exec, s[20:21]
	s_cbranch_vccnz .LBB0_687
	v_ashrrev_i32_e32 v123, 31, v122
	v_lshlrev_b64 v[76:77], 12, v[122:123]
	v_lshl_add_u64 v[76:77], s[58:59], 0, v[76:77]
	v_cvt_pk_bf16_f32 v74, v70, v71
	v_cvt_pk_bf16_f32 v75, v72, v73
	v_lshl_add_u64 v[76:77], v[148:149], 1, v[76:77]
	v_mov_b32_e32 v81, v96
	global_store_dwordx2 v[76:77], v[74:75], off offset:96

; #define BFLO_(u) __uint_as_float((u) << 16)
; #define BFHI_(u) __uint_as_float((u) & 0xffff0000u)
; __device__ __forceinline__ void epi_block(const int EPI, const GemmArgs& g, f32x4 a00, f32x4 a01, f32x4 a10, f32x4 a11,
;                                           const int fbase, const int tok0, const float (&rs)[4], float (&sq)[4]) {
;     ...
;     } else if (EPI == EPI_PP) {
;       uint2 o; o.x = pack2bf(v0, v1); o.y = pack2bf(v2, v3);
;       *(uint2*)(g.outb + (size_t)token * D_ + fbase) = o;
;     } else if (EPI == EPI_PLE) {
;       const size_t idx = (size_t)token * D_ + fbase;
;       const float r = rs[q];
;       float4 hv = *(const float4*)(g.h + idx);
;       uint2 pp = *(const uint2*)(g.pp + idx);
;       const float rl = -r * 1.4426950408889634f;
;       hv.x += BFLO_(pp.x) * __builtin_amdgcn_rcpf(1.f + __builtin_amdgcn_exp2f(v0 * rl));
;       hv.y += BFHI_(pp.x) * __builtin_amdgcn_rcpf(1.f + __builtin_amdgcn_exp2f(v1 * rl));
;       hv.z += BFLO_(pp.y) * __builtin_amdgcn_rcpf(1.f + __builtin_amdgcn_exp2f(v2 * rl));
;       hv.w += BFHI_(pp.y) * __builtin_amdgcn_rcpf(1.f + __builtin_amdgcn_exp2f(v3 * rl));
;       *(float4*)(g.h + idx) = hv;
;       uint2 o; o.x = pack2bf(hv.x, hv.y); o.y = pack2bf(hv.z, hv.w);
;       *(uint2*)(g.outb + idx) = o;
;       sq[q] += (hv.x * hv.x + hv.y * hv.y) + (hv.z * hv.z + hv.w * hv.w);
.LBB0_689:
	s_cmp_gt_i32 s55, 3
	s_cbranch_scc0 .LBB0_691
.LBB0_691:
	s_andn2_b64 vcc, exec, s[20:21]
	s_cbranch_vccnz .LBB0_693
	v_ashrrev_i32_e32 v119, 31, v118
	v_lshlrev_b64 v[72:73], 12, v[118:119]
	v_lshl_add_u64 v[72:73], s[58:59], 0, v[72:73]
	v_cvt_pk_bf16_f32 v70, v66, v67
	v_cvt_pk_bf16_f32 v71, v68, v69
	v_lshl_add_u64 v[72:73], v[148:149], 1, v[72:73]
	v_mov_b32_e32 v80, v94
	global_store_dwordx2 v[72:73], v[70:71], off offset:96

; __device__ __forceinline__ void epi_block(const int EPI, const GemmArgs& g, f32x4 a00, f32x4 a01, f32x4 a10, f32x4 a11,
;                                           const int fbase, const int tok0, const float (&rs)[4], float (&sq)[4]) {
;     ...
;     } else if (EPI == EPI_RES) {
;       const size_t idx = (size_t)token * D_ + fbase;
;       float4 hv = *(const float4*)(g.h + idx);
;       hv.x += v0; hv.y += v1; hv.z += v2; hv.w += v3;
;       *(float4*)(g.h + idx) = hv;
;       uint2 o; o.x = pack2bf(hv.x, hv.y); o.y = pack2bf(hv.z, hv.w);
;       *(uint2*)(g.outb + idx) = o;
;       sq[q] += (hv.x * hv.x + hv.y * hv.y) + (hv.z * hv.z + hv.w * hv.w);
.LBB0_703:
	s_andn2_b64 vcc, exec, s[12:13]
	s_cbranch_vccnz .LBB0_705
.LBB0_705:
	v_mov_b32_e32 v90, v106
	v_cmp_gt_i32_e64 s[12:13], s95, v95
	s_cmp_lt_i32 s55, 3
	s_mov_b64 s[20:21], -1
	s_cbranch_scc0 .LBB0_677

; __device__ __forceinline__ void epi_block(const int EPI, const GemmArgs& g, f32x4 a00, f32x4 a01, f32x4 a10, f32x4 a11,
;                                           const int fbase, const int tok0, const float (&rs)[4], float (&sq)[4]) {
;     ...
;     } else if (EPI == EPI_RES) {
;       const size_t idx = (size_t)token * D_ + fbase;
;       float4 hv = *(const float4*)(g.h + idx);
;       hv.x += v0; hv.y += v1; hv.z += v2; hv.w += v3;
;       *(float4*)(g.h + idx) = hv;
;       uint2 o; o.x = pack2bf(hv.x, hv.y); o.y = pack2bf(hv.z, hv.w);
;       *(uint2*)(g.outb + idx) = o;
;       sq[q] += (hv.x * hv.x + hv.y * hv.y) + (hv.z * hv.z + hv.w * hv.w);
.LBB0_717:
	s_andn2_b64 vcc, exec, s[20:21]
	s_cbranch_vccnz .LBB0_719
.LBB0_719:
	v_mov_b32_e32 v86, v102
	s_cmp_lt_i32 s55, 3
	s_mov_b64 s[20:21], -1
	s_cbranch_scc0 .LBB0_683

; __device__ __forceinline__ void epi_block(const int EPI, const GemmArgs& g, f32x4 a00, f32x4 a01, f32x4 a10, f32x4 a11,
;                                           const int fbase, const int tok0, const float (&rs)[4], float (&sq)[4]) {
;     ...
;     } else if (EPI == EPI_RES) {
;       const size_t idx = (size_t)token * D_ + fbase;
;       float4 hv = *(const float4*)(g.h + idx);
;       hv.x += v0; hv.y += v1; hv.z += v2; hv.w += v3;
;       *(float4*)(g.h + idx) = hv;
;       uint2 o; o.x = pack2bf(hv.x, hv.y); o.y = pack2bf(hv.z, hv.w);
;       *(uint2*)(g.outb + idx) = o;
;       sq[q] += (hv.x * hv.x + hv.y * hv.y) + (hv.z * hv.z + hv.w * hv.w);
.LBB0_729:
	s_andn2_b64 vcc, exec, s[20:21]
	s_cbranch_vccnz .LBB0_731
.LBB0_731:
	v_mov_b32_e32 v81, v96
	s_cmp_lt_i32 s55, 3
	s_mov_b64 s[20:21], -1
	s_cbranch_scc0 .LBB0_689

; #define BFLO_(u) __uint_as_float((u) << 16)
; #define BFHI_(u) __uint_as_float((u) & 0xffff0000u)
; __device__ __forceinline__ void epi_block(const int EPI, const GemmArgs& g, f32x4 a00, f32x4 a01, f32x4 a10, f32x4 a11,
;                                           const int fbase, const int tok0, const float (&rs)[4], float (&sq)[4]) {
;     ...
;     } else if (EPI == EPI_RES) {
;       const size_t idx = (size_t)token * D_ + fbase;
;       float4 hv = *(const float4*)(g.h + idx);
;       hv.x += v0; hv.y += v1; hv.z += v2; hv.w += v3;
;       *(float4*)(g.h + idx) = hv;
;       uint2 o; o.x = pack2bf(hv.x, hv.y); o.y = pack2bf(hv.z, hv.w);
;       *(uint2*)(g.outb + idx) = o;
;       sq[q] += (hv.x * hv.x + hv.y * hv.y) + (hv.z * hv.z + hv.w * hv.w);
;     } else if (EPI == EPI_FF1) {
;       const float r = rs[q];
;       v0 = fmaxf(v0 * r, 0.f); v1 = fmaxf(v1 * r, 0.f); v2 = fmaxf(v2 * r, 0.f); v3 = fmaxf(v3 * r, 0.f);
;       uint2 o; o.x = pack2bf(v0 * v0, v1 * v1); o.y = pack2bf(v2 * v2, v3 * v3);
;       *(uint2*)(g.outb + (size_t)token * DFF + fbase) = o;
;     } else if (EPI == EPI_PP) {
;       uint2 o; o.x = pack2bf(v0, v1); o.y = pack2bf(v2, v3);
;       *(uint2*)(g.outb + (size_t)token * D_ + fbase) = o;
;     } else if (EPI == EPI_PLE) {
;       const size_t idx = (size_t)token * D_ + fbase;
;       const float r = rs[q];
;       float4 hv = *(const float4*)(g.h + idx);
;       uint2 pp = *(const uint2*)(g.pp + idx);
;       const float rl = -r * 1.4426950408889634f;
;       hv.x += BFLO_(pp.x) * __builtin_amdgcn_rcpf(1.f + __builtin_amdgcn_exp2f(v0 * rl));
;       hv.y += BFHI_(pp.x) * __builtin_amdgcn_rcpf(1.f + __builtin_amdgcn_exp2f(v1 * rl));
;       hv.z += BFLO_(pp.y) * __builtin_amdgcn_rcpf(1.f + __builtin_amdgcn_exp2f(v2 * rl));
;       hv.w += BFHI_(pp.y) * __builtin_amdgcn_rcpf(1.f + __builtin_amdgcn_exp2f(v3 * rl));
;       *(float4*)(g.h + idx) = hv;
;       uint2 o; o.x = pack2bf(hv.x, hv.y); o.y = pack2bf(hv.z, hv.w);
;       *(uint2*)(g.outb + idx) = o;
;       sq[q] += (hv.x * hv.x + hv.y * hv.y) + (hv.z * hv.z + hv.w * hv.w);
.LBB0_743:
	s_andn2_b64 vcc, exec, s[20:21]
	s_cbranch_vccnz .LBB0_745
.LBB0_745:
	v_mov_b32_e32 v80, v94
.LBB0_746:
	v_add_u32_e32 v66, s4, v142
	v_or_b32_e32 v66, v66, v0
	v_cmp_gt_i32_e64 s[10:11], s77, v66
	v_cmp_lt_i32_e64 s[8:9], s60, v66
	s_cmp_lt_i32 s55, 3
	s_mov_b64 s[12:13], -1
	s_cbranch_scc1 .LBB0_770
	s_cmp_gt_i32 s55, 3
	s_cbranch_scc0 .LBB0_749
.LBB0_749:
	s_andn2_b64 vcc, exec, s[12:13]
	s_cbranch_vccnz .LBB0_751
	v_ashrrev_i32_e32 v143, 31, v142
	v_lshlrev_b64 v[70:71], 12, v[140:141]
	v_lshl_add_u64 v[72:73], v[142:143], 0, s[50:51]
	v_lshl_add_u64 v[70:71], s[58:59], 0, v[70:71]
	v_lshl_add_u64 v[72:73], v[72:73], 0, v[0:1]
	v_cvt_pk_bf16_f32 v68, v62, v63
	v_cvt_pk_bf16_f32 v69, v64, v65
	v_lshl_add_u64 v[70:71], v[72:73], 1, v[70:71]
	v_mov_b32_e32 v76, v90
	global_store_dwordx2 v[70:71], v[68:69], off offset:256

; #define BFLO_(u) __uint_as_float((u) << 16)
; #define BFHI_(u) __uint_as_float((u) & 0xffff0000u)
; __device__ __forceinline__ void epi_block(const int EPI, const GemmArgs& g, f32x4 a00, f32x4 a01, f32x4 a10, f32x4 a11,
;                                           const int fbase, const int tok0, const float (&rs)[4], float (&sq)[4]) {
;     ...
;     } else if (EPI == EPI_PP) {
;       uint2 o; o.x = pack2bf(v0, v1); o.y = pack2bf(v2, v3);
;       *(uint2*)(g.outb + (size_t)token * D_ + fbase) = o;
;     } else if (EPI == EPI_PLE) {
;       const size_t idx = (size_t)token * D_ + fbase;
;       const float r = rs[q];
;       float4 hv = *(const float4*)(g.h + idx);
;       uint2 pp = *(const uint2*)(g.pp + idx);
;       const float rl = -r * 1.4426950408889634f;
;       hv.x += BFLO_(pp.x) * __builtin_amdgcn_rcpf(1.f + __builtin_amdgcn_exp2f(v0 * rl));
;       hv.y += BFHI_(pp.x) * __builtin_amdgcn_rcpf(1.f + __builtin_amdgcn_exp2f(v1 * rl));
;       hv.z += BFLO_(pp.y) * __builtin_amdgcn_rcpf(1.f + __builtin_amdgcn_exp2f(v2 * rl));
;       hv.w += BFHI_(pp.y) * __builtin_amdgcn_rcpf(1.f + __builtin_amdgcn_exp2f(v3 * rl));
;       *(float4*)(g.h + idx) = hv;
;       uint2 o; o.x = pack2bf(hv.x, hv.y); o.y = pack2bf(hv.z, hv.w);
;       *(uint2*)(g.outb + idx) = o;
;       sq[q] += (hv.x * hv.x + hv.y * hv.y) + (hv.z * hv.z + hv.w * hv.w);
.LBB0_753:
	s_cmp_gt_i32 s55, 3
	s_cbranch_scc0 .LBB0_755
.LBB0_755:
	s_andn2_b64 vcc, exec, s[20:21]
	s_cbranch_vccnz .LBB0_757
	v_ashrrev_i32_e32 v127, 31, v126
	v_ashrrev_i32_e32 v143, 31, v142
	v_lshlrev_b64 v[64:65], 12, v[126:127]
	v_lshl_add_u64 v[70:71], v[142:143], 0, s[50:51]
	v_lshl_add_u64 v[64:65], s[58:59], 0, v[64:65]
	v_lshl_add_u64 v[70:71], v[70:71], 0, v[0:1]
	v_cvt_pk_bf16_f32 v62, v58, v59
	v_cvt_pk_bf16_f32 v63, v60, v61
	v_lshl_add_u64 v[64:65], v[70:71], 1, v[64:65]
	v_mov_b32_e32 v72, v86
	global_store_dwordx2 v[64:65], v[62:63], off offset:256

; #define BFLO_(u) __uint_as_float((u) << 16)
; #define BFHI_(u) __uint_as_float((u) & 0xffff0000u)
; __device__ __forceinline__ void epi_block(const int EPI, const GemmArgs& g, f32x4 a00, f32x4 a01, f32x4 a10, f32x4 a11,
;                                           const int fbase, const int tok0, const float (&rs)[4], float (&sq)[4]) {
;     ...
;     } else if (EPI == EPI_PP) {
;       uint2 o; o.x = pack2bf(v0, v1); o.y = pack2bf(v2, v3);
;       *(uint2*)(g.outb + (size_t)token * D_ + fbase) = o;
;     } else if (EPI == EPI_PLE) {
;       const size_t idx = (size_t)token * D_ + fbase;
;       const float r = rs[q];
;       float4 hv = *(const float4*)(g.h + idx);
;       uint2 pp = *(const uint2*)(g.pp + idx);
;       const float rl = -r * 1.4426950408889634f;
;       hv.x += BFLO_(pp.x) * __builtin_amdgcn_rcpf(1.f + __builtin_amdgcn_exp2f(v0 * rl));
;       hv.y += BFHI_(pp.x) * __builtin_amdgcn_rcpf(1.f + __builtin_amdgcn_exp2f(v1 * rl));
;       hv.z += BFLO_(pp.y) * __builtin_amdgcn_rcpf(1.f + __builtin_amdgcn_exp2f(v2 * rl));
;       hv.w += BFHI_(pp.y) * __builtin_amdgcn_rcpf(1.f + __builtin_amdgcn_exp2f(v3 * rl));
;       *(float4*)(g.h + idx) = hv;
;       uint2 o; o.x = pack2bf(hv.x, hv.y); o.y = pack2bf(hv.z, hv.w);
;       *(uint2*)(g.outb + idx) = o;
;       sq[q] += (hv.x * hv.x + hv.y * hv.y) + (hv.z * hv.z + hv.w * hv.w);
.LBB0_759:
	s_cmp_gt_i32 s55, 3
	s_cbranch_scc0 .LBB0_761
.LBB0_761:
	s_andn2_b64 vcc, exec, s[20:21]
	s_cbranch_vccnz .LBB0_763
	v_ashrrev_i32_e32 v123, 31, v122
	v_ashrrev_i32_e32 v143, 31, v142
	v_lshlrev_b64 v[60:61], 12, v[122:123]
	v_lshl_add_u64 v[62:63], v[142:143], 0, s[50:51]
	v_lshl_add_u64 v[60:61], s[58:59], 0, v[60:61]
	v_lshl_add_u64 v[62:63], v[62:63], 0, v[0:1]
	v_cvt_pk_bf16_f32 v58, v54, v55
	v_cvt_pk_bf16_f32 v59, v56, v57
	v_lshl_add_u64 v[60:61], v[62:63], 1, v[60:61]
	v_mov_b32_e32 v64, v81
	global_store_dwordx2 v[60:61], v[58:59], off offset:256

; #define BFLO_(u) __uint_as_float((u) << 16)
; #define BFHI_(u) __uint_as_float((u) & 0xffff0000u)
; __device__ __forceinline__ void epi_block(const int EPI, const GemmArgs& g, f32x4 a00, f32x4 a01, f32x4 a10, f32x4 a11,
;                                           const int fbase, const int tok0, const float (&rs)[4], float (&sq)[4]) {
;     ...
;     } else if (EPI == EPI_PP) {
;       uint2 o; o.x = pack2bf(v0, v1); o.y = pack2bf(v2, v3);
;       *(uint2*)(g.outb + (size_t)token * D_ + fbase) = o;
;     } else if (EPI == EPI_PLE) {
;       const size_t idx = (size_t)token * D_ + fbase;
;       const float r = rs[q];
;       float4 hv = *(const float4*)(g.h + idx);
;       uint2 pp = *(const uint2*)(g.pp + idx);
;       const float rl = -r * 1.4426950408889634f;
;       hv.x += BFLO_(pp.x) * __builtin_amdgcn_rcpf(1.f + __builtin_amdgcn_exp2f(v0 * rl));
;       hv.y += BFHI_(pp.x) * __builtin_amdgcn_rcpf(1.f + __builtin_amdgcn_exp2f(v1 * rl));
;       hv.z += BFLO_(pp.y) * __builtin_amdgcn_rcpf(1.f + __builtin_amdgcn_exp2f(v2 * rl));
;       hv.w += BFHI_(pp.y) * __builtin_amdgcn_rcpf(1.f + __builtin_amdgcn_exp2f(v3 * rl));
;       *(float4*)(g.h + idx) = hv;
;       uint2 o; o.x = pack2bf(hv.x, hv.y); o.y = pack2bf(hv.z, hv.w);
;       *(uint2*)(g.outb + idx) = o;
;       sq[q] += (hv.x * hv.x + hv.y * hv.y) + (hv.z * hv.z + hv.w * hv.w);
.LBB0_765:
	s_cmp_gt_i32 s55, 3
	s_cbranch_scc0 .LBB0_767
.LBB0_767:
	s_andn2_b64 vcc, exec, s[20:21]
	s_cbranch_vccnz .LBB0_769
	v_ashrrev_i32_e32 v119, 31, v118
	v_ashrrev_i32_e32 v143, 31, v142
	v_lshlrev_b64 v[56:57], 12, v[118:119]
	v_lshl_add_u64 v[58:59], v[142:143], 0, s[50:51]
	v_lshl_add_u64 v[56:57], s[58:59], 0, v[56:57]
	v_lshl_add_u64 v[58:59], v[58:59], 0, v[0:1]
	v_cvt_pk_bf16_f32 v54, v50, v51
	v_cvt_pk_bf16_f32 v55, v52, v53
	v_lshl_add_u64 v[56:57], v[58:59], 1, v[56:57]
	v_mov_b32_e32 v62, v80
	global_store_dwordx2 v[56:57], v[54:55], off offset:256

; __device__ __forceinline__ void epi_block(const int EPI, const GemmArgs& g, f32x4 a00, f32x4 a01, f32x4 a10, f32x4 a11,
;                                           const int fbase, const int tok0, const float (&rs)[4], float (&sq)[4]) {
;     ...
;     } else if (EPI == EPI_RES) {
;       const size_t idx = (size_t)token * D_ + fbase;
;       float4 hv = *(const float4*)(g.h + idx);
;       hv.x += v0; hv.y += v1; hv.z += v2; hv.w += v3;
;       *(float4*)(g.h + idx) = hv;
;       uint2 o; o.x = pack2bf(hv.x, hv.y); o.y = pack2bf(hv.z, hv.w);
;       *(uint2*)(g.outb + idx) = o;
;       sq[q] += (hv.x * hv.x + hv.y * hv.y) + (hv.z * hv.z + hv.w * hv.w);
.LBB0_779:
	s_andn2_b64 vcc, exec, s[12:13]
	s_cbranch_vccnz .LBB0_781
.LBB0_781:
	v_mov_b32_e32 v76, v90
	v_cmp_gt_i32_e64 s[12:13], s95, v66
	s_cmp_lt_i32 s55, 3
	s_mov_b64 s[20:21], -1
	s_cbranch_scc0 .LBB0_753

; __device__ __forceinline__ void epi_block(const int EPI, const GemmArgs& g, f32x4 a00, f32x4 a01, f32x4 a10, f32x4 a11,
;                                           const int fbase, const int tok0, const float (&rs)[4], float (&sq)[4]) {
;     ...
;     } else if (EPI == EPI_RES) {
;       const size_t idx = (size_t)token * D_ + fbase;
;       float4 hv = *(const float4*)(g.h + idx);
;       hv.x += v0; hv.y += v1; hv.z += v2; hv.w += v3;
;       *(float4*)(g.h + idx) = hv;
;       uint2 o; o.x = pack2bf(hv.x, hv.y); o.y = pack2bf(hv.z, hv.w);
;       *(uint2*)(g.outb + idx) = o;
;       sq[q] += (hv.x * hv.x + hv.y * hv.y) + (hv.z * hv.z + hv.w * hv.w);
.LBB0_793:
	s_andn2_b64 vcc, exec, s[20:21]
	s_cbranch_vccnz .LBB0_795
.LBB0_795:
	v_mov_b32_e32 v72, v86
	s_cmp_lt_i32 s55, 3
	s_mov_b64 s[20:21], -1
	s_cbranch_scc0 .LBB0_759

; __device__ __forceinline__ void epi_block(const int EPI, const GemmArgs& g, f32x4 a00, f32x4 a01, f32x4 a10, f32x4 a11,
;                                           const int fbase, const int tok0, const float (&rs)[4], float (&sq)[4]) {
;     ...
;     } else if (EPI == EPI_RES) {
;       const size_t idx = (size_t)token * D_ + fbase;
;       float4 hv = *(const float4*)(g.h + idx);
;       hv.x += v0; hv.y += v1; hv.z += v2; hv.w += v3;
;       *(float4*)(g.h + idx) = hv;
;       uint2 o; o.x = pack2bf(hv.x, hv.y); o.y = pack2bf(hv.z, hv.w);
;       *(uint2*)(g.outb + idx) = o;
;       sq[q] += (hv.x * hv.x + hv.y * hv.y) + (hv.z * hv.z + hv.w * hv.w);
.LBB0_805:
	s_andn2_b64 vcc, exec, s[20:21]
	s_cbranch_vccnz .LBB0_807
.LBB0_807:
	v_mov_b32_e32 v64, v81
	s_cmp_lt_i32 s55, 3
	s_mov_b64 s[20:21], -1
	s_cbranch_scc0 .LBB0_765

; #define BFLO_(u) __uint_as_float((u) << 16)
; #define BFHI_(u) __uint_as_float((u) & 0xffff0000u)
; __device__ __forceinline__ void epi_block(const int EPI, const GemmArgs& g, f32x4 a00, f32x4 a01, f32x4 a10, f32x4 a11,
;                                           const int fbase, const int tok0, const float (&rs)[4], float (&sq)[4]) {
;     ...
;     } else if (EPI == EPI_RES) {
;       const size_t idx = (size_t)token * D_ + fbase;
;       float4 hv = *(const float4*)(g.h + idx);
;       hv.x += v0; hv.y += v1; hv.z += v2; hv.w += v3;
;       *(float4*)(g.h + idx) = hv;
;       uint2 o; o.x = pack2bf(hv.x, hv.y); o.y = pack2bf(hv.z, hv.w);
;       *(uint2*)(g.outb + idx) = o;
;       sq[q] += (hv.x * hv.x + hv.y * hv.y) + (hv.z * hv.z + hv.w * hv.w);
;     } else if (EPI == EPI_FF1) {
;       const float r = rs[q];
;       v0 = fmaxf(v0 * r, 0.f); v1 = fmaxf(v1 * r, 0.f); v2 = fmaxf(v2 * r, 0.f); v3 = fmaxf(v3 * r, 0.f);
;       uint2 o; o.x = pack2bf(v0 * v0, v1 * v1); o.y = pack2bf(v2 * v2, v3 * v3);
;       *(uint2*)(g.outb + (size_t)token * DFF + fbase) = o;
;     } else if (EPI == EPI_PP) {
;       uint2 o; o.x = pack2bf(v0, v1); o.y = pack2bf(v2, v3);
;       *(uint2*)(g.outb + (size_t)token * D_ + fbase) = o;
;     } else if (EPI == EPI_PLE) {
;       const size_t idx = (size_t)token * D_ + fbase;
;       const float r = rs[q];
;       float4 hv = *(const float4*)(g.h + idx);
;       uint2 pp = *(const uint2*)(g.pp + idx);
;       const float rl = -r * 1.4426950408889634f;
;       hv.x += BFLO_(pp.x) * __builtin_amdgcn_rcpf(1.f + __builtin_amdgcn_exp2f(v0 * rl));
;       hv.y += BFHI_(pp.x) * __builtin_amdgcn_rcpf(1.f + __builtin_amdgcn_exp2f(v1 * rl));
;       hv.z += BFLO_(pp.y) * __builtin_amdgcn_rcpf(1.f + __builtin_amdgcn_exp2f(v2 * rl));
;       hv.w += BFHI_(pp.y) * __builtin_amdgcn_rcpf(1.f + __builtin_amdgcn_exp2f(v3 * rl));
;       *(float4*)(g.h + idx) = hv;
;       uint2 o; o.x = pack2bf(hv.x, hv.y); o.y = pack2bf(hv.z, hv.w);
;       *(uint2*)(g.outb + idx) = o;
;       sq[q] += (hv.x * hv.x + hv.y * hv.y) + (hv.z * hv.z + hv.w * hv.w);
.LBB0_819:
	s_andn2_b64 vcc, exec, s[20:21]
	s_cbranch_vccnz .LBB0_821
.LBB0_821:
	v_mov_b32_e32 v62, v80
.LBB0_822:
	v_or_b32_e32 v63, 16, v66
	v_cmp_gt_i32_e64 s[10:11], s77, v63
	v_cmp_lt_i32_e64 s[8:9], s60, v63
	s_cmp_lt_i32 s55, 3
	s_mov_b64 s[12:13], -1
	s_cbranch_scc1 .LBB0_846
	s_cmp_gt_i32 s55, 3
	s_cbranch_scc0 .LBB0_825
.LBB0_825:
	s_andn2_b64 vcc, exec, s[12:13]
	s_cbranch_vccnz .LBB0_827
	v_ashrrev_i32_e32 v143, 31, v142
	v_lshlrev_b64 v[52:53], 12, v[140:141]
	v_lshl_add_u64 v[54:55], v[142:143], 0, s[50:51]
	v_lshl_add_u64 v[52:53], s[58:59], 0, v[52:53]
	v_lshl_add_u64 v[54:55], v[54:55], 0, v[0:1]
	v_cvt_pk_bf16_f32 v50, v46, v47
	v_cvt_pk_bf16_f32 v51, v48, v49
	v_lshl_add_u64 v[52:53], v[54:55], 1, v[52:53]
	v_mov_b32_e32 v58, v76
	global_store_dwordx2 v[52:53], v[50:51], off offset:288

; #define BFLO_(u) __uint_as_float((u) << 16)
; #define BFHI_(u) __uint_as_float((u) & 0xffff0000u)
; __device__ __forceinline__ void epi_block(const int EPI, const GemmArgs& g, f32x4 a00, f32x4 a01, f32x4 a10, f32x4 a11,
;                                           const int fbase, const int tok0, const float (&rs)[4], float (&sq)[4]) {
;     ...
;     } else if (EPI == EPI_PP) {
;       uint2 o; o.x = pack2bf(v0, v1); o.y = pack2bf(v2, v3);
;       *(uint2*)(g.outb + (size_t)token * D_ + fbase) = o;
;     } else if (EPI == EPI_PLE) {
;       const size_t idx = (size_t)token * D_ + fbase;
;       const float r = rs[q];
;       float4 hv = *(const float4*)(g.h + idx);
;       uint2 pp = *(const uint2*)(g.pp + idx);
;       const float rl = -r * 1.4426950408889634f;
;       hv.x += BFLO_(pp.x) * __builtin_amdgcn_rcpf(1.f + __builtin_amdgcn_exp2f(v0 * rl));
;       hv.y += BFHI_(pp.x) * __builtin_amdgcn_rcpf(1.f + __builtin_amdgcn_exp2f(v1 * rl));
;       hv.z += BFLO_(pp.y) * __builtin_amdgcn_rcpf(1.f + __builtin_amdgcn_exp2f(v2 * rl));
;       hv.w += BFHI_(pp.y) * __builtin_amdgcn_rcpf(1.f + __builtin_amdgcn_exp2f(v3 * rl));
;       *(float4*)(g.h + idx) = hv;
;       uint2 o; o.x = pack2bf(hv.x, hv.y); o.y = pack2bf(hv.z, hv.w);
;       *(uint2*)(g.outb + idx) = o;
;       sq[q] += (hv.x * hv.x + hv.y * hv.y) + (hv.z * hv.z + hv.w * hv.w);
.LBB0_829:
	s_cmp_gt_i32 s55, 3
	s_cbranch_scc0 .LBB0_831
.LBB0_831:
	s_andn2_b64 vcc, exec, s[20:21]
	s_cbranch_vccnz .LBB0_833
	v_ashrrev_i32_e32 v127, 31, v126
	v_ashrrev_i32_e32 v143, 31, v142
	v_lshlrev_b64 v[48:49], 12, v[126:127]
	v_lshl_add_u64 v[52:53], v[142:143], 0, s[50:51]
	v_lshl_add_u64 v[48:49], s[58:59], 0, v[48:49]
	v_lshl_add_u64 v[52:53], v[52:53], 0, v[0:1]
	v_cvt_pk_bf16_f32 v46, v42, v43
	v_cvt_pk_bf16_f32 v47, v44, v45
	v_lshl_add_u64 v[48:49], v[52:53], 1, v[48:49]
	v_mov_b32_e32 v54, v72
	global_store_dwordx2 v[48:49], v[46:47], off offset:288

; #define BFLO_(u) __uint_as_float((u) << 16)
; #define BFHI_(u) __uint_as_float((u) & 0xffff0000u)
; __device__ __forceinline__ void epi_block(const int EPI, const GemmArgs& g, f32x4 a00, f32x4 a01, f32x4 a10, f32x4 a11,
;                                           const int fbase, const int tok0, const float (&rs)[4], float (&sq)[4]) {
;     ...
;     } else if (EPI == EPI_PP) {
;       uint2 o; o.x = pack2bf(v0, v1); o.y = pack2bf(v2, v3);
;       *(uint2*)(g.outb + (size_t)token * D_ + fbase) = o;
;     } else if (EPI == EPI_PLE) {
;       const size_t idx = (size_t)token * D_ + fbase;
;       const float r = rs[q];
;       float4 hv = *(const float4*)(g.h + idx);
;       uint2 pp = *(const uint2*)(g.pp + idx);
;       const float rl = -r * 1.4426950408889634f;
;       hv.x += BFLO_(pp.x) * __builtin_amdgcn_rcpf(1.f + __builtin_amdgcn_exp2f(v0 * rl));
;       hv.y += BFHI_(pp.x) * __builtin_amdgcn_rcpf(1.f + __builtin_amdgcn_exp2f(v1 * rl));
;       hv.z += BFLO_(pp.y) * __builtin_amdgcn_rcpf(1.f + __builtin_amdgcn_exp2f(v2 * rl));
;       hv.w += BFHI_(pp.y) * __builtin_amdgcn_rcpf(1.f + __builtin_amdgcn_exp2f(v3 * rl));
;       *(float4*)(g.h + idx) = hv;
;       uint2 o; o.x = pack2bf(hv.x, hv.y); o.y = pack2bf(hv.z, hv.w);
;       *(uint2*)(g.outb + idx) = o;
;       sq[q] += (hv.x * hv.x + hv.y * hv.y) + (hv.z * hv.z + hv.w * hv.w);
.LBB0_835:
	s_cmp_gt_i32 s55, 3
	s_cbranch_scc0 .LBB0_837
.LBB0_837:
	s_andn2_b64 vcc, exec, s[20:21]
	s_cbranch_vccnz .LBB0_839
	v_ashrrev_i32_e32 v123, 31, v122
	v_ashrrev_i32_e32 v143, 31, v142
	v_lshlrev_b64 v[44:45], 12, v[122:123]
	v_lshl_add_u64 v[46:47], v[142:143], 0, s[50:51]
	v_lshl_add_u64 v[44:45], s[58:59], 0, v[44:45]
	v_lshl_add_u64 v[46:47], v[46:47], 0, v[0:1]
	v_cvt_pk_bf16_f32 v42, v38, v39
	v_cvt_pk_bf16_f32 v43, v40, v41
	v_lshl_add_u64 v[44:45], v[46:47], 1, v[44:45]
	v_mov_b32_e32 v48, v64
	global_store_dwordx2 v[44:45], v[42:43], off offset:288

; #define BFLO_(u) __uint_as_float((u) << 16)
; #define BFHI_(u) __uint_as_float((u) & 0xffff0000u)
; __device__ __forceinline__ void epi_block(const int EPI, const GemmArgs& g, f32x4 a00, f32x4 a01, f32x4 a10, f32x4 a11,
;                                           const int fbase, const int tok0, const float (&rs)[4], float (&sq)[4]) {
;     ...
;     } else if (EPI == EPI_PP) {
;       uint2 o; o.x = pack2bf(v0, v1); o.y = pack2bf(v2, v3);
;       *(uint2*)(g.outb + (size_t)token * D_ + fbase) = o;
;     } else if (EPI == EPI_PLE) {
;       const size_t idx = (size_t)token * D_ + fbase;
;       const float r = rs[q];
;       float4 hv = *(const float4*)(g.h + idx);
;       uint2 pp = *(const uint2*)(g.pp + idx);
;       const float rl = -r * 1.4426950408889634f;
;       hv.x += BFLO_(pp.x) * __builtin_amdgcn_rcpf(1.f + __builtin_amdgcn_exp2f(v0 * rl));
;       hv.y += BFHI_(pp.x) * __builtin_amdgcn_rcpf(1.f + __builtin_amdgcn_exp2f(v1 * rl));
;       hv.z += BFLO_(pp.y) * __builtin_amdgcn_rcpf(1.f + __builtin_amdgcn_exp2f(v2 * rl));
;       hv.w += BFHI_(pp.y) * __builtin_amdgcn_rcpf(1.f + __builtin_amdgcn_exp2f(v3 * rl));
;       *(float4*)(g.h + idx) = hv;
;       uint2 o; o.x = pack2bf(hv.x, hv.y); o.y = pack2bf(hv.z, hv.w);
;       *(uint2*)(g.outb + idx) = o;
;       sq[q] += (hv.x * hv.x + hv.y * hv.y) + (hv.z * hv.z + hv.w * hv.w);
.LBB0_841:
	s_cmp_gt_i32 s55, 3
	s_cbranch_scc0 .LBB0_843
.LBB0_843:
	s_andn2_b64 vcc, exec, s[20:21]
	s_cbranch_vccnz .LBB0_845
	v_ashrrev_i32_e32 v119, 31, v118
	v_ashrrev_i32_e32 v143, 31, v142
	v_lshlrev_b64 v[40:41], 12, v[118:119]
	v_lshl_add_u64 v[42:43], v[142:143], 0, s[50:51]
	v_lshl_add_u64 v[40:41], s[58:59], 0, v[40:41]
	v_lshl_add_u64 v[42:43], v[42:43], 0, v[0:1]
	v_cvt_pk_bf16_f32 v38, v34, v35
	v_cvt_pk_bf16_f32 v39, v36, v37
	v_lshl_add_u64 v[40:41], v[42:43], 1, v[40:41]
	v_mov_b32_e32 v46, v62
	global_store_dwordx2 v[40:41], v[38:39], off offset:288

; __device__ __forceinline__ void epi_block(const int EPI, const GemmArgs& g, f32x4 a00, f32x4 a01, f32x4 a10, f32x4 a11,
;                                           const int fbase, const int tok0, const float (&rs)[4], float (&sq)[4]) {
;     ...
;     } else if (EPI == EPI_RES) {
;       const size_t idx = (size_t)token * D_ + fbase;
;       float4 hv = *(const float4*)(g.h + idx);
;       hv.x += v0; hv.y += v1; hv.z += v2; hv.w += v3;
;       *(float4*)(g.h + idx) = hv;
;       uint2 o; o.x = pack2bf(hv.x, hv.y); o.y = pack2bf(hv.z, hv.w);
;       *(uint2*)(g.outb + idx) = o;
;       sq[q] += (hv.x * hv.x + hv.y * hv.y) + (hv.z * hv.z + hv.w * hv.w);
.LBB0_855:
	s_andn2_b64 vcc, exec, s[12:13]
	s_cbranch_vccnz .LBB0_857
.LBB0_857:
	v_mov_b32_e32 v58, v76
	v_cmp_gt_i32_e64 s[12:13], s95, v63
	s_cmp_lt_i32 s55, 3
	s_mov_b64 s[20:21], -1
	s_cbranch_scc0 .LBB0_829

; __device__ __forceinline__ void epi_block(const int EPI, const GemmArgs& g, f32x4 a00, f32x4 a01, f32x4 a10, f32x4 a11,
;                                           const int fbase, const int tok0, const float (&rs)[4], float (&sq)[4]) {
;     ...
;     } else if (EPI == EPI_RES) {
;       const size_t idx = (size_t)token * D_ + fbase;
;       float4 hv = *(const float4*)(g.h + idx);
;       hv.x += v0; hv.y += v1; hv.z += v2; hv.w += v3;
;       *(float4*)(g.h + idx) = hv;
;       uint2 o; o.x = pack2bf(hv.x, hv.y); o.y = pack2bf(hv.z, hv.w);
;       *(uint2*)(g.outb + idx) = o;
;       sq[q] += (hv.x * hv.x + hv.y * hv.y) + (hv.z * hv.z + hv.w * hv.w);
.LBB0_869:
	s_andn2_b64 vcc, exec, s[20:21]
	s_cbranch_vccnz .LBB0_871
.LBB0_871:
	v_mov_b32_e32 v54, v72
	s_cmp_lt_i32 s55, 3
	s_mov_b64 s[20:21], -1
	s_cbranch_scc0 .LBB0_835

; __device__ __forceinline__ void epi_block(const int EPI, const GemmArgs& g, f32x4 a00, f32x4 a01, f32x4 a10, f32x4 a11,
;                                           const int fbase, const int tok0, const float (&rs)[4], float (&sq)[4]) {
;     ...
;     } else if (EPI == EPI_RES) {
;       const size_t idx = (size_t)token * D_ + fbase;
;       float4 hv = *(const float4*)(g.h + idx);
;       hv.x += v0; hv.y += v1; hv.z += v2; hv.w += v3;
;       *(float4*)(g.h + idx) = hv;
;       uint2 o; o.x = pack2bf(hv.x, hv.y); o.y = pack2bf(hv.z, hv.w);
;       *(uint2*)(g.outb + idx) = o;
;       sq[q] += (hv.x * hv.x + hv.y * hv.y) + (hv.z * hv.z + hv.w * hv.w);
.LBB0_881:
	s_andn2_b64 vcc, exec, s[20:21]
	s_cbranch_vccnz .LBB0_883
.LBB0_883:
	v_mov_b32_e32 v48, v64
	s_cmp_lt_i32 s55, 3
	s_mov_b64 s[20:21], -1
	s_cbranch_scc0 .LBB0_841

; #define BFLO_(u) __uint_as_float((u) << 16)
; #define BFHI_(u) __uint_as_float((u) & 0xffff0000u)
; __device__ __forceinline__ void epi_block(const int EPI, const GemmArgs& g, f32x4 a00, f32x4 a01, f32x4 a10, f32x4 a11,
;                                           const int fbase, const int tok0, const float (&rs)[4], float (&sq)[4]) {
;     ...
;     } else if (EPI == EPI_RES) {
;       const size_t idx = (size_t)token * D_ + fbase;
;       float4 hv = *(const float4*)(g.h + idx);
;       hv.x += v0; hv.y += v1; hv.z += v2; hv.w += v3;
;       *(float4*)(g.h + idx) = hv;
;       uint2 o; o.x = pack2bf(hv.x, hv.y); o.y = pack2bf(hv.z, hv.w);
;       *(uint2*)(g.outb + idx) = o;
;       sq[q] += (hv.x * hv.x + hv.y * hv.y) + (hv.z * hv.z + hv.w * hv.w);
;     } else if (EPI == EPI_FF1) {
;       const float r = rs[q];
;       v0 = fmaxf(v0 * r, 0.f); v1 = fmaxf(v1 * r, 0.f); v2 = fmaxf(v2 * r, 0.f); v3 = fmaxf(v3 * r, 0.f);
;       uint2 o; o.x = pack2bf(v0 * v0, v1 * v1); o.y = pack2bf(v2 * v2, v3 * v3);
;       *(uint2*)(g.outb + (size_t)token * DFF + fbase) = o;
;     } else if (EPI == EPI_PP) {
;       uint2 o; o.x = pack2bf(v0, v1); o.y = pack2bf(v2, v3);
;       *(uint2*)(g.outb + (size_t)token * D_ + fbase) = o;
;     } else if (EPI == EPI_PLE) {
;       const size_t idx = (size_t)token * D_ + fbase;
;       const float r = rs[q];
;       float4 hv = *(const float4*)(g.h + idx);
;       uint2 pp = *(const uint2*)(g.pp + idx);
;       const float rl = -r * 1.4426950408889634f;
;       hv.x += BFLO_(pp.x) * __builtin_amdgcn_rcpf(1.f + __builtin_amdgcn_exp2f(v0 * rl));
;       hv.y += BFHI_(pp.x) * __builtin_amdgcn_rcpf(1.f + __builtin_amdgcn_exp2f(v1 * rl));
;       hv.z += BFLO_(pp.y) * __builtin_amdgcn_rcpf(1.f + __builtin_amdgcn_exp2f(v2 * rl));
;       hv.w += BFHI_(pp.y) * __builtin_amdgcn_rcpf(1.f + __builtin_amdgcn_exp2f(v3 * rl));
;       *(float4*)(g.h + idx) = hv;
;       uint2 o; o.x = pack2bf(hv.x, hv.y); o.y = pack2bf(hv.z, hv.w);
;       *(uint2*)(g.outb + idx) = o;
;       sq[q] += (hv.x * hv.x + hv.y * hv.y) + (hv.z * hv.z + hv.w * hv.w);
.LBB0_895:
	s_andn2_b64 vcc, exec, s[20:21]
	s_cbranch_vccnz .LBB0_897
.LBB0_897:
	v_mov_b32_e32 v46, v62
.LBB0_898:
	v_or_b32_e32 v47, 32, v66
	v_cmp_gt_i32_e64 s[10:11], s77, v47
	v_cmp_lt_i32_e64 s[8:9], s60, v47
	s_cmp_lt_i32 s55, 3
	s_mov_b64 s[12:13], -1
	s_cbranch_scc1 .LBB0_922
	s_cmp_gt_i32 s55, 3
	s_cbranch_scc0 .LBB0_901
.LBB0_901:
	s_andn2_b64 vcc, exec, s[12:13]
	s_cbranch_vccnz .LBB0_903
	v_ashrrev_i32_e32 v143, 31, v142
	v_lshlrev_b64 v[36:37], 12, v[140:141]
	v_lshl_add_u64 v[38:39], v[142:143], 0, s[50:51]
	v_lshl_add_u64 v[36:37], s[58:59], 0, v[36:37]
	v_lshl_add_u64 v[38:39], v[38:39], 0, v[0:1]
	v_cvt_pk_bf16_f32 v34, v30, v31
	v_cvt_pk_bf16_f32 v35, v32, v33
	v_lshl_add_u64 v[36:37], v[38:39], 1, v[36:37]
	v_mov_b32_e32 v42, v58
	global_store_dwordx2 v[36:37], v[34:35], off offset:320

; #define BFLO_(u) __uint_as_float((u) << 16)
; #define BFHI_(u) __uint_as_float((u) & 0xffff0000u)
; __device__ __forceinline__ void epi_block(const int EPI, const GemmArgs& g, f32x4 a00, f32x4 a01, f32x4 a10, f32x4 a11,
;                                           const int fbase, const int tok0, const float (&rs)[4], float (&sq)[4]) {
;     ...
;     } else if (EPI == EPI_PP) {
;       uint2 o; o.x = pack2bf(v0, v1); o.y = pack2bf(v2, v3);
;       *(uint2*)(g.outb + (size_t)token * D_ + fbase) = o;
;     } else if (EPI == EPI_PLE) {
;       const size_t idx = (size_t)token * D_ + fbase;
;       const float r = rs[q];
;       float4 hv = *(const float4*)(g.h + idx);
;       uint2 pp = *(const uint2*)(g.pp + idx);
;       const float rl = -r * 1.4426950408889634f;
;       hv.x += BFLO_(pp.x) * __builtin_amdgcn_rcpf(1.f + __builtin_amdgcn_exp2f(v0 * rl));
;       hv.y += BFHI_(pp.x) * __builtin_amdgcn_rcpf(1.f + __builtin_amdgcn_exp2f(v1 * rl));
;       hv.z += BFLO_(pp.y) * __builtin_amdgcn_rcpf(1.f + __builtin_amdgcn_exp2f(v2 * rl));
;       hv.w += BFHI_(pp.y) * __builtin_amdgcn_rcpf(1.f + __builtin_amdgcn_exp2f(v3 * rl));
;       *(float4*)(g.h + idx) = hv;
;       uint2 o; o.x = pack2bf(hv.x, hv.y); o.y = pack2bf(hv.z, hv.w);
;       *(uint2*)(g.outb + idx) = o;
;       sq[q] += (hv.x * hv.x + hv.y * hv.y) + (hv.z * hv.z + hv.w * hv.w);
.LBB0_905:
	s_cmp_gt_i32 s55, 3
	s_cbranch_scc0 .LBB0_907
.LBB0_907:
	s_andn2_b64 vcc, exec, s[20:21]
	s_cbranch_vccnz .LBB0_909
	v_ashrrev_i32_e32 v127, 31, v126
	v_ashrrev_i32_e32 v143, 31, v142
	v_lshlrev_b64 v[32:33], 12, v[126:127]
	v_lshl_add_u64 v[36:37], v[142:143], 0, s[50:51]
	v_lshl_add_u64 v[32:33], s[58:59], 0, v[32:33]
	v_lshl_add_u64 v[36:37], v[36:37], 0, v[0:1]
	v_cvt_pk_bf16_f32 v30, v26, v27
	v_cvt_pk_bf16_f32 v31, v28, v29
	v_lshl_add_u64 v[32:33], v[36:37], 1, v[32:33]
	v_mov_b32_e32 v38, v54
	global_store_dwordx2 v[32:33], v[30:31], off offset:320

; #define BFLO_(u) __uint_as_float((u) << 16)
; #define BFHI_(u) __uint_as_float((u) & 0xffff0000u)
; __device__ __forceinline__ void epi_block(const int EPI, const GemmArgs& g, f32x4 a00, f32x4 a01, f32x4 a10, f32x4 a11,
;                                           const int fbase, const int tok0, const float (&rs)[4], float (&sq)[4]) {
;     ...
;     } else if (EPI == EPI_PP) {
;       uint2 o; o.x = pack2bf(v0, v1); o.y = pack2bf(v2, v3);
;       *(uint2*)(g.outb + (size_t)token * D_ + fbase) = o;
;     } else if (EPI == EPI_PLE) {
;       const size_t idx = (size_t)token * D_ + fbase;
;       const float r = rs[q];
;       float4 hv = *(const float4*)(g.h + idx);
;       uint2 pp = *(const uint2*)(g.pp + idx);
;       const float rl = -r * 1.4426950408889634f;
;       hv.x += BFLO_(pp.x) * __builtin_amdgcn_rcpf(1.f + __builtin_amdgcn_exp2f(v0 * rl));
;       hv.y += BFHI_(pp.x) * __builtin_amdgcn_rcpf(1.f + __builtin_amdgcn_exp2f(v1 * rl));
;       hv.z += BFLO_(pp.y) * __builtin_amdgcn_rcpf(1.f + __builtin_amdgcn_exp2f(v2 * rl));
;       hv.w += BFHI_(pp.y) * __builtin_amdgcn_rcpf(1.f + __builtin_amdgcn_exp2f(v3 * rl));
;       *(float4*)(g.h + idx) = hv;
;       uint2 o; o.x = pack2bf(hv.x, hv.y); o.y = pack2bf(hv.z, hv.w);
;       *(uint2*)(g.outb + idx) = o;
;       sq[q] += (hv.x * hv.x + hv.y * hv.y) + (hv.z * hv.z + hv.w * hv.w);
.LBB0_911:
	s_cmp_gt_i32 s55, 3
	s_cbranch_scc0 .LBB0_913
.LBB0_913:
	s_andn2_b64 vcc, exec, s[20:21]
	s_cbranch_vccnz .LBB0_915
	v_ashrrev_i32_e32 v123, 31, v122
	v_ashrrev_i32_e32 v143, 31, v142
	v_lshlrev_b64 v[28:29], 12, v[122:123]
	v_lshl_add_u64 v[30:31], v[142:143], 0, s[50:51]
	v_lshl_add_u64 v[28:29], s[58:59], 0, v[28:29]
	v_lshl_add_u64 v[30:31], v[30:31], 0, v[0:1]
	v_cvt_pk_bf16_f32 v26, v22, v23
	v_cvt_pk_bf16_f32 v27, v24, v25
	v_lshl_add_u64 v[28:29], v[30:31], 1, v[28:29]
	v_mov_b32_e32 v32, v48
	global_store_dwordx2 v[28:29], v[26:27], off offset:320

; #define BFLO_(u) __uint_as_float((u) << 16)
; #define BFHI_(u) __uint_as_float((u) & 0xffff0000u)
; __device__ __forceinline__ void epi_block(const int EPI, const GemmArgs& g, f32x4 a00, f32x4 a01, f32x4 a10, f32x4 a11,
;                                           const int fbase, const int tok0, const float (&rs)[4], float (&sq)[4]) {
;     ...
;     } else if (EPI == EPI_PP) {
;       uint2 o; o.x = pack2bf(v0, v1); o.y = pack2bf(v2, v3);
;       *(uint2*)(g.outb + (size_t)token * D_ + fbase) = o;
;     } else if (EPI == EPI_PLE) {
;       const size_t idx = (size_t)token * D_ + fbase;
;       const float r = rs[q];
;       float4 hv = *(const float4*)(g.h + idx);
;       uint2 pp = *(const uint2*)(g.pp + idx);
;       const float rl = -r * 1.4426950408889634f;
;       hv.x += BFLO_(pp.x) * __builtin_amdgcn_rcpf(1.f + __builtin_amdgcn_exp2f(v0 * rl));
;       hv.y += BFHI_(pp.x) * __builtin_amdgcn_rcpf(1.f + __builtin_amdgcn_exp2f(v1 * rl));
;       hv.z += BFLO_(pp.y) * __builtin_amdgcn_rcpf(1.f + __builtin_amdgcn_exp2f(v2 * rl));
;       hv.w += BFHI_(pp.y) * __builtin_amdgcn_rcpf(1.f + __builtin_amdgcn_exp2f(v3 * rl));
;       *(float4*)(g.h + idx) = hv;
;       uint2 o; o.x = pack2bf(hv.x, hv.y); o.y = pack2bf(hv.z, hv.w);
;       *(uint2*)(g.outb + idx) = o;
;       sq[q] += (hv.x * hv.x + hv.y * hv.y) + (hv.z * hv.z + hv.w * hv.w);
.LBB0_917:
	s_cmp_gt_i32 s55, 3
	s_cbranch_scc0 .LBB0_919
.LBB0_919:
	s_andn2_b64 vcc, exec, s[20:21]
	s_cbranch_vccnz .LBB0_921
	v_ashrrev_i32_e32 v119, 31, v118
	v_ashrrev_i32_e32 v143, 31, v142
	v_lshlrev_b64 v[24:25], 12, v[118:119]
	v_lshl_add_u64 v[26:27], v[142:143], 0, s[50:51]
	v_lshl_add_u64 v[24:25], s[58:59], 0, v[24:25]
	v_lshl_add_u64 v[26:27], v[26:27], 0, v[0:1]
	v_cvt_pk_bf16_f32 v22, v18, v19
	v_cvt_pk_bf16_f32 v23, v20, v21
	v_lshl_add_u64 v[24:25], v[26:27], 1, v[24:25]
	v_mov_b32_e32 v30, v46
	global_store_dwordx2 v[24:25], v[22:23], off offset:320

; __device__ __forceinline__ void epi_block(const int EPI, const GemmArgs& g, f32x4 a00, f32x4 a01, f32x4 a10, f32x4 a11,
;                                           const int fbase, const int tok0, const float (&rs)[4], float (&sq)[4]) {
;     ...
;     } else if (EPI == EPI_RES) {
;       const size_t idx = (size_t)token * D_ + fbase;
;       float4 hv = *(const float4*)(g.h + idx);
;       hv.x += v0; hv.y += v1; hv.z += v2; hv.w += v3;
;       *(float4*)(g.h + idx) = hv;
;       uint2 o; o.x = pack2bf(hv.x, hv.y); o.y = pack2bf(hv.z, hv.w);
;       *(uint2*)(g.outb + idx) = o;
;       sq[q] += (hv.x * hv.x + hv.y * hv.y) + (hv.z * hv.z + hv.w * hv.w);
.LBB0_931:
	s_andn2_b64 vcc, exec, s[12:13]
	s_cbranch_vccnz .LBB0_933
.LBB0_933:
	v_mov_b32_e32 v42, v58
	v_cmp_gt_i32_e64 s[12:13], s95, v47
	s_cmp_lt_i32 s55, 3
	s_mov_b64 s[20:21], -1
	s_cbranch_scc0 .LBB0_905

; __device__ __forceinline__ void epi_block(const int EPI, const GemmArgs& g, f32x4 a00, f32x4 a01, f32x4 a10, f32x4 a11,
;                                           const int fbase, const int tok0, const float (&rs)[4], float (&sq)[4]) {
;     ...
;     } else if (EPI == EPI_RES) {
;       const size_t idx = (size_t)token * D_ + fbase;
;       float4 hv = *(const float4*)(g.h + idx);
;       hv.x += v0; hv.y += v1; hv.z += v2; hv.w += v3;
;       *(float4*)(g.h + idx) = hv;
;       uint2 o; o.x = pack2bf(hv.x, hv.y); o.y = pack2bf(hv.z, hv.w);
;       *(uint2*)(g.outb + idx) = o;
;       sq[q] += (hv.x * hv.x + hv.y * hv.y) + (hv.z * hv.z + hv.w * hv.w);
.LBB0_945:
	s_andn2_b64 vcc, exec, s[20:21]
	s_cbranch_vccnz .LBB0_947
.LBB0_947:
	v_mov_b32_e32 v38, v54
	s_cmp_lt_i32 s55, 3
	s_mov_b64 s[20:21], -1
	s_cbranch_scc0 .LBB0_911

; __device__ __forceinline__ void epi_block(const int EPI, const GemmArgs& g, f32x4 a00, f32x4 a01, f32x4 a10, f32x4 a11,
;                                           const int fbase, const int tok0, const float (&rs)[4], float (&sq)[4]) {
;     ...
;     } else if (EPI == EPI_RES) {
;       const size_t idx = (size_t)token * D_ + fbase;
;       float4 hv = *(const float4*)(g.h + idx);
;       hv.x += v0; hv.y += v1; hv.z += v2; hv.w += v3;
;       *(float4*)(g.h + idx) = hv;
;       uint2 o; o.x = pack2bf(hv.x, hv.y); o.y = pack2bf(hv.z, hv.w);
;       *(uint2*)(g.outb + idx) = o;
;       sq[q] += (hv.x * hv.x + hv.y * hv.y) + (hv.z * hv.z + hv.w * hv.w);
.LBB0_957:
	s_andn2_b64 vcc, exec, s[20:21]
	s_cbranch_vccnz .LBB0_959
.LBB0_959:
	v_mov_b32_e32 v32, v48
	s_cmp_lt_i32 s55, 3
	s_mov_b64 s[20:21], -1
	s_cbranch_scc0 .LBB0_917

; #define BFLO_(u) __uint_as_float((u) << 16)
; #define BFHI_(u) __uint_as_float((u) & 0xffff0000u)
; __device__ __forceinline__ void epi_block(const int EPI, const GemmArgs& g, f32x4 a00, f32x4 a01, f32x4 a10, f32x4 a11,
;                                           const int fbase, const int tok0, const float (&rs)[4], float (&sq)[4]) {
;     ...
;     } else if (EPI == EPI_RES) {
;       const size_t idx = (size_t)token * D_ + fbase;
;       float4 hv = *(const float4*)(g.h + idx);
;       hv.x += v0; hv.y += v1; hv.z += v2; hv.w += v3;
;       *(float4*)(g.h + idx) = hv;
;       uint2 o; o.x = pack2bf(hv.x, hv.y); o.y = pack2bf(hv.z, hv.w);
;       *(uint2*)(g.outb + idx) = o;
;       sq[q] += (hv.x * hv.x + hv.y * hv.y) + (hv.z * hv.z + hv.w * hv.w);
;     } else if (EPI == EPI_FF1) {
;       const float r = rs[q];
;       v0 = fmaxf(v0 * r, 0.f); v1 = fmaxf(v1 * r, 0.f); v2 = fmaxf(v2 * r, 0.f); v3 = fmaxf(v3 * r, 0.f);
;       uint2 o; o.x = pack2bf(v0 * v0, v1 * v1); o.y = pack2bf(v2 * v2, v3 * v3);
;       *(uint2*)(g.outb + (size_t)token * DFF + fbase) = o;
;     } else if (EPI == EPI_PP) {
;       uint2 o; o.x = pack2bf(v0, v1); o.y = pack2bf(v2, v3);
;       *(uint2*)(g.outb + (size_t)token * D_ + fbase) = o;
;     } else if (EPI == EPI_PLE) {
;       const size_t idx = (size_t)token * D_ + fbase;
;       const float r = rs[q];
;       float4 hv = *(const float4*)(g.h + idx);
;       uint2 pp = *(const uint2*)(g.pp + idx);
;       const float rl = -r * 1.4426950408889634f;
;       hv.x += BFLO_(pp.x) * __builtin_amdgcn_rcpf(1.f + __builtin_amdgcn_exp2f(v0 * rl));
;       hv.y += BFHI_(pp.x) * __builtin_amdgcn_rcpf(1.f + __builtin_amdgcn_exp2f(v1 * rl));
;       hv.z += BFLO_(pp.y) * __builtin_amdgcn_rcpf(1.f + __builtin_amdgcn_exp2f(v2 * rl));
;       hv.w += BFHI_(pp.y) * __builtin_amdgcn_rcpf(1.f + __builtin_amdgcn_exp2f(v3 * rl));
;       *(float4*)(g.h + idx) = hv;
;       uint2 o; o.x = pack2bf(hv.x, hv.y); o.y = pack2bf(hv.z, hv.w);
;       *(uint2*)(g.outb + idx) = o;
;       sq[q] += (hv.x * hv.x + hv.y * hv.y) + (hv.z * hv.z + hv.w * hv.w);
.LBB0_971:
	s_andn2_b64 vcc, exec, s[20:21]
	s_cbranch_vccnz .LBB0_973
.LBB0_973:
	v_mov_b32_e32 v30, v46
.LBB0_974:
	v_or_b32_e32 v31, 48, v66
	v_cmp_gt_i32_e64 s[10:11], s77, v31
	v_cmp_lt_i32_e64 s[8:9], s60, v31
	s_cmp_lt_i32 s55, 3
	s_mov_b64 s[12:13], -1
	s_cbranch_scc1 .LBB0_1000
	s_cmp_gt_i32 s55, 3
	s_cbranch_scc0 .LBB0_977
.LBB0_977:
	s_andn2_b64 vcc, exec, s[12:13]
	s_cbranch_vccnz .LBB0_979
	v_ashrrev_i32_e32 v143, 31, v142
	v_lshlrev_b64 v[20:21], 12, v[140:141]
	v_lshl_add_u64 v[22:23], v[142:143], 0, s[50:51]
	v_lshl_add_u64 v[20:21], s[58:59], 0, v[20:21]
	v_lshl_add_u64 v[22:23], v[22:23], 0, v[0:1]
	v_cvt_pk_bf16_f32 v18, v14, v15
	v_cvt_pk_bf16_f32 v19, v16, v17
	v_lshl_add_u64 v[20:21], v[22:23], 1, v[20:21]
	v_mov_b32_e32 v26, v42
	global_store_dwordx2 v[20:21], v[18:19], off offset:352

; #define BFLO_(u) __uint_as_float((u) << 16)
; #define BFHI_(u) __uint_as_float((u) & 0xffff0000u)
; __device__ __forceinline__ void epi_block(const int EPI, const GemmArgs& g, f32x4 a00, f32x4 a01, f32x4 a10, f32x4 a11,
;                                           const int fbase, const int tok0, const float (&rs)[4], float (&sq)[4]) {
;     ...
;     } else if (EPI == EPI_PP) {
;       uint2 o; o.x = pack2bf(v0, v1); o.y = pack2bf(v2, v3);
;       *(uint2*)(g.outb + (size_t)token * D_ + fbase) = o;
;     } else if (EPI == EPI_PLE) {
;       const size_t idx = (size_t)token * D_ + fbase;
;       const float r = rs[q];
;       float4 hv = *(const float4*)(g.h + idx);
;       uint2 pp = *(const uint2*)(g.pp + idx);
;       const float rl = -r * 1.4426950408889634f;
;       hv.x += BFLO_(pp.x) * __builtin_amdgcn_rcpf(1.f + __builtin_amdgcn_exp2f(v0 * rl));
;       hv.y += BFHI_(pp.x) * __builtin_amdgcn_rcpf(1.f + __builtin_amdgcn_exp2f(v1 * rl));
;       hv.z += BFLO_(pp.y) * __builtin_amdgcn_rcpf(1.f + __builtin_amdgcn_exp2f(v2 * rl));
;       hv.w += BFHI_(pp.y) * __builtin_amdgcn_rcpf(1.f + __builtin_amdgcn_exp2f(v3 * rl));
;       *(float4*)(g.h + idx) = hv;
;       uint2 o; o.x = pack2bf(hv.x, hv.y); o.y = pack2bf(hv.z, hv.w);
;       *(uint2*)(g.outb + idx) = o;
;       sq[q] += (hv.x * hv.x + hv.y * hv.y) + (hv.z * hv.z + hv.w * hv.w);
.LBB0_981:
	s_cmp_gt_i32 s55, 3
	s_cbranch_scc0 .LBB0_983
.LBB0_983:
	s_andn2_b64 vcc, exec, s[20:21]
	s_cbranch_vccnz .LBB0_985
	v_ashrrev_i32_e32 v127, 31, v126
	v_ashrrev_i32_e32 v143, 31, v142
	v_lshlrev_b64 v[16:17], 12, v[126:127]
	v_lshl_add_u64 v[20:21], v[142:143], 0, s[50:51]
	v_lshl_add_u64 v[16:17], s[58:59], 0, v[16:17]
	v_lshl_add_u64 v[20:21], v[20:21], 0, v[0:1]
	v_cvt_pk_bf16_f32 v14, v10, v11
	v_cvt_pk_bf16_f32 v15, v12, v13
	v_lshl_add_u64 v[16:17], v[20:21], 1, v[16:17]
	v_mov_b32_e32 v22, v38
	global_store_dwordx2 v[16:17], v[14:15], off offset:352

; #define BFLO_(u) __uint_as_float((u) << 16)
; #define BFHI_(u) __uint_as_float((u) & 0xffff0000u)
; __device__ __forceinline__ void epi_block(const int EPI, const GemmArgs& g, f32x4 a00, f32x4 a01, f32x4 a10, f32x4 a11,
;                                           const int fbase, const int tok0, const float (&rs)[4], float (&sq)[4]) {
;     ...
;     } else if (EPI == EPI_PP) {
;       uint2 o; o.x = pack2bf(v0, v1); o.y = pack2bf(v2, v3);
;       *(uint2*)(g.outb + (size_t)token * D_ + fbase) = o;
;     } else if (EPI == EPI_PLE) {
;       const size_t idx = (size_t)token * D_ + fbase;
;       const float r = rs[q];
;       float4 hv = *(const float4*)(g.h + idx);
;       uint2 pp = *(const uint2*)(g.pp + idx);
;       const float rl = -r * 1.4426950408889634f;
;       hv.x += BFLO_(pp.x) * __builtin_amdgcn_rcpf(1.f + __builtin_amdgcn_exp2f(v0 * rl));
;       hv.y += BFHI_(pp.x) * __builtin_amdgcn_rcpf(1.f + __builtin_amdgcn_exp2f(v1 * rl));
;       hv.z += BFLO_(pp.y) * __builtin_amdgcn_rcpf(1.f + __builtin_amdgcn_exp2f(v2 * rl));
;       hv.w += BFHI_(pp.y) * __builtin_amdgcn_rcpf(1.f + __builtin_amdgcn_exp2f(v3 * rl));
;       *(float4*)(g.h + idx) = hv;
;       uint2 o; o.x = pack2bf(hv.x, hv.y); o.y = pack2bf(hv.z, hv.w);
;       *(uint2*)(g.outb + idx) = o;
;       sq[q] += (hv.x * hv.x + hv.y * hv.y) + (hv.z * hv.z + hv.w * hv.w);
.LBB0_987:
	s_cmp_gt_i32 s55, 3
	s_cbranch_scc0 .LBB0_989
.LBB0_989:
	s_andn2_b64 vcc, exec, s[20:21]
	s_cbranch_vccnz .LBB0_991
	v_ashrrev_i32_e32 v123, 31, v122
	v_ashrrev_i32_e32 v143, 31, v142
	v_lshlrev_b64 v[12:13], 12, v[122:123]
	v_lshl_add_u64 v[14:15], v[142:143], 0, s[50:51]
	v_lshl_add_u64 v[12:13], s[58:59], 0, v[12:13]
	v_lshl_add_u64 v[14:15], v[14:15], 0, v[0:1]
	v_cvt_pk_bf16_f32 v10, v6, v7
	v_cvt_pk_bf16_f32 v11, v8, v9
	v_lshl_add_u64 v[12:13], v[14:15], 1, v[12:13]
	v_mov_b32_e32 v16, v32
	global_store_dwordx2 v[12:13], v[10:11], off offset:352

; #define BFLO_(u) __uint_as_float((u) << 16)
; #define BFHI_(u) __uint_as_float((u) & 0xffff0000u)
; __device__ __forceinline__ void epi_block(const int EPI, const GemmArgs& g, f32x4 a00, f32x4 a01, f32x4 a10, f32x4 a11,
;                                           const int fbase, const int tok0, const float (&rs)[4], float (&sq)[4]) {
;     ...
;     } else if (EPI == EPI_PP) {
;       uint2 o; o.x = pack2bf(v0, v1); o.y = pack2bf(v2, v3);
;       *(uint2*)(g.outb + (size_t)token * D_ + fbase) = o;
;     } else if (EPI == EPI_PLE) {
;       const size_t idx = (size_t)token * D_ + fbase;
;       const float r = rs[q];
;       float4 hv = *(const float4*)(g.h + idx);
;       uint2 pp = *(const uint2*)(g.pp + idx);
;       const float rl = -r * 1.4426950408889634f;
;       hv.x += BFLO_(pp.x) * __builtin_amdgcn_rcpf(1.f + __builtin_amdgcn_exp2f(v0 * rl));
;       hv.y += BFHI_(pp.x) * __builtin_amdgcn_rcpf(1.f + __builtin_amdgcn_exp2f(v1 * rl));
;       hv.z += BFLO_(pp.y) * __builtin_amdgcn_rcpf(1.f + __builtin_amdgcn_exp2f(v2 * rl));
;       hv.w += BFHI_(pp.y) * __builtin_amdgcn_rcpf(1.f + __builtin_amdgcn_exp2f(v3 * rl));
;       *(float4*)(g.h + idx) = hv;
;       uint2 o; o.x = pack2bf(hv.x, hv.y); o.y = pack2bf(hv.z, hv.w);
;       *(uint2*)(g.outb + idx) = o;
;       sq[q] += (hv.x * hv.x + hv.y * hv.y) + (hv.z * hv.z + hv.w * hv.w);
.LBB0_993:
	s_cmp_gt_i32 s55, 3
	s_cbranch_scc0 .LBB0_995
.LBB0_995:
	s_andn2_b64 vcc, exec, s[20:21]
	s_cbranch_vccnz .LBB0_997
	v_ashrrev_i32_e32 v119, 31, v118
	v_ashrrev_i32_e32 v143, 31, v142
	v_lshlrev_b64 v[8:9], 12, v[118:119]
	v_lshl_add_u64 v[10:11], v[142:143], 0, s[50:51]
	v_lshl_add_u64 v[8:9], s[58:59], 0, v[8:9]
	v_lshl_add_u64 v[10:11], v[10:11], 0, v[0:1]
	v_cvt_pk_bf16_f32 v6, v2, v3
	v_cvt_pk_bf16_f32 v7, v4, v5
	v_lshl_add_u64 v[8:9], v[10:11], 1, v[8:9]
	global_store_dwordx2 v[8:9], v[6:7], off offset:352
	v_mov_b32_e32 v6, v30

; __device__ __forceinline__ void epi_block(const int EPI, const GemmArgs& g, f32x4 a00, f32x4 a01, f32x4 a10, f32x4 a11,
;                                           const int fbase, const int tok0, const float (&rs)[4], float (&sq)[4]) {
;     ...
;     } else if (EPI == EPI_RES) {
;       const size_t idx = (size_t)token * D_ + fbase;
;       float4 hv = *(const float4*)(g.h + idx);
;       hv.x += v0; hv.y += v1; hv.z += v2; hv.w += v3;
;       *(float4*)(g.h + idx) = hv;
;       uint2 o; o.x = pack2bf(hv.x, hv.y); o.y = pack2bf(hv.z, hv.w);
;       *(uint2*)(g.outb + idx) = o;
;       sq[q] += (hv.x * hv.x + hv.y * hv.y) + (hv.z * hv.z + hv.w * hv.w);
.LBB0_1009:
	s_andn2_b64 vcc, exec, s[12:13]
	s_cbranch_vccnz .LBB0_1011
.LBB0_1011:
	v_mov_b32_e32 v26, v42
	v_cmp_gt_i32_e64 s[12:13], s95, v31
	s_cmp_lt_i32 s55, 3
	s_mov_b64 s[20:21], -1
	s_cbranch_scc0 .LBB0_981

; __device__ __forceinline__ void epi_block(const int EPI, const GemmArgs& g, f32x4 a00, f32x4 a01, f32x4 a10, f32x4 a11,
;                                           const int fbase, const int tok0, const float (&rs)[4], float (&sq)[4]) {
;     ...
;     } else if (EPI == EPI_RES) {
;       const size_t idx = (size_t)token * D_ + fbase;
;       float4 hv = *(const float4*)(g.h + idx);
;       hv.x += v0; hv.y += v1; hv.z += v2; hv.w += v3;
;       *(float4*)(g.h + idx) = hv;
;       uint2 o; o.x = pack2bf(hv.x, hv.y); o.y = pack2bf(hv.z, hv.w);
;       *(uint2*)(g.outb + idx) = o;
;       sq[q] += (hv.x * hv.x + hv.y * hv.y) + (hv.z * hv.z + hv.w * hv.w);
.LBB0_1023:
	s_andn2_b64 vcc, exec, s[20:21]
	s_cbranch_vccnz .LBB0_1025
.LBB0_1025:
	v_mov_b32_e32 v22, v38
	s_cmp_lt_i32 s55, 3
	s_mov_b64 s[20:21], -1
	s_cbranch_scc0 .LBB0_987

; __device__ __forceinline__ void epi_block(const int EPI, const GemmArgs& g, f32x4 a00, f32x4 a01, f32x4 a10, f32x4 a11,
;                                           const int fbase, const int tok0, const float (&rs)[4], float (&sq)[4]) {
;     ...
;     } else if (EPI == EPI_RES) {
;       const size_t idx = (size_t)token * D_ + fbase;
;       float4 hv = *(const float4*)(g.h + idx);
;       hv.x += v0; hv.y += v1; hv.z += v2; hv.w += v3;
;       *(float4*)(g.h + idx) = hv;
;       uint2 o; o.x = pack2bf(hv.x, hv.y); o.y = pack2bf(hv.z, hv.w);
;       *(uint2*)(g.outb + idx) = o;
;       sq[q] += (hv.x * hv.x + hv.y * hv.y) + (hv.z * hv.z + hv.w * hv.w);
.LBB0_1035:
	s_andn2_b64 vcc, exec, s[20:21]
	s_cbranch_vccnz .LBB0_1037
.LBB0_1037:
	v_mov_b32_e32 v16, v32
	s_cmp_lt_i32 s55, 3
	s_mov_b64 s[20:21], -1
	s_cbranch_scc0 .LBB0_993

; __device__ __forceinline__ void epi_block(const int EPI, const GemmArgs& g, f32x4 a00, f32x4 a01, f32x4 a10, f32x4 a11,
;                                           const int fbase, const int tok0, const float (&rs)[4], float (&sq)[4]) {
;     ...
;     } else if (EPI == EPI_RES) {
;       const size_t idx = (size_t)token * D_ + fbase;
;       float4 hv = *(const float4*)(g.h + idx);
;       hv.x += v0; hv.y += v1; hv.z += v2; hv.w += v3;
;       *(float4*)(g.h + idx) = hv;
;       uint2 o; o.x = pack2bf(hv.x, hv.y); o.y = pack2bf(hv.z, hv.w);
;       *(uint2*)(g.outb + idx) = o;
;       sq[q] += (hv.x * hv.x + hv.y * hv.y) + (hv.z * hv.z + hv.w * hv.w);
.LBB0_1049:
	s_andn2_b64 vcc, exec, s[20:21]
	s_cbranch_vccnz .LBB0_1051
.LBB0_1051:
	v_mov_b32_e32 v6, v30
	s_cmp_gt_i32 s55, 3
	s_mov_b64 s[8:9], -1
	s_cbranch_scc0 .LBB0_999
